# v18 with the redundant mid-block s_setprio 0/1 pairs removed from the seven GEMM K-loops
# speedup vs baseline: 1.0027x; 1.0027x over previous
; #define PG8_STAGE(bufoff, gbase, voff) do { _Pragma("unroll") for (int _i = 0; _i < 2; ++_i) \
;         __builtin_amdgcn_global_load_lds((const unsigned*)((const char*)(gbase) + (voff)[_i]), (PG8_LAS unsigned*)(lds + (bufoff) + ldsw + _i * 8192), 16, 0, 0); } while (0)
; #define PG8_LDA(dst, b, h) do { _Pragma("unroll") for (int m = 0; m < 4; ++m) _Pragma("unroll") for (int k = 0; k < 2; ++k) dst[m][k] = *(const PG8_LAS bf16x8*)(lds + PG8_SA(b, h) + aoff + m * 2048 + k * 1024); } while (0)
; #define PG8_LDB(dst, b, h) do { _Pragma("unroll") for (int n = 0; n < 2; ++n) _Pragma("unroll") for (int k = 0; k < 2; ++k) dst[n][k] = *(const PG8_LAS bf16x8*)(lds + PG8_SB(b, h) + boff + n * 2048 + k * 1024); } while (0)
; #define PG8_MMA(ai, bj, At, Bt) do { __builtin_amdgcn_s_setprio(1); _Pragma("unroll") for (int m = 0; m < 4; ++m) _Pragma("unroll") for (int n = 0; n < 2; ++n) _Pragma("unroll") for (int k = 0; k < 2; ++k) \
;         acc[ai][bj][m][n] = __builtin_amdgcn_mfma_f32_16x16x32_bf16(Bt[n][k], At[m][k], acc[ai][bj][m][n], 0, 0, 0); __builtin_amdgcn_s_setprio(0); } while (0)
; #define PG8_WAIT_V(n) asm volatile("s_waitcnt vmcnt(" #n ")" ::: "memory")
; #define PG8_WAIT_L(n) asm volatile("s_waitcnt lgkmcnt(" #n ")" ::: "memory")
; #define PG8_BAR __builtin_amdgcn_s_barrier()
; template <class Epi, class Sched, bool ALIGN_EPI = false, bool SP2 = false>
; __device__ __forceinline__ void gemm_phase(PG8_LAS unsigned char* lds, const Gemm g, const Sched& S, const Epi& E, const int wave_id) {
;     ...
;             const char* a1 = cA + (size_t)(t + 1) * kstep;
;             const char* a2 = last ? nA : cA + (size_t)(t + 2) * kstep; const char* b2 = last ? nB : cB + (size_t)(t + 2) * kstep;
;             const char* a3 = a2 + kstep; const char* b3 = b2 + kstep;
;             if (last && has_next) S.a_ready(nxt);
;             if constexpr (SP2) {
;             PG8_LDB(B0, 0, 0); PG8_LDB(B1, 0, 1); PG8_SCHED; PG8_LDA(At, 0, 0); PG8_STAGE(PG8_SA(1, 1), a1 + hstepA, voffA);
;             PG8_WAIT_V(8); PG8_WAIT_L(0); PG8_BAR; PG8_MMA(0, 0, At, B0); PG8_MMA(0, 1, At, B1); PG8_BAR; PG8_SCHED;
;             PG8_LDA(At, 0, 1); PG8_STAGE(PG8_SB(0, 0), b2, voffB); PG8_STAGE(PG8_SB(0, 1), b2 + hstepB, voffB); PG8_STAGE(PG8_SA(0, 0), a2, voffA);
;             PG8_WAIT_V(8); PG8_WAIT_L(0); PG8_BAR; PG8_MMA(1, 0, At, B0); PG8_MMA(1, 1, At, B1); PG8_BAR; PG8_SCHED;
.LBB0_35:
	s_add_u32 s28, s26, 0xfff00080
	s_addc_u32 s29, s27, -1
	s_add_i32 s86, 0, 0x10000
	s_cmp_eq_u32 s83, 60
	s_cselect_b32 s31, s0, s29
	s_cselect_b32 s30, s1, s28
	v_add_u32_e32 v0, s86, v188
	s_cselect_b32 s29, s3, s38
	s_cselect_b32 s28, s19, s21
	s_add_i32 s91, 0, 0x14000
	ds_read_b128 v[130:133], v0
	ds_read_b128 v[134:137], v0 offset:1024
	ds_read_b128 v[138:141], v0 offset:2048
	ds_read_b128 v[142:145], v0 offset:3072
	v_add_u32_e32 v0, s91, v188
	ds_read_b128 v[146:149], v0
	ds_read_b128 v[150:153], v0 offset:1024
	ds_read_b128 v[166:169], v0 offset:2048
	ds_read_b128 v[178:181], v0 offset:3072
	v_lshl_add_u64 v[186:187], s[26:27], 0, v[162:163]
	s_add_i32 m0, s9, 0xc000
	ds_read_b128 v[182:185], v194
	ds_read_b128 v[196:199], v194 offset:1024
	ds_read_b128 v[200:203], v194 offset:2048
	ds_read_b128 v[204:207], v194 offset:3072
	ds_read_b128 v[208:211], v194 offset:4096
	ds_read_b128 v[212:215], v194 offset:5120
	ds_read_b128 v[216:219], v194 offset:6144
	ds_read_b128 v[220:223], v194 offset:7168
	global_load_lds_dwordx4 v[186:187], off
	v_lshl_add_u64 v[186:187], s[26:27], 0, v[164:165]
	s_add_i32 m0, s9, 0xe000
	s_nop 0
	global_load_lds_dwordx4 v[186:187], off
	s_waitcnt vmcnt(8)
	s_waitcnt lgkmcnt(0)
	s_barrier
	s_setprio 1
	s_waitcnt lgkmcnt(0)
	v_mfma_f32_16x16x32_bf16 v[126:129], v[130:133], v[182:185], v[126:129]
	v_mfma_f32_16x16x32_bf16 v[122:125], v[138:141], v[182:185], v[122:125]
	v_mfma_f32_16x16x32_bf16 v[110:113], v[130:133], v[200:203], v[110:113]
	v_mfma_f32_16x16x32_bf16 v[106:109], v[138:141], v[200:203], v[106:109]
	v_mfma_f32_16x16x32_bf16 v[94:97], v[130:133], v[208:211], v[94:97]
	v_mfma_f32_16x16x32_bf16 v[90:93], v[138:141], v[208:211], v[90:93]
	v_mfma_f32_16x16x32_bf16 v[78:81], v[130:133], v[216:219], v[78:81]
	v_mfma_f32_16x16x32_bf16 v[74:77], v[138:141], v[216:219], v[74:77]
	v_mfma_f32_16x16x32_bf16 v[126:129], v[134:137], v[196:199], v[126:129]
	v_mfma_f32_16x16x32_bf16 v[122:125], v[142:145], v[196:199], v[122:125]
	v_mfma_f32_16x16x32_bf16 v[110:113], v[134:137], v[204:207], v[110:113]
	v_mfma_f32_16x16x32_bf16 v[106:109], v[142:145], v[204:207], v[106:109]
	v_mfma_f32_16x16x32_bf16 v[94:97], v[134:137], v[212:215], v[94:97]
	v_mfma_f32_16x16x32_bf16 v[90:93], v[142:145], v[212:215], v[90:93]
	v_mfma_f32_16x16x32_bf16 v[78:81], v[134:137], v[220:223], v[78:81]
	v_mfma_f32_16x16x32_bf16 v[74:77], v[142:145], v[220:223], v[74:77]
	v_mfma_f32_16x16x32_bf16 v[118:121], v[146:149], v[182:185], v[118:121]
	v_mfma_f32_16x16x32_bf16 v[114:117], v[166:169], v[182:185], v[114:117]
	v_mfma_f32_16x16x32_bf16 v[102:105], v[146:149], v[200:203], v[102:105]
	v_mfma_f32_16x16x32_bf16 v[98:101], v[166:169], v[200:203], v[98:101]
	v_mfma_f32_16x16x32_bf16 v[86:89], v[146:149], v[208:211], v[86:89]
	v_mfma_f32_16x16x32_bf16 v[82:85], v[166:169], v[208:211], v[82:85]
	v_mfma_f32_16x16x32_bf16 v[70:73], v[146:149], v[216:219], v[70:73]
	v_mfma_f32_16x16x32_bf16 v[66:69], v[166:169], v[216:219], v[66:69]
	v_mfma_f32_16x16x32_bf16 v[118:121], v[150:153], v[196:199], v[118:121]
	v_mfma_f32_16x16x32_bf16 v[114:117], v[178:181], v[196:199], v[114:117]
	v_mfma_f32_16x16x32_bf16 v[102:105], v[150:153], v[204:207], v[102:105]
	v_mfma_f32_16x16x32_bf16 v[98:101], v[178:181], v[204:207], v[98:101]
	v_mfma_f32_16x16x32_bf16 v[86:89], v[150:153], v[212:215], v[86:89]
	v_mfma_f32_16x16x32_bf16 v[82:85], v[178:181], v[212:215], v[82:85]
	v_mfma_f32_16x16x32_bf16 v[70:73], v[150:153], v[220:223], v[70:73]
	v_mfma_f32_16x16x32_bf16 v[66:69], v[178:181], v[220:223], v[66:69]
	s_setprio 0
	s_barrier
	s_add_i32 s86, s86, s14
	v_lshl_add_u64 v[186:187], s[28:29], 0, v[156:157]
	s_mov_b32 m0, s86
	ds_read_b128 v[182:185], v194 offset:16384
	ds_read_b128 v[196:199], v194 offset:17408
	ds_read_b128 v[200:203], v194 offset:18432
	ds_read_b128 v[204:207], v194 offset:19456
	ds_read_b128 v[208:211], v194 offset:20480
	ds_read_b128 v[212:215], v194 offset:21504
	ds_read_b128 v[216:219], v194 offset:22528
	ds_read_b128 v[220:223], v194 offset:23552
	global_load_lds_dwordx4 v[186:187], off
	s_add_i32 m0, s86, 0x2000
	s_add_u32 s86, s28, 0x100000
	v_lshl_add_u64 v[224:225], s[28:29], 0, v[160:161]
	s_addc_u32 s87, s29, 0
	s_add_i32 s91, s91, s14
	global_load_lds_dwordx4 v[224:225], off
	v_lshl_add_u64 v[234:235], s[86:87], 0, v[156:157]
	s_mov_b32 m0, s91
	v_lshl_add_u64 v[236:237], s[30:31], 0, v[158:159]
	global_load_lds_dwordx4 v[234:235], off
	v_lshl_add_u64 v[234:235], s[86:87], 0, v[160:161]
	s_add_i32 m0, s91, 0x2000
	s_nop 0
	global_load_lds_dwordx4 v[234:235], off
	v_lshl_add_u64 v[234:235], s[30:31], 0, v[154:155]
	s_mov_b32 m0, s9
	s_nop 0
	global_load_lds_dwordx4 v[234:235], off
	s_mov_b32 m0, s15
	s_nop 0
	global_load_lds_dwordx4 v[236:237], off
	s_waitcnt vmcnt(8)
	s_waitcnt lgkmcnt(0)
	s_barrier
; #define PG8_STAGE(bufoff, gbase, voff) do { _Pragma("unroll") for (int _i = 0; _i < 2; ++_i) \
;         __builtin_amdgcn_global_load_lds((const unsigned*)((const char*)(gbase) + (voff)[_i]), (PG8_LAS unsigned*)(lds + (bufoff) + ldsw + _i * 8192), 16, 0, 0); } while (0)
; #define PG8_LDA(dst, b, h) do { _Pragma("unroll") for (int m = 0; m < 4; ++m) _Pragma("unroll") for (int k = 0; k < 2; ++k) dst[m][k] = *(const PG8_LAS bf16x8*)(lds + PG8_SA(b, h) + aoff + m * 2048 + k * 1024); } while (0)
; #define PG8_LDB(dst, b, h) do { _Pragma("unroll") for (int n = 0; n < 2; ++n) _Pragma("unroll") for (int k = 0; k < 2; ++k) dst[n][k] = *(const PG8_LAS bf16x8*)(lds + PG8_SB(b, h) + boff + n * 2048 + k * 1024); } while (0)
; #define PG8_MMA(ai, bj, At, Bt) do { __builtin_amdgcn_s_setprio(1); _Pragma("unroll") for (int m = 0; m < 4; ++m) _Pragma("unroll") for (int n = 0; n < 2; ++n) _Pragma("unroll") for (int k = 0; k < 2; ++k) \
;         acc[ai][bj][m][n] = __builtin_amdgcn_mfma_f32_16x16x32_bf16(Bt[n][k], At[m][k], acc[ai][bj][m][n], 0, 0, 0); __builtin_amdgcn_s_setprio(0); } while (0)
; #define PG8_WAIT_V(n) asm volatile("s_waitcnt vmcnt(" #n ")" ::: "memory")
; #define PG8_WAIT_L(n) asm volatile("s_waitcnt lgkmcnt(" #n ")" ::: "memory")
; #define PG8_BAR __builtin_amdgcn_s_barrier()
; #define PG8_SCHED __builtin_amdgcn_sched_barrier(0)
; template <class Epi, class Sched, bool ALIGN_EPI = false, bool SP2 = false>
; __device__ __forceinline__ void gemm_phase(PG8_LAS unsigned char* lds, const Gemm g, const Sched& S, const Epi& E, const int wave_id) {
;     ...
;             PG8_WAIT_V(8); PG8_WAIT_L(0); PG8_BAR; PG8_MMA(1, 0, At, B0); PG8_MMA(1, 1, At, B1); PG8_BAR; PG8_SCHED;
;             PG8_LDB(B0, 1, 0); PG8_LDB(B1, 1, 1); PG8_SCHED; PG8_LDA(At, 1, 0); PG8_STAGE(PG8_SA(0, 1), a2 + hstepA, voffA);
;             PG8_WAIT_V(8); PG8_WAIT_L(0); PG8_BAR; PG8_MMA(0, 0, At, B0); PG8_MMA(0, 1, At, B1); PG8_BAR; PG8_SCHED;
	s_setprio 1
	s_waitcnt lgkmcnt(0)
	v_mfma_f32_16x16x32_bf16 v[62:65], v[130:133], v[182:185], v[62:65]
	v_mfma_f32_16x16x32_bf16 v[58:61], v[138:141], v[182:185], v[58:61]
	v_mfma_f32_16x16x32_bf16 v[46:49], v[130:133], v[200:203], v[46:49]
	v_mfma_f32_16x16x32_bf16 v[42:45], v[138:141], v[200:203], v[42:45]
	v_mfma_f32_16x16x32_bf16 v[30:33], v[130:133], v[208:211], v[30:33]
	v_mfma_f32_16x16x32_bf16 v[26:29], v[138:141], v[208:211], v[26:29]
	v_mfma_f32_16x16x32_bf16 v[14:17], v[130:133], v[216:219], v[14:17]
	v_mfma_f32_16x16x32_bf16 v[10:13], v[138:141], v[216:219], v[10:13]
	v_mfma_f32_16x16x32_bf16 v[62:65], v[134:137], v[196:199], v[62:65]
	v_mfma_f32_16x16x32_bf16 v[58:61], v[142:145], v[196:199], v[58:61]
	v_mfma_f32_16x16x32_bf16 v[46:49], v[134:137], v[204:207], v[46:49]
	v_mfma_f32_16x16x32_bf16 v[42:45], v[142:145], v[204:207], v[42:45]
	v_mfma_f32_16x16x32_bf16 v[30:33], v[134:137], v[212:215], v[30:33]
	v_mfma_f32_16x16x32_bf16 v[26:29], v[142:145], v[212:215], v[26:29]
	v_mfma_f32_16x16x32_bf16 v[14:17], v[134:137], v[220:223], v[14:17]
	v_mfma_f32_16x16x32_bf16 v[10:13], v[142:145], v[220:223], v[10:13]
	v_mfma_f32_16x16x32_bf16 v[54:57], v[146:149], v[182:185], v[54:57]
	v_mfma_f32_16x16x32_bf16 v[50:53], v[166:169], v[182:185], v[50:53]
	v_mfma_f32_16x16x32_bf16 v[38:41], v[146:149], v[200:203], v[38:41]
	v_mfma_f32_16x16x32_bf16 v[34:37], v[166:169], v[200:203], v[34:37]
	v_mfma_f32_16x16x32_bf16 v[22:25], v[146:149], v[208:211], v[22:25]
	v_mfma_f32_16x16x32_bf16 v[18:21], v[166:169], v[208:211], v[18:21]
	v_mfma_f32_16x16x32_bf16 v[6:9], v[146:149], v[216:219], v[6:9]
	v_mfma_f32_16x16x32_bf16 v[2:5], v[166:169], v[216:219], v[2:5]
	v_mfma_f32_16x16x32_bf16 v[54:57], v[150:153], v[196:199], v[54:57]
	v_mfma_f32_16x16x32_bf16 v[50:53], v[178:181], v[196:199], v[50:53]
	v_mfma_f32_16x16x32_bf16 v[38:41], v[150:153], v[204:207], v[38:41]
	v_mfma_f32_16x16x32_bf16 v[34:37], v[178:181], v[204:207], v[34:37]
	v_mfma_f32_16x16x32_bf16 v[22:25], v[150:153], v[212:215], v[22:25]
	v_mfma_f32_16x16x32_bf16 v[18:21], v[178:181], v[212:215], v[18:21]
	v_mfma_f32_16x16x32_bf16 v[6:9], v[150:153], v[220:223], v[6:9]
	v_mfma_f32_16x16x32_bf16 v[2:5], v[178:181], v[220:223], v[2:5]
	s_setprio 0
	s_barrier
	s_add_i32 s86, 0, 0x18000
	v_add_u32_e32 v0, s86, v188
	s_add_i32 s87, 0, 0x1c000
	ds_read_b128 v[130:133], v0
	ds_read_b128 v[134:137], v0 offset:1024
	ds_read_b128 v[138:141], v0 offset:2048
	ds_read_b128 v[142:145], v0 offset:3072
	v_add_u32_e32 v0, s87, v188
	ds_read_b128 v[146:149], v0
	ds_read_b128 v[150:153], v0 offset:1024
	ds_read_b128 v[166:169], v0 offset:2048
	ds_read_b128 v[178:181], v0 offset:3072
	s_add_u32 s30, s30, 0x100000
	s_addc_u32 s31, s31, 0
	s_mov_b32 m0, s34
	v_lshl_add_u64 v[240:241], s[30:31], 0, v[154:155]
	ds_read_b128 v[182:185], v194 offset:32768
	ds_read_b128 v[196:199], v194 offset:33792
	ds_read_b128 v[200:203], v194 offset:34816
	ds_read_b128 v[204:207], v194 offset:35840
	ds_read_b128 v[208:211], v194 offset:36864
	ds_read_b128 v[212:215], v194 offset:37888
	ds_read_b128 v[216:219], v194 offset:38912
	ds_read_b128 v[220:223], v194 offset:39936
	global_load_lds_dwordx4 v[240:241], off
	v_lshl_add_u64 v[240:241], s[30:31], 0, v[158:159]
	s_mov_b32 m0, s35
	s_nop 0
	global_load_lds_dwordx4 v[240:241], off
	s_waitcnt vmcnt(8)
	s_waitcnt lgkmcnt(0)
	s_barrier
	s_setprio 1
	s_waitcnt lgkmcnt(0)
	v_mfma_f32_16x16x32_bf16 v[126:129], v[130:133], v[182:185], v[126:129]
	v_mfma_f32_16x16x32_bf16 v[122:125], v[138:141], v[182:185], v[122:125]
	v_mfma_f32_16x16x32_bf16 v[110:113], v[130:133], v[200:203], v[110:113]
	v_mfma_f32_16x16x32_bf16 v[106:109], v[138:141], v[200:203], v[106:109]
	v_mfma_f32_16x16x32_bf16 v[94:97], v[130:133], v[208:211], v[94:97]
	v_mfma_f32_16x16x32_bf16 v[90:93], v[138:141], v[208:211], v[90:93]
	v_mfma_f32_16x16x32_bf16 v[78:81], v[130:133], v[216:219], v[78:81]
	v_mfma_f32_16x16x32_bf16 v[74:77], v[138:141], v[216:219], v[74:77]
	v_mfma_f32_16x16x32_bf16 v[126:129], v[134:137], v[196:199], v[126:129]
	v_mfma_f32_16x16x32_bf16 v[122:125], v[142:145], v[196:199], v[122:125]
	v_mfma_f32_16x16x32_bf16 v[110:113], v[134:137], v[204:207], v[110:113]
	v_mfma_f32_16x16x32_bf16 v[106:109], v[142:145], v[204:207], v[106:109]
	v_mfma_f32_16x16x32_bf16 v[94:97], v[134:137], v[212:215], v[94:97]
	v_mfma_f32_16x16x32_bf16 v[90:93], v[142:145], v[212:215], v[90:93]
	v_mfma_f32_16x16x32_bf16 v[78:81], v[134:137], v[220:223], v[78:81]
	v_mfma_f32_16x16x32_bf16 v[74:77], v[142:145], v[220:223], v[74:77]
	v_mfma_f32_16x16x32_bf16 v[118:121], v[146:149], v[182:185], v[118:121]
	v_mfma_f32_16x16x32_bf16 v[114:117], v[166:169], v[182:185], v[114:117]
	v_mfma_f32_16x16x32_bf16 v[102:105], v[146:149], v[200:203], v[102:105]
	v_mfma_f32_16x16x32_bf16 v[98:101], v[166:169], v[200:203], v[98:101]
	v_mfma_f32_16x16x32_bf16 v[86:89], v[146:149], v[208:211], v[86:89]
	v_mfma_f32_16x16x32_bf16 v[82:85], v[166:169], v[208:211], v[82:85]
	v_mfma_f32_16x16x32_bf16 v[70:73], v[146:149], v[216:219], v[70:73]
	v_mfma_f32_16x16x32_bf16 v[66:69], v[166:169], v[216:219], v[66:69]
	v_mfma_f32_16x16x32_bf16 v[118:121], v[150:153], v[196:199], v[118:121]
	v_mfma_f32_16x16x32_bf16 v[114:117], v[178:181], v[196:199], v[114:117]
	v_mfma_f32_16x16x32_bf16 v[102:105], v[150:153], v[204:207], v[102:105]
	v_mfma_f32_16x16x32_bf16 v[98:101], v[178:181], v[204:207], v[98:101]
	v_mfma_f32_16x16x32_bf16 v[86:89], v[150:153], v[212:215], v[86:89]
	v_mfma_f32_16x16x32_bf16 v[82:85], v[178:181], v[212:215], v[82:85]
	v_mfma_f32_16x16x32_bf16 v[70:73], v[150:153], v[220:223], v[70:73]
	v_mfma_f32_16x16x32_bf16 v[66:69], v[178:181], v[220:223], v[66:69]
	s_setprio 0
	s_barrier
; #define PG8_STAGE(bufoff, gbase, voff) do { _Pragma("unroll") for (int _i = 0; _i < 2; ++_i) \
;         __builtin_amdgcn_global_load_lds((const unsigned*)((const char*)(gbase) + (voff)[_i]), (PG8_LAS unsigned*)(lds + (bufoff) + ldsw + _i * 8192), 16, 0, 0); } while (0)
; #define PG8_LDA(dst, b, h) do { _Pragma("unroll") for (int m = 0; m < 4; ++m) _Pragma("unroll") for (int k = 0; k < 2; ++k) dst[m][k] = *(const PG8_LAS bf16x8*)(lds + PG8_SA(b, h) + aoff + m * 2048 + k * 1024); } while (0)
; #define PG8_MMA(ai, bj, At, Bt) do { __builtin_amdgcn_s_setprio(1); _Pragma("unroll") for (int m = 0; m < 4; ++m) _Pragma("unroll") for (int n = 0; n < 2; ++n) _Pragma("unroll") for (int k = 0; k < 2; ++k) \
;         acc[ai][bj][m][n] = __builtin_amdgcn_mfma_f32_16x16x32_bf16(Bt[n][k], At[m][k], acc[ai][bj][m][n], 0, 0, 0); __builtin_amdgcn_s_setprio(0); } while (0)
; #define PG8_WAIT_V(n) asm volatile("s_waitcnt vmcnt(" #n ")" ::: "memory")
; #define PG8_WAIT_L(n) asm volatile("s_waitcnt lgkmcnt(" #n ")" ::: "memory")
; #define PG8_BAR __builtin_amdgcn_s_barrier()
; #define PG8_SCHED __builtin_amdgcn_sched_barrier(0)
; template <class Epi, class Sched, bool ALIGN_EPI = false, bool SP2 = false>
; __device__ __forceinline__ void gemm_phase(PG8_LAS unsigned char* lds, const Gemm g, const Sched& S, const Epi& E, const int wave_id) {
;     ...
;             PG8_LDA(At, 1, 1); PG8_STAGE(PG8_SB(1, 0), b3, voffB); PG8_STAGE(PG8_SB(1, 1), b3 + hstepB, voffB); PG8_STAGE(PG8_SA(1, 0), a3, voffA);
;             PG8_WAIT_V(8); PG8_WAIT_L(0); PG8_BAR; PG8_MMA(1, 0, At, B0); PG8_MMA(1, 1, At, B1); PG8_BAR; PG8_SCHED;
	s_add_i32 s30, s86, s14
	v_lshl_add_u64 v[186:187], v[186:187], 0, s[62:63]
	s_mov_b32 m0, s30
	ds_read_b128 v[182:185], v194 offset:49152
	ds_read_b128 v[196:199], v194 offset:50176
	ds_read_b128 v[200:203], v194 offset:51200
	ds_read_b128 v[204:207], v194 offset:52224
	ds_read_b128 v[208:211], v194 offset:53248
	ds_read_b128 v[212:215], v194 offset:54272
	ds_read_b128 v[216:219], v194 offset:55296
	ds_read_b128 v[220:223], v194 offset:56320
	global_load_lds_dwordx4 v[186:187], off
	s_add_i32 m0, s30, 0x2000
	s_add_u32 s28, s28, 0x100080
	v_lshl_add_u64 v[186:187], v[224:225], 0, s[62:63]
	s_addc_u32 s29, s29, 0
	s_add_i32 s30, s87, s14
	global_load_lds_dwordx4 v[186:187], off
	v_lshl_add_u64 v[186:187], s[28:29], 0, v[156:157]
	s_mov_b32 m0, s30
	s_nop 0
	global_load_lds_dwordx4 v[186:187], off
	v_lshl_add_u64 v[186:187], s[28:29], 0, v[160:161]
	s_add_i32 m0, s30, 0x2000
	s_nop 0
	global_load_lds_dwordx4 v[186:187], off
	v_lshl_add_u64 v[186:187], v[234:235], 0, s[62:63]
	s_mov_b32 m0, s50
	s_nop 0
	global_load_lds_dwordx4 v[186:187], off
	v_lshl_add_u64 v[186:187], v[236:237], 0, s[62:63]
	s_mov_b32 m0, s76
	s_nop 0
	global_load_lds_dwordx4 v[186:187], off
	s_waitcnt vmcnt(8)
	s_waitcnt lgkmcnt(0)
	s_barrier
	s_setprio 1
	s_waitcnt lgkmcnt(0)
	v_mfma_f32_16x16x32_bf16 v[62:65], v[130:133], v[182:185], v[62:65]
	v_mfma_f32_16x16x32_bf16 v[58:61], v[138:141], v[182:185], v[58:61]
	v_mfma_f32_16x16x32_bf16 v[46:49], v[130:133], v[200:203], v[46:49]
	v_mfma_f32_16x16x32_bf16 v[42:45], v[138:141], v[200:203], v[42:45]
	v_mfma_f32_16x16x32_bf16 v[30:33], v[130:133], v[208:211], v[30:33]
	v_mfma_f32_16x16x32_bf16 v[26:29], v[138:141], v[208:211], v[26:29]
	v_mfma_f32_16x16x32_bf16 v[14:17], v[130:133], v[216:219], v[14:17]
	v_mfma_f32_16x16x32_bf16 v[10:13], v[138:141], v[216:219], v[10:13]
	v_mfma_f32_16x16x32_bf16 v[62:65], v[134:137], v[196:199], v[62:65]
	v_mfma_f32_16x16x32_bf16 v[58:61], v[142:145], v[196:199], v[58:61]
	v_mfma_f32_16x16x32_bf16 v[46:49], v[134:137], v[204:207], v[46:49]
	v_mfma_f32_16x16x32_bf16 v[42:45], v[142:145], v[204:207], v[42:45]
	v_mfma_f32_16x16x32_bf16 v[30:33], v[134:137], v[212:215], v[30:33]
	v_mfma_f32_16x16x32_bf16 v[26:29], v[142:145], v[212:215], v[26:29]
	v_mfma_f32_16x16x32_bf16 v[14:17], v[134:137], v[220:223], v[14:17]
	v_mfma_f32_16x16x32_bf16 v[10:13], v[142:145], v[220:223], v[10:13]
	v_mfma_f32_16x16x32_bf16 v[54:57], v[146:149], v[182:185], v[54:57]
	v_mfma_f32_16x16x32_bf16 v[50:53], v[166:169], v[182:185], v[50:53]
	v_mfma_f32_16x16x32_bf16 v[38:41], v[146:149], v[200:203], v[38:41]
	v_mfma_f32_16x16x32_bf16 v[34:37], v[166:169], v[200:203], v[34:37]
	v_mfma_f32_16x16x32_bf16 v[22:25], v[146:149], v[208:211], v[22:25]
	v_mfma_f32_16x16x32_bf16 v[18:21], v[166:169], v[208:211], v[18:21]
	v_mfma_f32_16x16x32_bf16 v[6:9], v[146:149], v[216:219], v[6:9]
	v_mfma_f32_16x16x32_bf16 v[2:5], v[166:169], v[216:219], v[2:5]
	v_mfma_f32_16x16x32_bf16 v[54:57], v[150:153], v[196:199], v[54:57]
	v_mfma_f32_16x16x32_bf16 v[50:53], v[178:181], v[196:199], v[50:53]
	v_mfma_f32_16x16x32_bf16 v[38:41], v[150:153], v[204:207], v[38:41]
	v_mfma_f32_16x16x32_bf16 v[34:37], v[178:181], v[204:207], v[34:37]
	v_mfma_f32_16x16x32_bf16 v[22:25], v[150:153], v[212:215], v[22:25]
	v_mfma_f32_16x16x32_bf16 v[18:21], v[178:181], v[212:215], v[18:21]
	v_mfma_f32_16x16x32_bf16 v[6:9], v[150:153], v[220:223], v[6:9]
	v_mfma_f32_16x16x32_bf16 v[2:5], v[178:181], v[220:223], v[2:5]
	s_setprio 0
	s_barrier
	s_add_i32 s83, s83, 2
	s_add_u32 s26, s26, 0x100
	s_addc_u32 s27, s27, 0
	s_add_u32 s21, s21, 0x100
	s_addc_u32 s38, s38, 0
	s_cmp_gt_u32 s83, 61
	s_cbranch_scc0 .LBB0_35
	s_and_b64 vcc, exec, s[16:17]
	s_cbranch_vccz .LBB0_38
	s_barrier

; #define PG8_STAGE(bufoff, gbase, voff) do { _Pragma("unroll") for (int _i = 0; _i < 2; ++_i) \
;         __builtin_amdgcn_global_load_lds((const unsigned*)((const char*)(gbase) + (voff)[_i]), (PG8_LAS unsigned*)(lds + (bufoff) + ldsw + _i * 8192), 16, 0, 0); } while (0)
; #define PG8_LDA(dst, b, h) do { _Pragma("unroll") for (int m = 0; m < 4; ++m) _Pragma("unroll") for (int k = 0; k < 2; ++k) dst[m][k] = *(const PG8_LAS bf16x8*)(lds + PG8_SA(b, h) + aoff + m * 2048 + k * 1024); } while (0)
; #define PG8_LDB(dst, b, h) do { _Pragma("unroll") for (int n = 0; n < 2; ++n) _Pragma("unroll") for (int k = 0; k < 2; ++k) dst[n][k] = *(const PG8_LAS bf16x8*)(lds + PG8_SB(b, h) + boff + n * 2048 + k * 1024); } while (0)
; #define PG8_MMA(ai, bj, At, Bt) do { __builtin_amdgcn_s_setprio(1); _Pragma("unroll") for (int m = 0; m < 4; ++m) _Pragma("unroll") for (int n = 0; n < 2; ++n) _Pragma("unroll") for (int k = 0; k < 2; ++k) \
;         acc[ai][bj][m][n] = __builtin_amdgcn_mfma_f32_16x16x32_bf16(Bt[n][k], At[m][k], acc[ai][bj][m][n], 0, 0, 0); __builtin_amdgcn_s_setprio(0); } while (0)
; #define PG8_WAIT_V(n) asm volatile("s_waitcnt vmcnt(" #n ")" ::: "memory")
; #define PG8_WAIT_L(n) asm volatile("s_waitcnt lgkmcnt(" #n ")" ::: "memory")
; #define PG8_BAR __builtin_amdgcn_s_barrier()
; template <class Epi, class Sched, bool ALIGN_EPI = false, bool SP2 = false>
; __device__ __forceinline__ void gemm_phase(PG8_LAS unsigned char* lds, const Gemm g, const Sched& S, const Epi& E, const int wave_id) {
;     ...
;             const char* a1 = cA + (size_t)(t + 1) * kstep;
;             const char* a2 = last ? nA : cA + (size_t)(t + 2) * kstep; const char* b2 = last ? nB : cB + (size_t)(t + 2) * kstep;
;             const char* a3 = a2 + kstep; const char* b3 = b2 + kstep;
;             if (last && has_next) S.a_ready(nxt);
;             if constexpr (SP2) {
;             PG8_LDB(B0, 0, 0); PG8_LDB(B1, 0, 1); PG8_SCHED; PG8_LDA(At, 0, 0); PG8_STAGE(PG8_SA(1, 1), a1 + hstepA, voffA);
;             PG8_WAIT_V(8); PG8_WAIT_L(0); PG8_BAR; PG8_MMA(0, 0, At, B0); PG8_MMA(0, 1, At, B1); PG8_BAR; PG8_SCHED;
;             PG8_LDA(At, 0, 1); PG8_STAGE(PG8_SB(0, 0), b2, voffB); PG8_STAGE(PG8_SB(0, 1), b2 + hstepB, voffB); PG8_STAGE(PG8_SA(0, 0), a2, voffA);
;             PG8_WAIT_V(8); PG8_WAIT_L(0); PG8_BAR; PG8_MMA(1, 0, At, B0); PG8_MMA(1, 1, At, B1); PG8_BAR; PG8_SCHED;
.LBB0_69:
	s_add_u32 s18, s16, 0xfff00080
	s_addc_u32 s19, s17, -1
	s_add_i32 s39, 0, 0x10000
	s_cmp_eq_u32 s38, 4
	s_cselect_b32 s21, s30, s19
	s_cselect_b32 s20, s31, s18
	v_add_u32_e32 v0, s39, v139
	s_cselect_b32 s19, s34, s37
	s_cselect_b32 s18, s35, s36
	s_add_i32 s50, 0, 0x14000
	ds_read_b128 v[142:145], v0
	ds_read_b128 v[146:149], v0 offset:1024
	ds_read_b128 v[150:153], v0 offset:2048
	ds_read_b128 v[154:157], v0 offset:3072
	v_add_u32_e32 v0, s50, v139
	ds_read_b128 v[158:161], v0
	ds_read_b128 v[162:165], v0 offset:1024
	ds_read_b128 v[166:169], v0 offset:2048
	ds_read_b128 v[178:181], v0 offset:3072
	v_lshl_add_u64 v[214:215], s[16:17], 0, v[134:135]
	s_add_i32 m0, s3, 0xc000
	ds_read_b128 v[182:185], v141
	ds_read_b128 v[186:189], v141 offset:1024
	ds_read_b128 v[190:193], v141 offset:2048
	ds_read_b128 v[194:197], v141 offset:3072
	ds_read_b128 v[198:201], v141 offset:4096
	ds_read_b128 v[202:205], v141 offset:5120
	ds_read_b128 v[206:209], v141 offset:6144
	ds_read_b128 v[210:213], v141 offset:7168
	global_load_lds_dwordx4 v[214:215], off
	v_lshl_add_u64 v[214:215], s[16:17], 0, v[136:137]
	s_add_i32 m0, s3, 0xe000
	s_nop 0
	global_load_lds_dwordx4 v[214:215], off
	s_waitcnt vmcnt(8)
	s_waitcnt lgkmcnt(0)
	s_barrier
	s_setprio 1
	s_waitcnt lgkmcnt(0)
	v_mfma_f32_16x16x32_bf16 v[126:129], v[142:145], v[182:185], v[126:129]
	v_mfma_f32_16x16x32_bf16 v[122:125], v[150:153], v[182:185], v[122:125]
	v_mfma_f32_16x16x32_bf16 v[118:121], v[142:145], v[190:193], v[118:121]
	v_mfma_f32_16x16x32_bf16 v[114:117], v[150:153], v[190:193], v[114:117]
	v_mfma_f32_16x16x32_bf16 v[106:109], v[142:145], v[198:201], v[106:109]
	v_mfma_f32_16x16x32_bf16 v[98:101], v[150:153], v[198:201], v[98:101]
	v_mfma_f32_16x16x32_bf16 v[90:93], v[142:145], v[206:209], v[90:93]
	v_mfma_f32_16x16x32_bf16 v[82:85], v[150:153], v[206:209], v[82:85]
	v_mfma_f32_16x16x32_bf16 v[126:129], v[146:149], v[186:189], v[126:129]
	v_mfma_f32_16x16x32_bf16 v[122:125], v[154:157], v[186:189], v[122:125]
	v_mfma_f32_16x16x32_bf16 v[118:121], v[146:149], v[194:197], v[118:121]
	v_mfma_f32_16x16x32_bf16 v[114:117], v[154:157], v[194:197], v[114:117]
	v_mfma_f32_16x16x32_bf16 v[106:109], v[146:149], v[202:205], v[106:109]
	v_mfma_f32_16x16x32_bf16 v[98:101], v[154:157], v[202:205], v[98:101]
	v_mfma_f32_16x16x32_bf16 v[90:93], v[146:149], v[210:213], v[90:93]
	v_mfma_f32_16x16x32_bf16 v[82:85], v[154:157], v[210:213], v[82:85]
	v_mfma_f32_16x16x32_bf16 v[110:113], v[158:161], v[182:185], v[110:113]
	v_mfma_f32_16x16x32_bf16 v[102:105], v[166:169], v[182:185], v[102:105]
	v_mfma_f32_16x16x32_bf16 v[94:97], v[158:161], v[190:193], v[94:97]
	v_mfma_f32_16x16x32_bf16 v[86:89], v[166:169], v[190:193], v[86:89]
	v_mfma_f32_16x16x32_bf16 v[78:81], v[158:161], v[198:201], v[78:81]
	v_mfma_f32_16x16x32_bf16 v[74:77], v[166:169], v[198:201], v[74:77]
	v_mfma_f32_16x16x32_bf16 v[70:73], v[158:161], v[206:209], v[70:73]
	v_mfma_f32_16x16x32_bf16 v[66:69], v[166:169], v[206:209], v[66:69]
	v_mfma_f32_16x16x32_bf16 v[110:113], v[162:165], v[186:189], v[110:113]
	v_mfma_f32_16x16x32_bf16 v[102:105], v[178:181], v[186:189], v[102:105]
	v_mfma_f32_16x16x32_bf16 v[94:97], v[162:165], v[194:197], v[94:97]
	v_mfma_f32_16x16x32_bf16 v[86:89], v[178:181], v[194:197], v[86:89]
	v_mfma_f32_16x16x32_bf16 v[78:81], v[162:165], v[202:205], v[78:81]
	v_mfma_f32_16x16x32_bf16 v[74:77], v[178:181], v[202:205], v[74:77]
	v_mfma_f32_16x16x32_bf16 v[70:73], v[162:165], v[210:213], v[70:73]
	v_mfma_f32_16x16x32_bf16 v[66:69], v[178:181], v[210:213], v[66:69]
	s_setprio 0
	s_barrier
	s_add_i32 s39, s39, s0
	v_lshl_add_u64 v[214:215], s[18:19], 0, v[132:133]
	s_mov_b32 m0, s39
	ds_read_b128 v[182:185], v141 offset:16384
	ds_read_b128 v[186:189], v141 offset:17408
	ds_read_b128 v[190:193], v141 offset:18432
	ds_read_b128 v[194:197], v141 offset:19456
	ds_read_b128 v[198:201], v141 offset:20480
	ds_read_b128 v[202:205], v141 offset:21504
	ds_read_b128 v[206:209], v141 offset:22528
	ds_read_b128 v[210:213], v141 offset:23552
	global_load_lds_dwordx4 v[214:215], off
	s_add_i32 m0, s39, 0x2000
	s_add_u32 s44, s18, 0x100000
	v_lshl_add_u64 v[216:217], s[18:19], 0, v[130:131]
	s_addc_u32 s45, s19, 0
	s_add_i32 s39, s50, s0
	global_load_lds_dwordx4 v[216:217], off
	v_lshl_add_u64 v[218:219], s[44:45], 0, v[132:133]
	s_mov_b32 m0, s39
	v_lshl_add_u64 v[220:221], s[20:21], 0, v[130:131]
	global_load_lds_dwordx4 v[218:219], off
	v_lshl_add_u64 v[218:219], s[44:45], 0, v[130:131]
	s_add_i32 m0, s39, 0x2000
	s_nop 0
	global_load_lds_dwordx4 v[218:219], off
	v_lshl_add_u64 v[218:219], s[20:21], 0, v[132:133]
	s_mov_b32 m0, s3
	s_nop 0
	global_load_lds_dwordx4 v[218:219], off
	s_mov_b32 m0, s15
	s_nop 0
	global_load_lds_dwordx4 v[220:221], off
	s_waitcnt vmcnt(8)
	s_waitcnt lgkmcnt(0)
	s_barrier
; #define PG8_STAGE(bufoff, gbase, voff) do { _Pragma("unroll") for (int _i = 0; _i < 2; ++_i) \
;         __builtin_amdgcn_global_load_lds((const unsigned*)((const char*)(gbase) + (voff)[_i]), (PG8_LAS unsigned*)(lds + (bufoff) + ldsw + _i * 8192), 16, 0, 0); } while (0)
; #define PG8_LDA(dst, b, h) do { _Pragma("unroll") for (int m = 0; m < 4; ++m) _Pragma("unroll") for (int k = 0; k < 2; ++k) dst[m][k] = *(const PG8_LAS bf16x8*)(lds + PG8_SA(b, h) + aoff + m * 2048 + k * 1024); } while (0)
; #define PG8_LDB(dst, b, h) do { _Pragma("unroll") for (int n = 0; n < 2; ++n) _Pragma("unroll") for (int k = 0; k < 2; ++k) dst[n][k] = *(const PG8_LAS bf16x8*)(lds + PG8_SB(b, h) + boff + n * 2048 + k * 1024); } while (0)
; #define PG8_MMA(ai, bj, At, Bt) do { __builtin_amdgcn_s_setprio(1); _Pragma("unroll") for (int m = 0; m < 4; ++m) _Pragma("unroll") for (int n = 0; n < 2; ++n) _Pragma("unroll") for (int k = 0; k < 2; ++k) \
;         acc[ai][bj][m][n] = __builtin_amdgcn_mfma_f32_16x16x32_bf16(Bt[n][k], At[m][k], acc[ai][bj][m][n], 0, 0, 0); __builtin_amdgcn_s_setprio(0); } while (0)
; #define PG8_WAIT_V(n) asm volatile("s_waitcnt vmcnt(" #n ")" ::: "memory")
; #define PG8_WAIT_L(n) asm volatile("s_waitcnt lgkmcnt(" #n ")" ::: "memory")
; #define PG8_BAR __builtin_amdgcn_s_barrier()
; #define PG8_SCHED __builtin_amdgcn_sched_barrier(0)
; template <class Epi, class Sched, bool ALIGN_EPI = false, bool SP2 = false>
; __device__ __forceinline__ void gemm_phase(PG8_LAS unsigned char* lds, const Gemm g, const Sched& S, const Epi& E, const int wave_id) {
;     ...
;             PG8_WAIT_V(8); PG8_WAIT_L(0); PG8_BAR; PG8_MMA(1, 0, At, B0); PG8_MMA(1, 1, At, B1); PG8_BAR; PG8_SCHED;
;             PG8_LDB(B0, 1, 0); PG8_LDB(B1, 1, 1); PG8_SCHED; PG8_LDA(At, 1, 0); PG8_STAGE(PG8_SA(0, 1), a2 + hstepA, voffA);
;             PG8_WAIT_V(8); PG8_WAIT_L(0); PG8_BAR; PG8_MMA(0, 0, At, B0); PG8_MMA(0, 1, At, B1); PG8_BAR; PG8_SCHED;
	s_setprio 1
	s_waitcnt lgkmcnt(0)
	v_mfma_f32_16x16x32_bf16 v[62:65], v[142:145], v[182:185], v[62:65]
	v_mfma_f32_16x16x32_bf16 v[58:61], v[150:153], v[182:185], v[58:61]
	v_mfma_f32_16x16x32_bf16 v[54:57], v[142:145], v[190:193], v[54:57]
	v_mfma_f32_16x16x32_bf16 v[50:53], v[150:153], v[190:193], v[50:53]
	v_mfma_f32_16x16x32_bf16 v[42:45], v[142:145], v[198:201], v[42:45]
	v_mfma_f32_16x16x32_bf16 v[34:37], v[150:153], v[198:201], v[34:37]
	v_mfma_f32_16x16x32_bf16 v[26:29], v[142:145], v[206:209], v[26:29]
	v_mfma_f32_16x16x32_bf16 v[18:21], v[150:153], v[206:209], v[18:21]
	v_mfma_f32_16x16x32_bf16 v[62:65], v[146:149], v[186:189], v[62:65]
	v_mfma_f32_16x16x32_bf16 v[58:61], v[154:157], v[186:189], v[58:61]
	v_mfma_f32_16x16x32_bf16 v[54:57], v[146:149], v[194:197], v[54:57]
	v_mfma_f32_16x16x32_bf16 v[50:53], v[154:157], v[194:197], v[50:53]
	v_mfma_f32_16x16x32_bf16 v[42:45], v[146:149], v[202:205], v[42:45]
	v_mfma_f32_16x16x32_bf16 v[34:37], v[154:157], v[202:205], v[34:37]
	v_mfma_f32_16x16x32_bf16 v[26:29], v[146:149], v[210:213], v[26:29]
	v_mfma_f32_16x16x32_bf16 v[18:21], v[154:157], v[210:213], v[18:21]
	v_mfma_f32_16x16x32_bf16 v[46:49], v[158:161], v[182:185], v[46:49]
	v_mfma_f32_16x16x32_bf16 v[38:41], v[166:169], v[182:185], v[38:41]
	v_mfma_f32_16x16x32_bf16 v[30:33], v[158:161], v[190:193], v[30:33]
	v_mfma_f32_16x16x32_bf16 v[22:25], v[166:169], v[190:193], v[22:25]
	v_mfma_f32_16x16x32_bf16 v[14:17], v[158:161], v[198:201], v[14:17]
	v_mfma_f32_16x16x32_bf16 v[10:13], v[166:169], v[198:201], v[10:13]
	v_mfma_f32_16x16x32_bf16 v[6:9], v[158:161], v[206:209], v[6:9]
	v_mfma_f32_16x16x32_bf16 v[2:5], v[166:169], v[206:209], v[2:5]
	v_mfma_f32_16x16x32_bf16 v[46:49], v[162:165], v[186:189], v[46:49]
	v_mfma_f32_16x16x32_bf16 v[38:41], v[178:181], v[186:189], v[38:41]
	v_mfma_f32_16x16x32_bf16 v[30:33], v[162:165], v[194:197], v[30:33]
	v_mfma_f32_16x16x32_bf16 v[22:25], v[178:181], v[194:197], v[22:25]
	v_mfma_f32_16x16x32_bf16 v[14:17], v[162:165], v[202:205], v[14:17]
	v_mfma_f32_16x16x32_bf16 v[10:13], v[178:181], v[202:205], v[10:13]
	v_mfma_f32_16x16x32_bf16 v[6:9], v[162:165], v[210:213], v[6:9]
	v_mfma_f32_16x16x32_bf16 v[2:5], v[178:181], v[210:213], v[2:5]
	s_setprio 0
	s_barrier
	s_add_i32 s39, 0, 0x18000
	v_add_u32_e32 v0, s39, v139
	s_add_i32 s44, 0, 0x1c000
	ds_read_b128 v[142:145], v0
	ds_read_b128 v[146:149], v0 offset:1024
	ds_read_b128 v[150:153], v0 offset:2048
	ds_read_b128 v[154:157], v0 offset:3072
	v_add_u32_e32 v0, s44, v139
	ds_read_b128 v[158:161], v0
	ds_read_b128 v[162:165], v0 offset:1024
	ds_read_b128 v[166:169], v0 offset:2048
	ds_read_b128 v[178:181], v0 offset:3072
	s_add_u32 s20, s20, 0x100000
	s_addc_u32 s21, s21, 0
	s_mov_b32 m0, s22
	v_lshl_add_u64 v[222:223], s[20:21], 0, v[132:133]
	ds_read_b128 v[182:185], v141 offset:32768
	ds_read_b128 v[186:189], v141 offset:33792
	ds_read_b128 v[190:193], v141 offset:34816
	ds_read_b128 v[194:197], v141 offset:35840
	ds_read_b128 v[198:201], v141 offset:36864
	ds_read_b128 v[202:205], v141 offset:37888
	ds_read_b128 v[206:209], v141 offset:38912
	ds_read_b128 v[210:213], v141 offset:39936
	global_load_lds_dwordx4 v[222:223], off
	v_lshl_add_u64 v[222:223], s[20:21], 0, v[130:131]
	s_mov_b32 m0, s23
	s_nop 0
	global_load_lds_dwordx4 v[222:223], off
	s_waitcnt vmcnt(8)
	s_waitcnt lgkmcnt(0)
	s_barrier
	s_setprio 1
	s_waitcnt lgkmcnt(0)
	v_mfma_f32_16x16x32_bf16 v[126:129], v[142:145], v[182:185], v[126:129]
	v_mfma_f32_16x16x32_bf16 v[122:125], v[150:153], v[182:185], v[122:125]
	v_mfma_f32_16x16x32_bf16 v[118:121], v[142:145], v[190:193], v[118:121]
	v_mfma_f32_16x16x32_bf16 v[114:117], v[150:153], v[190:193], v[114:117]
	v_mfma_f32_16x16x32_bf16 v[106:109], v[142:145], v[198:201], v[106:109]
	v_mfma_f32_16x16x32_bf16 v[98:101], v[150:153], v[198:201], v[98:101]
	v_mfma_f32_16x16x32_bf16 v[90:93], v[142:145], v[206:209], v[90:93]
	v_mfma_f32_16x16x32_bf16 v[82:85], v[150:153], v[206:209], v[82:85]
	v_mfma_f32_16x16x32_bf16 v[126:129], v[146:149], v[186:189], v[126:129]
	v_mfma_f32_16x16x32_bf16 v[122:125], v[154:157], v[186:189], v[122:125]
	v_mfma_f32_16x16x32_bf16 v[118:121], v[146:149], v[194:197], v[118:121]
	v_mfma_f32_16x16x32_bf16 v[114:117], v[154:157], v[194:197], v[114:117]
	v_mfma_f32_16x16x32_bf16 v[106:109], v[146:149], v[202:205], v[106:109]
	v_mfma_f32_16x16x32_bf16 v[98:101], v[154:157], v[202:205], v[98:101]
	v_mfma_f32_16x16x32_bf16 v[90:93], v[146:149], v[210:213], v[90:93]
	v_mfma_f32_16x16x32_bf16 v[82:85], v[154:157], v[210:213], v[82:85]
	v_mfma_f32_16x16x32_bf16 v[110:113], v[158:161], v[182:185], v[110:113]
	v_mfma_f32_16x16x32_bf16 v[102:105], v[166:169], v[182:185], v[102:105]
	v_mfma_f32_16x16x32_bf16 v[94:97], v[158:161], v[190:193], v[94:97]
	v_mfma_f32_16x16x32_bf16 v[86:89], v[166:169], v[190:193], v[86:89]
	v_mfma_f32_16x16x32_bf16 v[78:81], v[158:161], v[198:201], v[78:81]
	v_mfma_f32_16x16x32_bf16 v[74:77], v[166:169], v[198:201], v[74:77]
	v_mfma_f32_16x16x32_bf16 v[70:73], v[158:161], v[206:209], v[70:73]
	v_mfma_f32_16x16x32_bf16 v[66:69], v[166:169], v[206:209], v[66:69]
	v_mfma_f32_16x16x32_bf16 v[110:113], v[162:165], v[186:189], v[110:113]
	v_mfma_f32_16x16x32_bf16 v[102:105], v[178:181], v[186:189], v[102:105]
	v_mfma_f32_16x16x32_bf16 v[94:97], v[162:165], v[194:197], v[94:97]
	v_mfma_f32_16x16x32_bf16 v[86:89], v[178:181], v[194:197], v[86:89]
	v_mfma_f32_16x16x32_bf16 v[78:81], v[162:165], v[202:205], v[78:81]
	v_mfma_f32_16x16x32_bf16 v[74:77], v[178:181], v[202:205], v[74:77]
	v_mfma_f32_16x16x32_bf16 v[70:73], v[162:165], v[210:213], v[70:73]
	v_mfma_f32_16x16x32_bf16 v[66:69], v[178:181], v[210:213], v[66:69]
	s_setprio 0
	s_barrier
; #define PG8_STAGE(bufoff, gbase, voff) do { _Pragma("unroll") for (int _i = 0; _i < 2; ++_i) \
;         __builtin_amdgcn_global_load_lds((const unsigned*)((const char*)(gbase) + (voff)[_i]), (PG8_LAS unsigned*)(lds + (bufoff) + ldsw + _i * 8192), 16, 0, 0); } while (0)
; #define PG8_LDA(dst, b, h) do { _Pragma("unroll") for (int m = 0; m < 4; ++m) _Pragma("unroll") for (int k = 0; k < 2; ++k) dst[m][k] = *(const PG8_LAS bf16x8*)(lds + PG8_SA(b, h) + aoff + m * 2048 + k * 1024); } while (0)
; #define PG8_MMA(ai, bj, At, Bt) do { __builtin_amdgcn_s_setprio(1); _Pragma("unroll") for (int m = 0; m < 4; ++m) _Pragma("unroll") for (int n = 0; n < 2; ++n) _Pragma("unroll") for (int k = 0; k < 2; ++k) \
;         acc[ai][bj][m][n] = __builtin_amdgcn_mfma_f32_16x16x32_bf16(Bt[n][k], At[m][k], acc[ai][bj][m][n], 0, 0, 0); __builtin_amdgcn_s_setprio(0); } while (0)
; #define PG8_WAIT_V(n) asm volatile("s_waitcnt vmcnt(" #n ")" ::: "memory")
; #define PG8_WAIT_L(n) asm volatile("s_waitcnt lgkmcnt(" #n ")" ::: "memory")
; #define PG8_BAR __builtin_amdgcn_s_barrier()
; #define PG8_SCHED __builtin_amdgcn_sched_barrier(0)
; template <class Epi, class Sched, bool ALIGN_EPI = false, bool SP2 = false>
; __device__ __forceinline__ void gemm_phase(PG8_LAS unsigned char* lds, const Gemm g, const Sched& S, const Epi& E, const int wave_id) {
;     ...
;             PG8_LDA(At, 1, 1); PG8_STAGE(PG8_SB(1, 0), b3, voffB); PG8_STAGE(PG8_SB(1, 1), b3 + hstepB, voffB); PG8_STAGE(PG8_SA(1, 0), a3, voffA);
;             PG8_WAIT_V(8); PG8_WAIT_L(0); PG8_BAR; PG8_MMA(1, 0, At, B0); PG8_MMA(1, 1, At, B1); PG8_BAR; PG8_SCHED;
	s_add_i32 s20, s39, s0
	v_lshl_add_u64 v[214:215], v[214:215], 0, s[62:63]
	s_mov_b32 m0, s20
	ds_read_b128 v[182:185], v141 offset:49152
	ds_read_b128 v[186:189], v141 offset:50176
	ds_read_b128 v[190:193], v141 offset:51200
	ds_read_b128 v[194:197], v141 offset:52224
	ds_read_b128 v[198:201], v141 offset:53248
	ds_read_b128 v[202:205], v141 offset:54272
	ds_read_b128 v[206:209], v141 offset:55296
	ds_read_b128 v[210:213], v141 offset:56320
	global_load_lds_dwordx4 v[214:215], off
	s_add_i32 m0, s20, 0x2000
	s_add_u32 s18, s18, 0x100080
	v_lshl_add_u64 v[214:215], v[216:217], 0, s[62:63]
	s_addc_u32 s19, s19, 0
	s_add_i32 s20, s44, s0
	global_load_lds_dwordx4 v[214:215], off
	v_lshl_add_u64 v[214:215], s[18:19], 0, v[132:133]
	s_mov_b32 m0, s20
	s_nop 0
	global_load_lds_dwordx4 v[214:215], off
	v_lshl_add_u64 v[214:215], s[18:19], 0, v[130:131]
	s_add_i32 m0, s20, 0x2000
	s_nop 0
	global_load_lds_dwordx4 v[214:215], off
	v_lshl_add_u64 v[214:215], v[218:219], 0, s[62:63]
	s_mov_b32 m0, s24
	s_nop 0
	global_load_lds_dwordx4 v[214:215], off
	v_lshl_add_u64 v[214:215], v[220:221], 0, s[62:63]
	s_mov_b32 m0, s25
	s_nop 0
	global_load_lds_dwordx4 v[214:215], off
	s_waitcnt vmcnt(8)
	s_waitcnt lgkmcnt(0)
	s_barrier
	s_setprio 1
	s_waitcnt lgkmcnt(0)
	v_mfma_f32_16x16x32_bf16 v[62:65], v[142:145], v[182:185], v[62:65]
	v_mfma_f32_16x16x32_bf16 v[58:61], v[150:153], v[182:185], v[58:61]
	v_mfma_f32_16x16x32_bf16 v[54:57], v[142:145], v[190:193], v[54:57]
	v_mfma_f32_16x16x32_bf16 v[50:53], v[150:153], v[190:193], v[50:53]
	v_mfma_f32_16x16x32_bf16 v[42:45], v[142:145], v[198:201], v[42:45]
	v_mfma_f32_16x16x32_bf16 v[34:37], v[150:153], v[198:201], v[34:37]
	v_mfma_f32_16x16x32_bf16 v[26:29], v[142:145], v[206:209], v[26:29]
	v_mfma_f32_16x16x32_bf16 v[18:21], v[150:153], v[206:209], v[18:21]
	v_mfma_f32_16x16x32_bf16 v[62:65], v[146:149], v[186:189], v[62:65]
	v_mfma_f32_16x16x32_bf16 v[58:61], v[154:157], v[186:189], v[58:61]
	v_mfma_f32_16x16x32_bf16 v[54:57], v[146:149], v[194:197], v[54:57]
	v_mfma_f32_16x16x32_bf16 v[50:53], v[154:157], v[194:197], v[50:53]
	v_mfma_f32_16x16x32_bf16 v[42:45], v[146:149], v[202:205], v[42:45]
	v_mfma_f32_16x16x32_bf16 v[34:37], v[154:157], v[202:205], v[34:37]
	v_mfma_f32_16x16x32_bf16 v[26:29], v[146:149], v[210:213], v[26:29]
	v_mfma_f32_16x16x32_bf16 v[18:21], v[154:157], v[210:213], v[18:21]
	v_mfma_f32_16x16x32_bf16 v[46:49], v[158:161], v[182:185], v[46:49]
	v_mfma_f32_16x16x32_bf16 v[38:41], v[166:169], v[182:185], v[38:41]
	v_mfma_f32_16x16x32_bf16 v[30:33], v[158:161], v[190:193], v[30:33]
	v_mfma_f32_16x16x32_bf16 v[22:25], v[166:169], v[190:193], v[22:25]
	v_mfma_f32_16x16x32_bf16 v[14:17], v[158:161], v[198:201], v[14:17]
	v_mfma_f32_16x16x32_bf16 v[10:13], v[166:169], v[198:201], v[10:13]
	v_mfma_f32_16x16x32_bf16 v[6:9], v[158:161], v[206:209], v[6:9]
	v_mfma_f32_16x16x32_bf16 v[2:5], v[166:169], v[206:209], v[2:5]
	v_mfma_f32_16x16x32_bf16 v[46:49], v[162:165], v[186:189], v[46:49]
	v_mfma_f32_16x16x32_bf16 v[38:41], v[178:181], v[186:189], v[38:41]
	v_mfma_f32_16x16x32_bf16 v[30:33], v[162:165], v[194:197], v[30:33]
	v_mfma_f32_16x16x32_bf16 v[22:25], v[178:181], v[194:197], v[22:25]
	v_mfma_f32_16x16x32_bf16 v[14:17], v[162:165], v[202:205], v[14:17]
	v_mfma_f32_16x16x32_bf16 v[10:13], v[178:181], v[202:205], v[10:13]
	v_mfma_f32_16x16x32_bf16 v[6:9], v[162:165], v[210:213], v[6:9]
	v_mfma_f32_16x16x32_bf16 v[2:5], v[178:181], v[210:213], v[2:5]
	s_setprio 0
	s_barrier
	s_add_i32 s38, s38, 2
	s_add_u32 s16, s16, 0x100
	s_addc_u32 s17, s17, 0
	s_add_u32 s36, s36, 0x100
	s_addc_u32 s37, s37, 0
	s_cmp_gt_u32 s38, 5
	s_cbranch_scc0 .LBB0_69
	s_and_b64 vcc, exec, s[10:11]
	s_cbranch_vccz .LBB0_72
	s_barrier

; #define PG8_STAGE(bufoff, gbase, voff) do { _Pragma("unroll") for (int _i = 0; _i < 2; ++_i) \
;         __builtin_amdgcn_global_load_lds((const unsigned*)((const char*)(gbase) + (voff)[_i]), (PG8_LAS unsigned*)(lds + (bufoff) + ldsw + _i * 8192), 16, 0, 0); } while (0)
; #define PG8_LDA(dst, b, h) do { _Pragma("unroll") for (int m = 0; m < 4; ++m) _Pragma("unroll") for (int k = 0; k < 2; ++k) dst[m][k] = *(const PG8_LAS bf16x8*)(lds + PG8_SA(b, h) + aoff + m * 2048 + k * 1024); } while (0)
; #define PG8_MMA(ai, bj, At, Bt) do { __builtin_amdgcn_s_setprio(1); _Pragma("unroll") for (int m = 0; m < 4; ++m) _Pragma("unroll") for (int n = 0; n < 2; ++n) _Pragma("unroll") for (int k = 0; k < 2; ++k) \
;         acc[ai][bj][m][n] = __builtin_amdgcn_mfma_f32_16x16x32_bf16(Bt[n][k], At[m][k], acc[ai][bj][m][n], 0, 0, 0); __builtin_amdgcn_s_setprio(0); } while (0)
; #define PG8_WAIT_V(n) asm volatile("s_waitcnt vmcnt(" #n ")" ::: "memory")
; #define PG8_WAIT_L(n) asm volatile("s_waitcnt lgkmcnt(" #n ")" ::: "memory")
; #define PG8_BAR __builtin_amdgcn_s_barrier()
; #define PG8_SCHED __builtin_amdgcn_sched_barrier(0)
; template <class Epi, class Sched, bool ALIGN_EPI = false, bool SP2 = false>
; __device__ __forceinline__ void gemm_phase(PG8_LAS unsigned char* lds, const Gemm g, const Sched& S, const Epi& E, const int wave_id) {
;     ...
;             PG8_WAIT_V(8); PG8_WAIT_L(0); PG8_BAR; PG8_MMA(0, 0, At, B0); PG8_MMA(0, 1, At, B1); PG8_BAR; PG8_SCHED;
;             PG8_LDA(At, 0, 1); PG8_STAGE(PG8_SB(0, 0), b2, voffB); PG8_STAGE(PG8_SB(0, 1), b2 + hstepB, voffB); PG8_STAGE(PG8_SA(0, 0), a2, voffA);
;             PG8_WAIT_V(8); PG8_WAIT_L(0); PG8_BAR; PG8_MMA(1, 0, At, B0); PG8_MMA(1, 1, At, B1); PG8_BAR; PG8_SCHED;
.Lrw_1:
	s_waitcnt lgkmcnt(0)
	s_barrier
	s_setprio 1
	s_waitcnt lgkmcnt(0)
	v_mfma_f32_16x16x32_bf16 v[134:137], v[138:141], v[190:193], v[134:137]
	v_mfma_f32_16x16x32_bf16 v[130:133], v[146:149], v[190:193], v[130:133]
	v_mfma_f32_16x16x32_bf16 v[118:121], v[138:141], v[198:201], v[118:121]
	v_mfma_f32_16x16x32_bf16 v[114:117], v[146:149], v[198:201], v[114:117]
	v_mfma_f32_16x16x32_bf16 v[102:105], v[138:141], v[214:217], v[102:105]
	v_mfma_f32_16x16x32_bf16 v[98:101], v[146:149], v[214:217], v[98:101]
	v_mfma_f32_16x16x32_bf16 v[86:89], v[138:141], v[222:225], v[86:89]
	v_mfma_f32_16x16x32_bf16 v[82:85], v[146:149], v[222:225], v[82:85]
	v_mfma_f32_16x16x32_bf16 v[134:137], v[142:145], v[194:197], v[134:137]
	v_mfma_f32_16x16x32_bf16 v[130:133], v[150:153], v[194:197], v[130:133]
	v_mfma_f32_16x16x32_bf16 v[118:121], v[142:145], v[210:213], v[118:121]
	v_mfma_f32_16x16x32_bf16 v[114:117], v[150:153], v[210:213], v[114:117]
	v_mfma_f32_16x16x32_bf16 v[102:105], v[142:145], v[218:221], v[102:105]
	v_mfma_f32_16x16x32_bf16 v[98:101], v[150:153], v[218:221], v[98:101]
	v_mfma_f32_16x16x32_bf16 v[86:89], v[142:145], v[234:237], v[86:89]
	v_mfma_f32_16x16x32_bf16 v[82:85], v[150:153], v[234:237], v[82:85]
	v_mfma_f32_16x16x32_bf16 v[126:129], v[154:157], v[190:193], v[126:129]
	v_mfma_f32_16x16x32_bf16 v[122:125], v[162:165], v[190:193], v[122:125]
	v_mfma_f32_16x16x32_bf16 v[110:113], v[154:157], v[198:201], v[110:113]
	v_mfma_f32_16x16x32_bf16 v[106:109], v[162:165], v[198:201], v[106:109]
	v_mfma_f32_16x16x32_bf16 v[94:97], v[154:157], v[214:217], v[94:97]
	v_mfma_f32_16x16x32_bf16 v[90:93], v[162:165], v[214:217], v[90:93]
	v_mfma_f32_16x16x32_bf16 v[78:81], v[154:157], v[222:225], v[78:81]
	v_mfma_f32_16x16x32_bf16 v[74:77], v[162:165], v[222:225], v[74:77]
	v_mfma_f32_16x16x32_bf16 v[126:129], v[158:161], v[194:197], v[126:129]
	v_mfma_f32_16x16x32_bf16 v[122:125], v[166:169], v[194:197], v[122:125]
	v_mfma_f32_16x16x32_bf16 v[110:113], v[158:161], v[210:213], v[110:113]
	v_mfma_f32_16x16x32_bf16 v[106:109], v[166:169], v[210:213], v[106:109]
	v_mfma_f32_16x16x32_bf16 v[94:97], v[158:161], v[218:221], v[94:97]
	v_mfma_f32_16x16x32_bf16 v[90:93], v[166:169], v[218:221], v[90:93]
	v_mfma_f32_16x16x32_bf16 v[78:81], v[158:161], v[234:237], v[78:81]
	v_mfma_f32_16x16x32_bf16 v[74:77], v[166:169], v[234:237], v[74:77]
	s_setprio 0
	s_barrier
	s_add_i32 s10, s37, s15
	v_lshl_add_u64 v[240:241], s[28:29], 0, v[180:181]
	s_mov_b32 m0, s10
	ds_read_b128 v[190:193], v208 offset:16384
	ds_read_b128 v[194:197], v208 offset:17408
	ds_read_b128 v[198:201], v208 offset:18432
	ds_read_b128 v[210:213], v208 offset:19456
	ds_read_b128 v[214:217], v208 offset:20480
	ds_read_b128 v[218:221], v208 offset:21504
	ds_read_b128 v[222:225], v208 offset:22528
	ds_read_b128 v[234:237], v208 offset:23552
	global_load_lds_dwordx4 v[240:241], off
	s_add_i32 m0, s10, 0x2000
	s_add_u32 s10, s28, 0x40000
	v_lshl_add_u64 v[242:243], s[28:29], 0, v[184:185]
	s_addc_u32 s11, s29, 0
	s_add_i32 s37, s39, s15
	global_load_lds_dwordx4 v[242:243], off
	v_lshl_add_u64 v[244:245], s[10:11], 0, v[180:181]
	s_mov_b32 m0, s37
	v_lshl_add_u64 v[246:247], s[30:31], 0, v[182:183]
	global_load_lds_dwordx4 v[244:245], off
	v_lshl_add_u64 v[244:245], s[10:11], 0, v[184:185]
	s_add_i32 m0, s37, 0x2000
	s_nop 0
	global_load_lds_dwordx4 v[244:245], off
	v_lshl_add_u64 v[244:245], s[30:31], 0, v[178:179]
	s_mov_b32 m0, s27
	s_nop 0
	global_load_lds_dwordx4 v[244:245], off
	s_mov_b32 m0, s34
	s_nop 0
	global_load_lds_dwordx4 v[246:247], off
	s_waitcnt vmcnt(24)
	s_cmp_eq_u32 s98, 1
	s_cbranch_scc1 .Lrw_2
	s_waitcnt vmcnt(8)
.Lrw_2:
	s_mov_b32 s98, 0
	s_waitcnt lgkmcnt(0)
	s_barrier
	s_setprio 1
	s_waitcnt lgkmcnt(0)
	v_mfma_f32_16x16x32_bf16 v[70:73], v[138:141], v[190:193], v[70:73]
	v_mfma_f32_16x16x32_bf16 v[66:69], v[146:149], v[190:193], v[66:69]
	v_mfma_f32_16x16x32_bf16 v[54:57], v[138:141], v[198:201], v[54:57]
	v_mfma_f32_16x16x32_bf16 v[50:53], v[146:149], v[198:201], v[50:53]
	v_mfma_f32_16x16x32_bf16 v[38:41], v[138:141], v[214:217], v[38:41]
	v_mfma_f32_16x16x32_bf16 v[34:37], v[146:149], v[214:217], v[34:37]
	v_mfma_f32_16x16x32_bf16 v[22:25], v[138:141], v[222:225], v[22:25]
	v_mfma_f32_16x16x32_bf16 v[18:21], v[146:149], v[222:225], v[18:21]
	v_mfma_f32_16x16x32_bf16 v[70:73], v[142:145], v[194:197], v[70:73]
	v_mfma_f32_16x16x32_bf16 v[66:69], v[150:153], v[194:197], v[66:69]
	v_mfma_f32_16x16x32_bf16 v[54:57], v[142:145], v[210:213], v[54:57]
	v_mfma_f32_16x16x32_bf16 v[50:53], v[150:153], v[210:213], v[50:53]
	v_mfma_f32_16x16x32_bf16 v[38:41], v[142:145], v[218:221], v[38:41]
	v_mfma_f32_16x16x32_bf16 v[34:37], v[150:153], v[218:221], v[34:37]
	v_mfma_f32_16x16x32_bf16 v[22:25], v[142:145], v[234:237], v[22:25]
	v_mfma_f32_16x16x32_bf16 v[18:21], v[150:153], v[234:237], v[18:21]
	v_mfma_f32_16x16x32_bf16 v[62:65], v[154:157], v[190:193], v[62:65]
	v_mfma_f32_16x16x32_bf16 v[58:61], v[162:165], v[190:193], v[58:61]
	v_mfma_f32_16x16x32_bf16 v[46:49], v[154:157], v[198:201], v[46:49]
	v_mfma_f32_16x16x32_bf16 v[42:45], v[162:165], v[198:201], v[42:45]
	v_mfma_f32_16x16x32_bf16 v[30:33], v[154:157], v[214:217], v[30:33]
	v_mfma_f32_16x16x32_bf16 v[26:29], v[162:165], v[214:217], v[26:29]
	v_mfma_f32_16x16x32_bf16 v[14:17], v[154:157], v[222:225], v[14:17]
	v_mfma_f32_16x16x32_bf16 v[10:13], v[162:165], v[222:225], v[10:13]
	v_mfma_f32_16x16x32_bf16 v[62:65], v[158:161], v[194:197], v[62:65]
	v_mfma_f32_16x16x32_bf16 v[58:61], v[166:169], v[194:197], v[58:61]
	v_mfma_f32_16x16x32_bf16 v[46:49], v[158:161], v[210:213], v[46:49]
	v_mfma_f32_16x16x32_bf16 v[42:45], v[166:169], v[210:213], v[42:45]
	v_mfma_f32_16x16x32_bf16 v[30:33], v[158:161], v[218:221], v[30:33]
	v_mfma_f32_16x16x32_bf16 v[26:29], v[166:169], v[218:221], v[26:29]
	v_mfma_f32_16x16x32_bf16 v[14:17], v[158:161], v[234:237], v[14:17]
	v_mfma_f32_16x16x32_bf16 v[10:13], v[166:169], v[234:237], v[10:13]
	s_setprio 0
	s_barrier
; #define PG8_STAGE(bufoff, gbase, voff) do { _Pragma("unroll") for (int _i = 0; _i < 2; ++_i) \
;         __builtin_amdgcn_global_load_lds((const unsigned*)((const char*)(gbase) + (voff)[_i]), (PG8_LAS unsigned*)(lds + (bufoff) + ldsw + _i * 8192), 16, 0, 0); } while (0)
; #define PG8_LDA(dst, b, h) do { _Pragma("unroll") for (int m = 0; m < 4; ++m) _Pragma("unroll") for (int k = 0; k < 2; ++k) dst[m][k] = *(const PG8_LAS bf16x8*)(lds + PG8_SA(b, h) + aoff + m * 2048 + k * 1024); } while (0)
; #define PG8_LDB(dst, b, h) do { _Pragma("unroll") for (int n = 0; n < 2; ++n) _Pragma("unroll") for (int k = 0; k < 2; ++k) dst[n][k] = *(const PG8_LAS bf16x8*)(lds + PG8_SB(b, h) + boff + n * 2048 + k * 1024); } while (0)
; #define PG8_MMA(ai, bj, At, Bt) do { __builtin_amdgcn_s_setprio(1); _Pragma("unroll") for (int m = 0; m < 4; ++m) _Pragma("unroll") for (int n = 0; n < 2; ++n) _Pragma("unroll") for (int k = 0; k < 2; ++k) \
;         acc[ai][bj][m][n] = __builtin_amdgcn_mfma_f32_16x16x32_bf16(Bt[n][k], At[m][k], acc[ai][bj][m][n], 0, 0, 0); __builtin_amdgcn_s_setprio(0); } while (0)
; #define PG8_WAIT_V(n) asm volatile("s_waitcnt vmcnt(" #n ")" ::: "memory")
; #define PG8_WAIT_L(n) asm volatile("s_waitcnt lgkmcnt(" #n ")" ::: "memory")
; #define PG8_BAR __builtin_amdgcn_s_barrier()
; #define PG8_SCHED __builtin_amdgcn_sched_barrier(0)
; template <class Epi, class Sched, bool ALIGN_EPI = false, bool SP2 = false>
; __device__ __forceinline__ void gemm_phase(PG8_LAS unsigned char* lds, const Gemm g, const Sched& S, const Epi& E, const int wave_id) {
;     ...
;             PG8_LDB(B0, 1, 0); PG8_LDB(B1, 1, 1); PG8_SCHED; PG8_LDA(At, 1, 0); PG8_STAGE(PG8_SA(0, 1), a2 + hstepA, voffA);
;             PG8_WAIT_V(8); PG8_WAIT_L(0); PG8_BAR; PG8_MMA(0, 0, At, B0); PG8_MMA(0, 1, At, B1); PG8_BAR; PG8_SCHED;
	s_add_i32 s37, 0, 0x18000
	v_add_u32_e32 v0, s37, v203
	s_add_i32 s39, 0, 0x1c000
	ds_read_b128 v[138:141], v0
	ds_read_b128 v[142:145], v0 offset:1024
	ds_read_b128 v[146:149], v0 offset:2048
	ds_read_b128 v[150:153], v0 offset:3072
	v_add_u32_e32 v0, s39, v203
	ds_read_b128 v[154:157], v0
	ds_read_b128 v[158:161], v0 offset:1024
	ds_read_b128 v[162:165], v0 offset:2048
	ds_read_b128 v[166:169], v0 offset:3072
	s_add_u32 s10, s30, 0x40000
	s_addc_u32 s11, s31, 0
	s_mov_b32 m0, s35
	v_lshl_add_u64 v[248:249], s[10:11], 0, v[178:179]
	ds_read_b128 v[190:193], v208 offset:32768
	ds_read_b128 v[194:197], v208 offset:33792
	ds_read_b128 v[198:201], v208 offset:34816
	ds_read_b128 v[210:213], v208 offset:35840
	ds_read_b128 v[214:217], v208 offset:36864
	ds_read_b128 v[218:221], v208 offset:37888
	ds_read_b128 v[222:225], v208 offset:38912
	ds_read_b128 v[234:237], v208 offset:39936
	global_load_lds_dwordx4 v[248:249], off
	v_lshl_add_u64 v[248:249], s[10:11], 0, v[182:183]
	s_mov_b32 m0, s36
	s_nop 0
	global_load_lds_dwordx4 v[248:249], off
	s_waitcnt vmcnt(8)
	s_waitcnt lgkmcnt(0)
	s_barrier
	s_setprio 1
	s_waitcnt lgkmcnt(0)
	v_mfma_f32_16x16x32_bf16 v[134:137], v[138:141], v[190:193], v[134:137]
	v_mfma_f32_16x16x32_bf16 v[130:133], v[146:149], v[190:193], v[130:133]
	v_mfma_f32_16x16x32_bf16 v[118:121], v[138:141], v[198:201], v[118:121]
	v_mfma_f32_16x16x32_bf16 v[114:117], v[146:149], v[198:201], v[114:117]
	v_mfma_f32_16x16x32_bf16 v[102:105], v[138:141], v[214:217], v[102:105]
	v_mfma_f32_16x16x32_bf16 v[98:101], v[146:149], v[214:217], v[98:101]
	v_mfma_f32_16x16x32_bf16 v[86:89], v[138:141], v[222:225], v[86:89]
	v_mfma_f32_16x16x32_bf16 v[82:85], v[146:149], v[222:225], v[82:85]
	v_mfma_f32_16x16x32_bf16 v[134:137], v[142:145], v[194:197], v[134:137]
	v_mfma_f32_16x16x32_bf16 v[130:133], v[150:153], v[194:197], v[130:133]
	v_mfma_f32_16x16x32_bf16 v[118:121], v[142:145], v[210:213], v[118:121]
	v_mfma_f32_16x16x32_bf16 v[114:117], v[150:153], v[210:213], v[114:117]
	v_mfma_f32_16x16x32_bf16 v[102:105], v[142:145], v[218:221], v[102:105]
	v_mfma_f32_16x16x32_bf16 v[98:101], v[150:153], v[218:221], v[98:101]
	v_mfma_f32_16x16x32_bf16 v[86:89], v[142:145], v[234:237], v[86:89]
	v_mfma_f32_16x16x32_bf16 v[82:85], v[150:153], v[234:237], v[82:85]
	v_mfma_f32_16x16x32_bf16 v[126:129], v[154:157], v[190:193], v[126:129]
	v_mfma_f32_16x16x32_bf16 v[122:125], v[162:165], v[190:193], v[122:125]
	v_mfma_f32_16x16x32_bf16 v[110:113], v[154:157], v[198:201], v[110:113]
	v_mfma_f32_16x16x32_bf16 v[106:109], v[162:165], v[198:201], v[106:109]
	v_mfma_f32_16x16x32_bf16 v[94:97], v[154:157], v[214:217], v[94:97]
	v_mfma_f32_16x16x32_bf16 v[90:93], v[162:165], v[214:217], v[90:93]
	v_mfma_f32_16x16x32_bf16 v[78:81], v[154:157], v[222:225], v[78:81]
	v_mfma_f32_16x16x32_bf16 v[74:77], v[162:165], v[222:225], v[74:77]
	v_mfma_f32_16x16x32_bf16 v[126:129], v[158:161], v[194:197], v[126:129]
	v_mfma_f32_16x16x32_bf16 v[122:125], v[166:169], v[194:197], v[122:125]
	v_mfma_f32_16x16x32_bf16 v[110:113], v[158:161], v[210:213], v[110:113]
	v_mfma_f32_16x16x32_bf16 v[106:109], v[166:169], v[210:213], v[106:109]
	v_mfma_f32_16x16x32_bf16 v[94:97], v[158:161], v[218:221], v[94:97]
	v_mfma_f32_16x16x32_bf16 v[90:93], v[166:169], v[218:221], v[90:93]
	v_mfma_f32_16x16x32_bf16 v[78:81], v[158:161], v[234:237], v[78:81]
	v_mfma_f32_16x16x32_bf16 v[74:77], v[166:169], v[234:237], v[74:77]
	s_setprio 0
	s_barrier
; #define PG8_STAGE(bufoff, gbase, voff) do { _Pragma("unroll") for (int _i = 0; _i < 2; ++_i) \
;         __builtin_amdgcn_global_load_lds((const unsigned*)((const char*)(gbase) + (voff)[_i]), (PG8_LAS unsigned*)(lds + (bufoff) + ldsw + _i * 8192), 16, 0, 0); } while (0)
; #define PG8_LDA(dst, b, h) do { _Pragma("unroll") for (int m = 0; m < 4; ++m) _Pragma("unroll") for (int k = 0; k < 2; ++k) dst[m][k] = *(const PG8_LAS bf16x8*)(lds + PG8_SA(b, h) + aoff + m * 2048 + k * 1024); } while (0)
; #define PG8_MMA(ai, bj, At, Bt) do { __builtin_amdgcn_s_setprio(1); _Pragma("unroll") for (int m = 0; m < 4; ++m) _Pragma("unroll") for (int n = 0; n < 2; ++n) _Pragma("unroll") for (int k = 0; k < 2; ++k) \
;         acc[ai][bj][m][n] = __builtin_amdgcn_mfma_f32_16x16x32_bf16(Bt[n][k], At[m][k], acc[ai][bj][m][n], 0, 0, 0); __builtin_amdgcn_s_setprio(0); } while (0)
; #define PG8_WAIT_V(n) asm volatile("s_waitcnt vmcnt(" #n ")" ::: "memory")
; #define PG8_WAIT_L(n) asm volatile("s_waitcnt lgkmcnt(" #n ")" ::: "memory")
; #define PG8_BAR __builtin_amdgcn_s_barrier()
; #define PG8_SCHED __builtin_amdgcn_sched_barrier(0)
; template <class Epi, class Sched, bool ALIGN_EPI = false, bool SP2 = false>
; __device__ __forceinline__ void gemm_phase(PG8_LAS unsigned char* lds, const Gemm g, const Sched& S, const Epi& E, const int wave_id) {
;     ...
;             PG8_LDA(At, 1, 1); PG8_STAGE(PG8_SB(1, 0), b3, voffB); PG8_STAGE(PG8_SB(1, 1), b3 + hstepB, voffB); PG8_STAGE(PG8_SA(1, 0), a3, voffA);
;             PG8_WAIT_V(8); PG8_WAIT_L(0); PG8_BAR; PG8_MMA(1, 0, At, B0); PG8_MMA(1, 1, At, B1); PG8_BAR; PG8_SCHED;
	s_add_i32 s10, s37, s15
	v_lshl_add_u64 v[240:241], v[240:241], 0, s[62:63]
	s_mov_b32 m0, s10
	ds_read_b128 v[190:193], v208 offset:49152
	ds_read_b128 v[194:197], v208 offset:50176
	ds_read_b128 v[198:201], v208 offset:51200
	ds_read_b128 v[210:213], v208 offset:52224
	ds_read_b128 v[214:217], v208 offset:53248
	ds_read_b128 v[218:221], v208 offset:54272
	ds_read_b128 v[222:225], v208 offset:55296
	ds_read_b128 v[234:237], v208 offset:56320
	global_load_lds_dwordx4 v[240:241], off
	s_add_i32 m0, s10, 0x2000
	s_add_u32 s10, s28, 0x40080
	v_lshl_add_u64 v[240:241], v[242:243], 0, s[62:63]
	s_addc_u32 s11, s29, 0
	s_add_i32 s28, s39, s15
	global_load_lds_dwordx4 v[240:241], off
	v_lshl_add_u64 v[240:241], s[10:11], 0, v[180:181]
	s_mov_b32 m0, s28
	s_nop 0
	global_load_lds_dwordx4 v[240:241], off
	v_lshl_add_u64 v[240:241], s[10:11], 0, v[184:185]
	s_add_i32 m0, s28, 0x2000
	s_nop 0
	global_load_lds_dwordx4 v[240:241], off
	v_lshl_add_u64 v[240:241], v[244:245], 0, s[62:63]
	s_mov_b32 m0, s76
	s_nop 0
	global_load_lds_dwordx4 v[240:241], off
	v_lshl_add_u64 v[240:241], v[246:247], 0, s[62:63]
	s_mov_b32 m0, s77
	s_nop 0
	global_load_lds_dwordx4 v[240:241], off
	s_waitcnt vmcnt(8)
	s_waitcnt lgkmcnt(0)
	s_barrier
	s_setprio 1
	s_waitcnt lgkmcnt(0)
	v_mfma_f32_16x16x32_bf16 v[70:73], v[138:141], v[190:193], v[70:73]
	v_mfma_f32_16x16x32_bf16 v[66:69], v[146:149], v[190:193], v[66:69]
	v_mfma_f32_16x16x32_bf16 v[54:57], v[138:141], v[198:201], v[54:57]
	v_mfma_f32_16x16x32_bf16 v[50:53], v[146:149], v[198:201], v[50:53]
	v_mfma_f32_16x16x32_bf16 v[38:41], v[138:141], v[214:217], v[38:41]
	v_mfma_f32_16x16x32_bf16 v[34:37], v[146:149], v[214:217], v[34:37]
	v_mfma_f32_16x16x32_bf16 v[22:25], v[138:141], v[222:225], v[22:25]
	v_mfma_f32_16x16x32_bf16 v[18:21], v[146:149], v[222:225], v[18:21]
	v_mfma_f32_16x16x32_bf16 v[70:73], v[142:145], v[194:197], v[70:73]
	v_mfma_f32_16x16x32_bf16 v[66:69], v[150:153], v[194:197], v[66:69]
	v_mfma_f32_16x16x32_bf16 v[54:57], v[142:145], v[210:213], v[54:57]
	v_mfma_f32_16x16x32_bf16 v[50:53], v[150:153], v[210:213], v[50:53]
	v_mfma_f32_16x16x32_bf16 v[38:41], v[142:145], v[218:221], v[38:41]
	v_mfma_f32_16x16x32_bf16 v[34:37], v[150:153], v[218:221], v[34:37]
	v_mfma_f32_16x16x32_bf16 v[22:25], v[142:145], v[234:237], v[22:25]
	v_mfma_f32_16x16x32_bf16 v[18:21], v[150:153], v[234:237], v[18:21]
	v_mfma_f32_16x16x32_bf16 v[62:65], v[154:157], v[190:193], v[62:65]
	v_mfma_f32_16x16x32_bf16 v[58:61], v[162:165], v[190:193], v[58:61]
	v_mfma_f32_16x16x32_bf16 v[46:49], v[154:157], v[198:201], v[46:49]
	v_mfma_f32_16x16x32_bf16 v[42:45], v[162:165], v[198:201], v[42:45]
	v_mfma_f32_16x16x32_bf16 v[30:33], v[154:157], v[214:217], v[30:33]
	v_mfma_f32_16x16x32_bf16 v[26:29], v[162:165], v[214:217], v[26:29]
	v_mfma_f32_16x16x32_bf16 v[14:17], v[154:157], v[222:225], v[14:17]
	v_mfma_f32_16x16x32_bf16 v[10:13], v[162:165], v[222:225], v[10:13]
	v_mfma_f32_16x16x32_bf16 v[62:65], v[158:161], v[194:197], v[62:65]
	v_mfma_f32_16x16x32_bf16 v[58:61], v[166:169], v[194:197], v[58:61]
	v_mfma_f32_16x16x32_bf16 v[46:49], v[158:161], v[210:213], v[46:49]
	v_mfma_f32_16x16x32_bf16 v[42:45], v[166:169], v[210:213], v[42:45]
	v_mfma_f32_16x16x32_bf16 v[30:33], v[158:161], v[218:221], v[30:33]
	v_mfma_f32_16x16x32_bf16 v[26:29], v[166:169], v[218:221], v[26:29]
	v_mfma_f32_16x16x32_bf16 v[14:17], v[158:161], v[234:237], v[14:17]
	v_mfma_f32_16x16x32_bf16 v[10:13], v[166:169], v[234:237], v[10:13]
	s_setprio 0
	s_barrier
	s_add_i32 s5, s5, 2
	s_add_u32 s8, s8, 0x100
	s_addc_u32 s9, s9, 0
	s_add_u32 s38, s38, 0x100
	s_addc_u32 s4, s4, 0
	s_cmp_gt_u32 s5, 13
	s_cbranch_scc0 .LBB0_90

; #define PG8_STAGE(bufoff, gbase, voff) do { _Pragma("unroll") for (int _i = 0; _i < 2; ++_i) \
;         __builtin_amdgcn_global_load_lds((const unsigned*)((const char*)(gbase) + (voff)[_i]), (PG8_LAS unsigned*)(lds + (bufoff) + ldsw + _i * 8192), 16, 0, 0); } while (0)
; #define PG8_LDA(dst, b, h) do { _Pragma("unroll") for (int m = 0; m < 4; ++m) _Pragma("unroll") for (int k = 0; k < 2; ++k) dst[m][k] = *(const PG8_LAS bf16x8*)(lds + PG8_SA(b, h) + aoff + m * 2048 + k * 1024); } while (0)
; #define PG8_LDB(dst, b, h) do { _Pragma("unroll") for (int n = 0; n < 2; ++n) _Pragma("unroll") for (int k = 0; k < 2; ++k) dst[n][k] = *(const PG8_LAS bf16x8*)(lds + PG8_SB(b, h) + boff + n * 2048 + k * 1024); } while (0)
; #define PG8_MMA(ai, bj, At, Bt) do { __builtin_amdgcn_s_setprio(1); _Pragma("unroll") for (int m = 0; m < 4; ++m) _Pragma("unroll") for (int n = 0; n < 2; ++n) _Pragma("unroll") for (int k = 0; k < 2; ++k) \
;         acc[ai][bj][m][n] = __builtin_amdgcn_mfma_f32_16x16x32_bf16(Bt[n][k], At[m][k], acc[ai][bj][m][n], 0, 0, 0); __builtin_amdgcn_s_setprio(0); } while (0)
; #define PG8_WAIT_V(n) asm volatile("s_waitcnt vmcnt(" #n ")" ::: "memory")
; #define PG8_WAIT_L(n) asm volatile("s_waitcnt lgkmcnt(" #n ")" ::: "memory")
; #define PG8_BAR __builtin_amdgcn_s_barrier()
; template <class Epi, class Sched, bool ALIGN_EPI = false, bool SP2 = false>
; __device__ __forceinline__ void gemm_phase(PG8_LAS unsigned char* lds, const Gemm g, const Sched& S, const Epi& E, const int wave_id) {
;     ...
;             const char* a1 = cA + (size_t)(t + 1) * kstep;
;             const char* a2 = last ? nA : cA + (size_t)(t + 2) * kstep; const char* b2 = last ? nB : cB + (size_t)(t + 2) * kstep;
;             const char* a3 = a2 + kstep; const char* b3 = b2 + kstep;
;             if (last && has_next) S.a_ready(nxt);
;             if constexpr (SP2) {
;             PG8_LDB(B0, 0, 0); PG8_LDB(B1, 0, 1); PG8_SCHED; PG8_LDA(At, 0, 0); PG8_STAGE(PG8_SA(1, 1), a1 + hstepA, voffA);
;             PG8_WAIT_V(8); PG8_WAIT_L(0); PG8_BAR; PG8_MMA(0, 0, At, B0); PG8_MMA(0, 1, At, B1); PG8_BAR; PG8_SCHED;
;             PG8_LDA(At, 0, 1); PG8_STAGE(PG8_SB(0, 0), b2, voffB); PG8_STAGE(PG8_SB(0, 1), b2 + hstepB, voffB); PG8_STAGE(PG8_SA(0, 0), a2, voffA);
;             PG8_WAIT_V(8); PG8_WAIT_L(0); PG8_BAR; PG8_MMA(1, 0, At, B0); PG8_MMA(1, 1, At, B1); PG8_BAR; PG8_SCHED;
.LBB0_189:
	s_add_u32 s10, s12, 0x100
	s_addc_u32 s11, s13, 0
	s_add_i32 s39, 0, 0x10000
	s_cmp_eq_u32 vcc_lo, 28
	s_cselect_b32 s31, s25, s11
	s_cselect_b32 s30, s24, s10
	v_add_u32_e32 v0, s39, v206
	s_cselect_b32 s29, s23, s91
	s_cselect_b32 s28, s87, s38
	s_add_i32 vcc_hi, 0, 0x14000
	ds_read_b128 v[122:125], v0
	ds_read_b128 v[134:137], v0 offset:1024
	ds_read_b128 v[138:141], v0 offset:2048
	ds_read_b128 v[142:145], v0 offset:3072
	v_add_u32_e32 v0, vcc_hi, v206
	ds_read_b128 v[146:149], v0
	ds_read_b128 v[150:153], v0 offset:1024
	ds_read_b128 v[154:157], v0 offset:2048
	ds_read_b128 v[158:161], v0 offset:3072
	v_lshl_add_u64 v[222:223], s[12:13], 0, v[178:179]
	s_add_i32 m0, s17, 0xc000
	ds_read_b128 v[182:185], v212
	ds_read_b128 v[186:189], v212 offset:1024
	ds_read_b128 v[190:193], v212 offset:2048
	ds_read_b128 v[194:197], v212 offset:3072
	ds_read_b128 v[198:201], v212 offset:4096
	ds_read_b128 v[202:205], v212 offset:5120
	ds_read_b128 v[214:217], v212 offset:6144
	ds_read_b128 v[218:221], v212 offset:7168
	global_load_lds_dwordx4 v[222:223], off
	v_lshl_add_u64 v[222:223], s[12:13], 0, v[180:181]
	s_add_i32 m0, s17, 0xe000
	s_nop 0
	global_load_lds_dwordx4 v[222:223], off
	s_waitcnt vmcnt(8)
	s_waitcnt lgkmcnt(0)
	s_barrier
	s_setprio 1
	s_waitcnt lgkmcnt(0)
	v_mfma_f32_16x16x32_bf16 v[130:133], v[122:125], v[182:185], v[130:133]
	v_mfma_f32_16x16x32_bf16 v[126:129], v[138:141], v[182:185], v[126:129]
	v_mfma_f32_16x16x32_bf16 v[110:113], v[122:125], v[190:193], v[110:113]
	v_mfma_f32_16x16x32_bf16 v[106:109], v[138:141], v[190:193], v[106:109]
	v_mfma_f32_16x16x32_bf16 v[94:97], v[122:125], v[198:201], v[94:97]
	v_mfma_f32_16x16x32_bf16 v[90:93], v[138:141], v[198:201], v[90:93]
	v_mfma_f32_16x16x32_bf16 v[78:81], v[122:125], v[214:217], v[78:81]
	v_mfma_f32_16x16x32_bf16 v[74:77], v[138:141], v[214:217], v[74:77]
	v_mfma_f32_16x16x32_bf16 v[130:133], v[134:137], v[186:189], v[130:133]
	v_mfma_f32_16x16x32_bf16 v[126:129], v[142:145], v[186:189], v[126:129]
	v_mfma_f32_16x16x32_bf16 v[110:113], v[134:137], v[194:197], v[110:113]
	v_mfma_f32_16x16x32_bf16 v[106:109], v[142:145], v[194:197], v[106:109]
	v_mfma_f32_16x16x32_bf16 v[94:97], v[134:137], v[202:205], v[94:97]
	v_mfma_f32_16x16x32_bf16 v[90:93], v[142:145], v[202:205], v[90:93]
	v_mfma_f32_16x16x32_bf16 v[78:81], v[134:137], v[218:221], v[78:81]
	v_mfma_f32_16x16x32_bf16 v[74:77], v[142:145], v[218:221], v[74:77]
	v_mfma_f32_16x16x32_bf16 v[118:121], v[146:149], v[182:185], v[118:121]
	v_mfma_f32_16x16x32_bf16 v[114:117], v[154:157], v[182:185], v[114:117]
	v_mfma_f32_16x16x32_bf16 v[102:105], v[146:149], v[190:193], v[102:105]
	v_mfma_f32_16x16x32_bf16 v[98:101], v[154:157], v[190:193], v[98:101]
	v_mfma_f32_16x16x32_bf16 v[86:89], v[146:149], v[198:201], v[86:89]
	v_mfma_f32_16x16x32_bf16 v[82:85], v[154:157], v[198:201], v[82:85]
	v_mfma_f32_16x16x32_bf16 v[70:73], v[146:149], v[214:217], v[70:73]
	v_mfma_f32_16x16x32_bf16 v[66:69], v[154:157], v[214:217], v[66:69]
	v_mfma_f32_16x16x32_bf16 v[118:121], v[150:153], v[186:189], v[118:121]
	v_mfma_f32_16x16x32_bf16 v[114:117], v[158:161], v[186:189], v[114:117]
	v_mfma_f32_16x16x32_bf16 v[102:105], v[150:153], v[194:197], v[102:105]
	v_mfma_f32_16x16x32_bf16 v[98:101], v[158:161], v[194:197], v[98:101]
	v_mfma_f32_16x16x32_bf16 v[86:89], v[150:153], v[202:205], v[86:89]
	v_mfma_f32_16x16x32_bf16 v[82:85], v[158:161], v[202:205], v[82:85]
	v_mfma_f32_16x16x32_bf16 v[70:73], v[150:153], v[218:221], v[70:73]
	v_mfma_f32_16x16x32_bf16 v[66:69], v[158:161], v[218:221], v[66:69]
	s_setprio 0
	s_barrier
	s_add_i32 s12, s39, s35
	v_lshl_add_u64 v[222:223], s[28:29], 0, v[164:165]
	s_mov_b32 m0, s12
	ds_read_b128 v[182:185], v212 offset:16384
	ds_read_b128 v[186:189], v212 offset:17408
	ds_read_b128 v[190:193], v212 offset:18432
	ds_read_b128 v[194:197], v212 offset:19456
	ds_read_b128 v[198:201], v212 offset:20480
	ds_read_b128 v[202:205], v212 offset:21504
	ds_read_b128 v[214:217], v212 offset:22528
	ds_read_b128 v[218:221], v212 offset:23552
	global_load_lds_dwordx4 v[222:223], off
	s_add_i32 m0, s12, 0x2000
	s_add_u32 s12, s28, 0x80000
	v_lshl_add_u64 v[224:225], s[28:29], 0, v[168:169]
	s_addc_u32 s13, s29, 0
	s_add_i32 s39, vcc_hi, s35
	global_load_lds_dwordx4 v[224:225], off
	v_lshl_add_u64 v[234:235], s[12:13], 0, v[164:165]
	s_mov_b32 m0, s39
	v_lshl_add_u64 v[236:237], s[30:31], 0, v[166:167]
	global_load_lds_dwordx4 v[234:235], off
	v_lshl_add_u64 v[234:235], s[12:13], 0, v[168:169]
	s_add_i32 m0, s39, 0x2000
	s_nop 0
	global_load_lds_dwordx4 v[234:235], off
	v_lshl_add_u64 v[234:235], s[30:31], 0, v[162:163]
	s_mov_b32 m0, s17
	s_nop 0
	global_load_lds_dwordx4 v[234:235], off
	s_mov_b32 m0, s36
	s_nop 0
	global_load_lds_dwordx4 v[236:237], off
	s_waitcnt vmcnt(8)
	s_waitcnt lgkmcnt(0)
	s_barrier
; #define PG8_STAGE(bufoff, gbase, voff) do { _Pragma("unroll") for (int _i = 0; _i < 2; ++_i) \
;         __builtin_amdgcn_global_load_lds((const unsigned*)((const char*)(gbase) + (voff)[_i]), (PG8_LAS unsigned*)(lds + (bufoff) + ldsw + _i * 8192), 16, 0, 0); } while (0)
; #define PG8_LDA(dst, b, h) do { _Pragma("unroll") for (int m = 0; m < 4; ++m) _Pragma("unroll") for (int k = 0; k < 2; ++k) dst[m][k] = *(const PG8_LAS bf16x8*)(lds + PG8_SA(b, h) + aoff + m * 2048 + k * 1024); } while (0)
; #define PG8_LDB(dst, b, h) do { _Pragma("unroll") for (int n = 0; n < 2; ++n) _Pragma("unroll") for (int k = 0; k < 2; ++k) dst[n][k] = *(const PG8_LAS bf16x8*)(lds + PG8_SB(b, h) + boff + n * 2048 + k * 1024); } while (0)
; #define PG8_MMA(ai, bj, At, Bt) do { __builtin_amdgcn_s_setprio(1); _Pragma("unroll") for (int m = 0; m < 4; ++m) _Pragma("unroll") for (int n = 0; n < 2; ++n) _Pragma("unroll") for (int k = 0; k < 2; ++k) \
;         acc[ai][bj][m][n] = __builtin_amdgcn_mfma_f32_16x16x32_bf16(Bt[n][k], At[m][k], acc[ai][bj][m][n], 0, 0, 0); __builtin_amdgcn_s_setprio(0); } while (0)
; #define PG8_WAIT_V(n) asm volatile("s_waitcnt vmcnt(" #n ")" ::: "memory")
; #define PG8_WAIT_L(n) asm volatile("s_waitcnt lgkmcnt(" #n ")" ::: "memory")
; #define PG8_BAR __builtin_amdgcn_s_barrier()
; #define PG8_SCHED __builtin_amdgcn_sched_barrier(0)
; template <class Epi, class Sched, bool ALIGN_EPI = false, bool SP2 = false>
; __device__ __forceinline__ void gemm_phase(PG8_LAS unsigned char* lds, const Gemm g, const Sched& S, const Epi& E, const int wave_id) {
;     ...
;             PG8_WAIT_V(8); PG8_WAIT_L(0); PG8_BAR; PG8_MMA(1, 0, At, B0); PG8_MMA(1, 1, At, B1); PG8_BAR; PG8_SCHED;
;             PG8_LDB(B0, 1, 0); PG8_LDB(B1, 1, 1); PG8_SCHED; PG8_LDA(At, 1, 0); PG8_STAGE(PG8_SA(0, 1), a2 + hstepA, voffA);
;             PG8_WAIT_V(8); PG8_WAIT_L(0); PG8_BAR; PG8_MMA(0, 0, At, B0); PG8_MMA(0, 1, At, B1); PG8_BAR; PG8_SCHED;
	s_setprio 1
	s_waitcnt lgkmcnt(0)
	v_mfma_f32_16x16x32_bf16 v[62:65], v[122:125], v[182:185], v[62:65]
	v_mfma_f32_16x16x32_bf16 v[58:61], v[138:141], v[182:185], v[58:61]
	v_mfma_f32_16x16x32_bf16 v[46:49], v[122:125], v[190:193], v[46:49]
	v_mfma_f32_16x16x32_bf16 v[42:45], v[138:141], v[190:193], v[42:45]
	v_mfma_f32_16x16x32_bf16 v[30:33], v[122:125], v[198:201], v[30:33]
	v_mfma_f32_16x16x32_bf16 v[26:29], v[138:141], v[198:201], v[26:29]
	v_mfma_f32_16x16x32_bf16 v[14:17], v[122:125], v[214:217], v[14:17]
	v_mfma_f32_16x16x32_bf16 v[10:13], v[138:141], v[214:217], v[10:13]
	v_mfma_f32_16x16x32_bf16 v[62:65], v[134:137], v[186:189], v[62:65]
	v_mfma_f32_16x16x32_bf16 v[58:61], v[142:145], v[186:189], v[58:61]
	v_mfma_f32_16x16x32_bf16 v[46:49], v[134:137], v[194:197], v[46:49]
	v_mfma_f32_16x16x32_bf16 v[42:45], v[142:145], v[194:197], v[42:45]
	v_mfma_f32_16x16x32_bf16 v[30:33], v[134:137], v[202:205], v[30:33]
	v_mfma_f32_16x16x32_bf16 v[26:29], v[142:145], v[202:205], v[26:29]
	v_mfma_f32_16x16x32_bf16 v[14:17], v[134:137], v[218:221], v[14:17]
	v_mfma_f32_16x16x32_bf16 v[10:13], v[142:145], v[218:221], v[10:13]
	v_mfma_f32_16x16x32_bf16 v[54:57], v[146:149], v[182:185], v[54:57]
	v_mfma_f32_16x16x32_bf16 v[50:53], v[154:157], v[182:185], v[50:53]
	v_mfma_f32_16x16x32_bf16 v[38:41], v[146:149], v[190:193], v[38:41]
	v_mfma_f32_16x16x32_bf16 v[34:37], v[154:157], v[190:193], v[34:37]
	v_mfma_f32_16x16x32_bf16 v[22:25], v[146:149], v[198:201], v[22:25]
	v_mfma_f32_16x16x32_bf16 v[18:21], v[154:157], v[198:201], v[18:21]
	v_mfma_f32_16x16x32_bf16 v[6:9], v[146:149], v[214:217], v[6:9]
	v_mfma_f32_16x16x32_bf16 v[2:5], v[154:157], v[214:217], v[2:5]
	v_mfma_f32_16x16x32_bf16 v[54:57], v[150:153], v[186:189], v[54:57]
	v_mfma_f32_16x16x32_bf16 v[50:53], v[158:161], v[186:189], v[50:53]
	v_mfma_f32_16x16x32_bf16 v[38:41], v[150:153], v[194:197], v[38:41]
	v_mfma_f32_16x16x32_bf16 v[34:37], v[158:161], v[194:197], v[34:37]
	v_mfma_f32_16x16x32_bf16 v[22:25], v[150:153], v[202:205], v[22:25]
	v_mfma_f32_16x16x32_bf16 v[18:21], v[158:161], v[202:205], v[18:21]
	v_mfma_f32_16x16x32_bf16 v[6:9], v[150:153], v[218:221], v[6:9]
	v_mfma_f32_16x16x32_bf16 v[2:5], v[158:161], v[218:221], v[2:5]
	s_setprio 0
	s_barrier
	s_add_i32 s39, 0, 0x18000
	v_add_u32_e32 v0, s39, v206
	s_add_i32 vcc_hi, 0, 0x1c000
	ds_read_b128 v[122:125], v0
	ds_read_b128 v[134:137], v0 offset:1024
	ds_read_b128 v[138:141], v0 offset:2048
	ds_read_b128 v[142:145], v0 offset:3072
	v_add_u32_e32 v0, vcc_hi, v206
	ds_read_b128 v[146:149], v0
	ds_read_b128 v[150:153], v0 offset:1024
	ds_read_b128 v[154:157], v0 offset:2048
	ds_read_b128 v[158:161], v0 offset:3072
	s_add_u32 s12, s30, 0x180000
	s_addc_u32 s13, s31, 0
	s_mov_b32 m0, s37
	v_lshl_add_u64 v[240:241], s[12:13], 0, v[162:163]
	ds_read_b128 v[182:185], v212 offset:32768
	ds_read_b128 v[186:189], v212 offset:33792
	ds_read_b128 v[190:193], v212 offset:34816
	ds_read_b128 v[194:197], v212 offset:35840
	ds_read_b128 v[198:201], v212 offset:36864
	ds_read_b128 v[202:205], v212 offset:37888
	ds_read_b128 v[214:217], v212 offset:38912
	ds_read_b128 v[218:221], v212 offset:39936
	global_load_lds_dwordx4 v[240:241], off
	v_lshl_add_u64 v[240:241], s[12:13], 0, v[166:167]
	s_mov_b32 m0, s76
	s_nop 0
	global_load_lds_dwordx4 v[240:241], off
	s_waitcnt vmcnt(8)
	s_waitcnt lgkmcnt(0)
	s_barrier
	s_setprio 1
	s_waitcnt lgkmcnt(0)
	v_mfma_f32_16x16x32_bf16 v[130:133], v[122:125], v[182:185], v[130:133]
	v_mfma_f32_16x16x32_bf16 v[126:129], v[138:141], v[182:185], v[126:129]
	v_mfma_f32_16x16x32_bf16 v[110:113], v[122:125], v[190:193], v[110:113]
	v_mfma_f32_16x16x32_bf16 v[106:109], v[138:141], v[190:193], v[106:109]
	v_mfma_f32_16x16x32_bf16 v[94:97], v[122:125], v[198:201], v[94:97]
	v_mfma_f32_16x16x32_bf16 v[90:93], v[138:141], v[198:201], v[90:93]
	v_mfma_f32_16x16x32_bf16 v[78:81], v[122:125], v[214:217], v[78:81]
	v_mfma_f32_16x16x32_bf16 v[74:77], v[138:141], v[214:217], v[74:77]
	v_mfma_f32_16x16x32_bf16 v[130:133], v[134:137], v[186:189], v[130:133]
	v_mfma_f32_16x16x32_bf16 v[126:129], v[142:145], v[186:189], v[126:129]
	v_mfma_f32_16x16x32_bf16 v[110:113], v[134:137], v[194:197], v[110:113]
	v_mfma_f32_16x16x32_bf16 v[106:109], v[142:145], v[194:197], v[106:109]
	v_mfma_f32_16x16x32_bf16 v[94:97], v[134:137], v[202:205], v[94:97]
	v_mfma_f32_16x16x32_bf16 v[90:93], v[142:145], v[202:205], v[90:93]
	v_mfma_f32_16x16x32_bf16 v[78:81], v[134:137], v[218:221], v[78:81]
	v_mfma_f32_16x16x32_bf16 v[74:77], v[142:145], v[218:221], v[74:77]
	v_mfma_f32_16x16x32_bf16 v[118:121], v[146:149], v[182:185], v[118:121]
	v_mfma_f32_16x16x32_bf16 v[114:117], v[154:157], v[182:185], v[114:117]
	v_mfma_f32_16x16x32_bf16 v[102:105], v[146:149], v[190:193], v[102:105]
	v_mfma_f32_16x16x32_bf16 v[98:101], v[154:157], v[190:193], v[98:101]
	v_mfma_f32_16x16x32_bf16 v[86:89], v[146:149], v[198:201], v[86:89]
	v_mfma_f32_16x16x32_bf16 v[82:85], v[154:157], v[198:201], v[82:85]
	v_mfma_f32_16x16x32_bf16 v[70:73], v[146:149], v[214:217], v[70:73]
	v_mfma_f32_16x16x32_bf16 v[66:69], v[154:157], v[214:217], v[66:69]
	v_mfma_f32_16x16x32_bf16 v[118:121], v[150:153], v[186:189], v[118:121]
	v_mfma_f32_16x16x32_bf16 v[114:117], v[158:161], v[186:189], v[114:117]
	v_mfma_f32_16x16x32_bf16 v[102:105], v[150:153], v[194:197], v[102:105]
	v_mfma_f32_16x16x32_bf16 v[98:101], v[158:161], v[194:197], v[98:101]
	v_mfma_f32_16x16x32_bf16 v[86:89], v[150:153], v[202:205], v[86:89]
	v_mfma_f32_16x16x32_bf16 v[82:85], v[158:161], v[202:205], v[82:85]
	v_mfma_f32_16x16x32_bf16 v[70:73], v[150:153], v[218:221], v[70:73]
	v_mfma_f32_16x16x32_bf16 v[66:69], v[158:161], v[218:221], v[66:69]
	s_setprio 0
	s_barrier
; #define PG8_STAGE(bufoff, gbase, voff) do { _Pragma("unroll") for (int _i = 0; _i < 2; ++_i) \
;         __builtin_amdgcn_global_load_lds((const unsigned*)((const char*)(gbase) + (voff)[_i]), (PG8_LAS unsigned*)(lds + (bufoff) + ldsw + _i * 8192), 16, 0, 0); } while (0)
; #define PG8_LDA(dst, b, h) do { _Pragma("unroll") for (int m = 0; m < 4; ++m) _Pragma("unroll") for (int k = 0; k < 2; ++k) dst[m][k] = *(const PG8_LAS bf16x8*)(lds + PG8_SA(b, h) + aoff + m * 2048 + k * 1024); } while (0)
; #define PG8_MMA(ai, bj, At, Bt) do { __builtin_amdgcn_s_setprio(1); _Pragma("unroll") for (int m = 0; m < 4; ++m) _Pragma("unroll") for (int n = 0; n < 2; ++n) _Pragma("unroll") for (int k = 0; k < 2; ++k) \
;         acc[ai][bj][m][n] = __builtin_amdgcn_mfma_f32_16x16x32_bf16(Bt[n][k], At[m][k], acc[ai][bj][m][n], 0, 0, 0); __builtin_amdgcn_s_setprio(0); } while (0)
; #define PG8_WAIT_V(n) asm volatile("s_waitcnt vmcnt(" #n ")" ::: "memory")
; #define PG8_WAIT_L(n) asm volatile("s_waitcnt lgkmcnt(" #n ")" ::: "memory")
; #define PG8_BAR __builtin_amdgcn_s_barrier()
; #define PG8_SCHED __builtin_amdgcn_sched_barrier(0)
; template <class Epi, class Sched, bool ALIGN_EPI = false, bool SP2 = false>
; __device__ __forceinline__ void gemm_phase(PG8_LAS unsigned char* lds, const Gemm g, const Sched& S, const Epi& E, const int wave_id) {
;     ...
;             PG8_LDA(At, 1, 1); PG8_STAGE(PG8_SB(1, 0), b3, voffB); PG8_STAGE(PG8_SB(1, 1), b3 + hstepB, voffB); PG8_STAGE(PG8_SA(1, 0), a3, voffA);
;             PG8_WAIT_V(8); PG8_WAIT_L(0); PG8_BAR; PG8_MMA(1, 0, At, B0); PG8_MMA(1, 1, At, B1); PG8_BAR; PG8_SCHED;
;     ...
;         if constexpr (ALIGN_EPI) { if (wr == 0) PG8_BAR; }
	s_add_i32 s12, s39, s35
	v_lshl_add_u64 v[222:223], v[222:223], 0, s[62:63]
	s_mov_b32 m0, s12
	ds_read_b128 v[182:185], v212 offset:49152
	ds_read_b128 v[186:189], v212 offset:50176
	ds_read_b128 v[190:193], v212 offset:51200
	ds_read_b128 v[194:197], v212 offset:52224
	ds_read_b128 v[198:201], v212 offset:53248
	ds_read_b128 v[202:205], v212 offset:54272
	ds_read_b128 v[214:217], v212 offset:55296
	ds_read_b128 v[218:221], v212 offset:56320
	global_load_lds_dwordx4 v[222:223], off
	s_add_i32 m0, s12, 0x2000
	s_add_u32 s12, s28, 0x80080
	v_lshl_add_u64 v[222:223], v[224:225], 0, s[62:63]
	s_addc_u32 s13, s29, 0
	s_add_i32 s28, vcc_hi, s35
	global_load_lds_dwordx4 v[222:223], off
	v_lshl_add_u64 v[222:223], s[12:13], 0, v[164:165]
	s_mov_b32 m0, s28
	s_nop 0
	global_load_lds_dwordx4 v[222:223], off
	v_lshl_add_u64 v[222:223], s[12:13], 0, v[168:169]
	s_add_i32 m0, s28, 0x2000
	s_nop 0
	global_load_lds_dwordx4 v[222:223], off
	v_lshl_add_u64 v[222:223], v[234:235], 0, s[62:63]
	s_mov_b32 m0, s80
	s_nop 0
	global_load_lds_dwordx4 v[222:223], off
	v_lshl_add_u64 v[222:223], v[236:237], 0, s[62:63]
	s_mov_b32 m0, s81
	s_nop 0
	global_load_lds_dwordx4 v[222:223], off
	s_waitcnt vmcnt(8)
	s_waitcnt lgkmcnt(0)
	s_barrier
	s_setprio 1
	s_waitcnt lgkmcnt(0)
	v_mfma_f32_16x16x32_bf16 v[62:65], v[122:125], v[182:185], v[62:65]
	v_mfma_f32_16x16x32_bf16 v[58:61], v[138:141], v[182:185], v[58:61]
	v_mfma_f32_16x16x32_bf16 v[46:49], v[122:125], v[190:193], v[46:49]
	v_mfma_f32_16x16x32_bf16 v[42:45], v[138:141], v[190:193], v[42:45]
	v_mfma_f32_16x16x32_bf16 v[30:33], v[122:125], v[198:201], v[30:33]
	v_mfma_f32_16x16x32_bf16 v[26:29], v[138:141], v[198:201], v[26:29]
	v_mfma_f32_16x16x32_bf16 v[14:17], v[122:125], v[214:217], v[14:17]
	v_mfma_f32_16x16x32_bf16 v[10:13], v[138:141], v[214:217], v[10:13]
	v_mfma_f32_16x16x32_bf16 v[62:65], v[134:137], v[186:189], v[62:65]
	v_mfma_f32_16x16x32_bf16 v[58:61], v[142:145], v[186:189], v[58:61]
	v_mfma_f32_16x16x32_bf16 v[46:49], v[134:137], v[194:197], v[46:49]
	v_mfma_f32_16x16x32_bf16 v[42:45], v[142:145], v[194:197], v[42:45]
	v_mfma_f32_16x16x32_bf16 v[30:33], v[134:137], v[202:205], v[30:33]
	v_mfma_f32_16x16x32_bf16 v[26:29], v[142:145], v[202:205], v[26:29]
	v_mfma_f32_16x16x32_bf16 v[14:17], v[134:137], v[218:221], v[14:17]
	v_mfma_f32_16x16x32_bf16 v[10:13], v[142:145], v[218:221], v[10:13]
	v_mfma_f32_16x16x32_bf16 v[54:57], v[146:149], v[182:185], v[54:57]
	v_mfma_f32_16x16x32_bf16 v[50:53], v[154:157], v[182:185], v[50:53]
	v_mfma_f32_16x16x32_bf16 v[38:41], v[146:149], v[190:193], v[38:41]
	v_mfma_f32_16x16x32_bf16 v[34:37], v[154:157], v[190:193], v[34:37]
	v_mfma_f32_16x16x32_bf16 v[22:25], v[146:149], v[198:201], v[22:25]
	v_mfma_f32_16x16x32_bf16 v[18:21], v[154:157], v[198:201], v[18:21]
	v_mfma_f32_16x16x32_bf16 v[6:9], v[146:149], v[214:217], v[6:9]
	v_mfma_f32_16x16x32_bf16 v[2:5], v[154:157], v[214:217], v[2:5]
	v_mfma_f32_16x16x32_bf16 v[54:57], v[150:153], v[186:189], v[54:57]
	v_mfma_f32_16x16x32_bf16 v[50:53], v[158:161], v[186:189], v[50:53]
	v_mfma_f32_16x16x32_bf16 v[38:41], v[150:153], v[194:197], v[38:41]
	v_mfma_f32_16x16x32_bf16 v[34:37], v[158:161], v[194:197], v[34:37]
	v_mfma_f32_16x16x32_bf16 v[22:25], v[150:153], v[202:205], v[22:25]
	v_mfma_f32_16x16x32_bf16 v[18:21], v[158:161], v[202:205], v[18:21]
	v_mfma_f32_16x16x32_bf16 v[6:9], v[150:153], v[218:221], v[6:9]
	v_mfma_f32_16x16x32_bf16 v[2:5], v[158:161], v[218:221], v[2:5]
	s_setprio 0
	s_barrier
	s_add_i32 vcc_lo, vcc_lo, 2
	s_add_u32 s38, s38, 0x100
	s_addc_u32 s91, s91, 0
	s_cmp_gt_u32 vcc_lo, 29
	s_mov_b64 s[12:13], s[10:11]
	s_cbranch_scc0 .LBB0_189
	s_and_b64 vcc, exec, s[20:21]
	s_cbranch_vccz .LBB0_192
	s_barrier

; #define PG8_STAGE(bufoff, gbase, voff) do { _Pragma("unroll") for (int _i = 0; _i < 2; ++_i) \
;         __builtin_amdgcn_global_load_lds((const unsigned*)((const char*)(gbase) + (voff)[_i]), (PG8_LAS unsigned*)(lds + (bufoff) + ldsw + _i * 8192), 16, 0, 0); } while (0)
; #define PG8_LDA(dst, b, h) do { _Pragma("unroll") for (int m = 0; m < 4; ++m) _Pragma("unroll") for (int k = 0; k < 2; ++k) dst[m][k] = *(const PG8_LAS bf16x8*)(lds + PG8_SA(b, h) + aoff + m * 2048 + k * 1024); } while (0)
; #define PG8_LDB(dst, b, h) do { _Pragma("unroll") for (int n = 0; n < 2; ++n) _Pragma("unroll") for (int k = 0; k < 2; ++k) dst[n][k] = *(const PG8_LAS bf16x8*)(lds + PG8_SB(b, h) + boff + n * 2048 + k * 1024); } while (0)
; #define PG8_MMA(ai, bj, At, Bt) do { __builtin_amdgcn_s_setprio(1); _Pragma("unroll") for (int m = 0; m < 4; ++m) _Pragma("unroll") for (int n = 0; n < 2; ++n) _Pragma("unroll") for (int k = 0; k < 2; ++k) \
;         acc[ai][bj][m][n] = __builtin_amdgcn_mfma_f32_16x16x32_bf16(Bt[n][k], At[m][k], acc[ai][bj][m][n], 0, 0, 0); __builtin_amdgcn_s_setprio(0); } while (0)
; #define PG8_WAIT_V(n) asm volatile("s_waitcnt vmcnt(" #n ")" ::: "memory")
; #define PG8_WAIT_L(n) asm volatile("s_waitcnt lgkmcnt(" #n ")" ::: "memory")
; #define PG8_BAR __builtin_amdgcn_s_barrier()
; template <class Epi, class Sched, bool ALIGN_EPI = false, bool SP2 = false>
; __device__ __forceinline__ void gemm_phase(PG8_LAS unsigned char* lds, const Gemm g, const Sched& S, const Epi& E, const int wave_id) {
;     ...
;             const char* a1 = cA + (size_t)(t + 1) * kstep;
;             const char* a2 = last ? nA : cA + (size_t)(t + 2) * kstep; const char* b2 = last ? nB : cB + (size_t)(t + 2) * kstep;
;             const char* a3 = a2 + kstep; const char* b3 = b2 + kstep;
;             if (last && has_next) S.a_ready(nxt);
;             if constexpr (SP2) {
;             PG8_LDB(B0, 0, 0); PG8_LDB(B1, 0, 1); PG8_SCHED; PG8_LDA(At, 0, 0); PG8_STAGE(PG8_SA(1, 1), a1 + hstepA, voffA);
;             PG8_WAIT_V(8); PG8_WAIT_L(0); PG8_BAR; PG8_MMA(0, 0, At, B0); PG8_MMA(0, 1, At, B1); PG8_BAR; PG8_SCHED;
;             PG8_LDA(At, 0, 1); PG8_STAGE(PG8_SB(0, 0), b2, voffB); PG8_STAGE(PG8_SB(0, 1), b2 + hstepB, voffB); PG8_STAGE(PG8_SA(0, 0), a2, voffA);
;             PG8_WAIT_V(8); PG8_WAIT_L(0); PG8_BAR; PG8_MMA(1, 0, At, B0); PG8_MMA(1, 1, At, B1); PG8_BAR; PG8_SCHED;
.LBB0_297:
	s_add_u32 s12, s10, 0xfffc0080
	s_addc_u32 s13, s11, -1
	s_add_i32 s20, 0, 0x10000
	s_cmp_eq_u32 vcc_lo, 12
	s_cselect_b32 s35, s15, s13
	s_cselect_b32 s34, s27, s12
	v_add_u32_e32 v0, s20, v206
	s_cselect_b32 s13, s25, s38
	s_cselect_b32 s12, s36, s37
	s_add_i32 vcc_hi, 0, 0x14000
	ds_read_b128 v[122:125], v0
	ds_read_b128 v[134:137], v0 offset:1024
	ds_read_b128 v[138:141], v0 offset:2048
	ds_read_b128 v[142:145], v0 offset:3072
	v_add_u32_e32 v0, vcc_hi, v206
	ds_read_b128 v[146:149], v0
	ds_read_b128 v[150:153], v0 offset:1024
	ds_read_b128 v[154:157], v0 offset:2048
	ds_read_b128 v[158:161], v0 offset:3072
	v_lshl_add_u64 v[222:223], s[10:11], 0, v[178:179]
	s_add_i32 m0, s17, 0xc000
	ds_read_b128 v[182:185], v212
	ds_read_b128 v[186:189], v212 offset:1024
	ds_read_b128 v[190:193], v212 offset:2048
	ds_read_b128 v[194:197], v212 offset:3072
	ds_read_b128 v[198:201], v212 offset:4096
	ds_read_b128 v[202:205], v212 offset:5120
	ds_read_b128 v[214:217], v212 offset:6144
	ds_read_b128 v[218:221], v212 offset:7168
	global_load_lds_dwordx4 v[222:223], off
	v_lshl_add_u64 v[222:223], s[10:11], 0, v[180:181]
	s_add_i32 m0, s17, 0xe000
	s_nop 0
	global_load_lds_dwordx4 v[222:223], off
	s_waitcnt vmcnt(8)
	s_waitcnt lgkmcnt(0)
	s_barrier
	s_setprio 1
	s_waitcnt lgkmcnt(0)
	v_mfma_f32_16x16x32_bf16 v[130:133], v[122:125], v[182:185], v[130:133]
	v_mfma_f32_16x16x32_bf16 v[126:129], v[138:141], v[182:185], v[126:129]
	v_mfma_f32_16x16x32_bf16 v[110:113], v[122:125], v[190:193], v[110:113]
	v_mfma_f32_16x16x32_bf16 v[106:109], v[138:141], v[190:193], v[106:109]
	v_mfma_f32_16x16x32_bf16 v[94:97], v[122:125], v[198:201], v[94:97]
	v_mfma_f32_16x16x32_bf16 v[90:93], v[138:141], v[198:201], v[90:93]
	v_mfma_f32_16x16x32_bf16 v[78:81], v[122:125], v[214:217], v[78:81]
	v_mfma_f32_16x16x32_bf16 v[74:77], v[138:141], v[214:217], v[74:77]
	v_mfma_f32_16x16x32_bf16 v[130:133], v[134:137], v[186:189], v[130:133]
	v_mfma_f32_16x16x32_bf16 v[126:129], v[142:145], v[186:189], v[126:129]
	v_mfma_f32_16x16x32_bf16 v[110:113], v[134:137], v[194:197], v[110:113]
	v_mfma_f32_16x16x32_bf16 v[106:109], v[142:145], v[194:197], v[106:109]
	v_mfma_f32_16x16x32_bf16 v[94:97], v[134:137], v[202:205], v[94:97]
	v_mfma_f32_16x16x32_bf16 v[90:93], v[142:145], v[202:205], v[90:93]
	v_mfma_f32_16x16x32_bf16 v[78:81], v[134:137], v[218:221], v[78:81]
	v_mfma_f32_16x16x32_bf16 v[74:77], v[142:145], v[218:221], v[74:77]
	v_mfma_f32_16x16x32_bf16 v[118:121], v[146:149], v[182:185], v[118:121]
	v_mfma_f32_16x16x32_bf16 v[114:117], v[154:157], v[182:185], v[114:117]
	v_mfma_f32_16x16x32_bf16 v[102:105], v[146:149], v[190:193], v[102:105]
	v_mfma_f32_16x16x32_bf16 v[98:101], v[154:157], v[190:193], v[98:101]
	v_mfma_f32_16x16x32_bf16 v[86:89], v[146:149], v[198:201], v[86:89]
	v_mfma_f32_16x16x32_bf16 v[82:85], v[154:157], v[198:201], v[82:85]
	v_mfma_f32_16x16x32_bf16 v[70:73], v[146:149], v[214:217], v[70:73]
	v_mfma_f32_16x16x32_bf16 v[66:69], v[154:157], v[214:217], v[66:69]
	v_mfma_f32_16x16x32_bf16 v[118:121], v[150:153], v[186:189], v[118:121]
	v_mfma_f32_16x16x32_bf16 v[114:117], v[158:161], v[186:189], v[114:117]
	v_mfma_f32_16x16x32_bf16 v[102:105], v[150:153], v[194:197], v[102:105]
	v_mfma_f32_16x16x32_bf16 v[98:101], v[158:161], v[194:197], v[98:101]
	v_mfma_f32_16x16x32_bf16 v[86:89], v[150:153], v[202:205], v[86:89]
	v_mfma_f32_16x16x32_bf16 v[82:85], v[158:161], v[202:205], v[82:85]
	v_mfma_f32_16x16x32_bf16 v[70:73], v[150:153], v[218:221], v[70:73]
	v_mfma_f32_16x16x32_bf16 v[66:69], v[158:161], v[218:221], v[66:69]
	s_setprio 0
	s_barrier
	s_add_i32 s20, s20, s76
	v_lshl_add_u64 v[222:223], s[12:13], 0, v[164:165]
	s_mov_b32 m0, s20
	ds_read_b128 v[182:185], v212 offset:16384
	ds_read_b128 v[186:189], v212 offset:17408
	ds_read_b128 v[190:193], v212 offset:18432
	ds_read_b128 v[194:197], v212 offset:19456
	ds_read_b128 v[198:201], v212 offset:20480
	ds_read_b128 v[202:205], v212 offset:21504
	ds_read_b128 v[214:217], v212 offset:22528
	ds_read_b128 v[218:221], v212 offset:23552
	global_load_lds_dwordx4 v[222:223], off
	s_add_i32 m0, s20, 0x2000
	s_add_u32 s20, s12, 0x40000
	v_lshl_add_u64 v[224:225], s[12:13], 0, v[168:169]
	s_addc_u32 s21, s13, 0
	s_add_i32 vcc_hi, vcc_hi, s76
	global_load_lds_dwordx4 v[224:225], off
	v_lshl_add_u64 v[234:235], s[20:21], 0, v[164:165]
	s_mov_b32 m0, vcc_hi
	v_lshl_add_u64 v[236:237], s[34:35], 0, v[166:167]
	global_load_lds_dwordx4 v[234:235], off
	v_lshl_add_u64 v[234:235], s[20:21], 0, v[168:169]
	s_add_i32 m0, vcc_hi, 0x2000
	s_nop 0
	global_load_lds_dwordx4 v[234:235], off
	v_lshl_add_u64 v[234:235], s[34:35], 0, v[162:163]
	s_mov_b32 m0, s17
	s_nop 0
	global_load_lds_dwordx4 v[234:235], off
	s_mov_b32 m0, s19
	s_nop 0
	global_load_lds_dwordx4 v[236:237], off
	s_waitcnt vmcnt(8)
	s_waitcnt lgkmcnt(0)
	s_barrier
; #define PG8_STAGE(bufoff, gbase, voff) do { _Pragma("unroll") for (int _i = 0; _i < 2; ++_i) \
;         __builtin_amdgcn_global_load_lds((const unsigned*)((const char*)(gbase) + (voff)[_i]), (PG8_LAS unsigned*)(lds + (bufoff) + ldsw + _i * 8192), 16, 0, 0); } while (0)
; #define PG8_LDA(dst, b, h) do { _Pragma("unroll") for (int m = 0; m < 4; ++m) _Pragma("unroll") for (int k = 0; k < 2; ++k) dst[m][k] = *(const PG8_LAS bf16x8*)(lds + PG8_SA(b, h) + aoff + m * 2048 + k * 1024); } while (0)
; #define PG8_LDB(dst, b, h) do { _Pragma("unroll") for (int n = 0; n < 2; ++n) _Pragma("unroll") for (int k = 0; k < 2; ++k) dst[n][k] = *(const PG8_LAS bf16x8*)(lds + PG8_SB(b, h) + boff + n * 2048 + k * 1024); } while (0)
; #define PG8_MMA(ai, bj, At, Bt) do { __builtin_amdgcn_s_setprio(1); _Pragma("unroll") for (int m = 0; m < 4; ++m) _Pragma("unroll") for (int n = 0; n < 2; ++n) _Pragma("unroll") for (int k = 0; k < 2; ++k) \
;         acc[ai][bj][m][n] = __builtin_amdgcn_mfma_f32_16x16x32_bf16(Bt[n][k], At[m][k], acc[ai][bj][m][n], 0, 0, 0); __builtin_amdgcn_s_setprio(0); } while (0)
; #define PG8_WAIT_V(n) asm volatile("s_waitcnt vmcnt(" #n ")" ::: "memory")
; #define PG8_WAIT_L(n) asm volatile("s_waitcnt lgkmcnt(" #n ")" ::: "memory")
; #define PG8_BAR __builtin_amdgcn_s_barrier()
; #define PG8_SCHED __builtin_amdgcn_sched_barrier(0)
; template <class Epi, class Sched, bool ALIGN_EPI = false, bool SP2 = false>
; __device__ __forceinline__ void gemm_phase(PG8_LAS unsigned char* lds, const Gemm g, const Sched& S, const Epi& E, const int wave_id) {
;     ...
;             PG8_WAIT_V(8); PG8_WAIT_L(0); PG8_BAR; PG8_MMA(1, 0, At, B0); PG8_MMA(1, 1, At, B1); PG8_BAR; PG8_SCHED;
;             PG8_LDB(B0, 1, 0); PG8_LDB(B1, 1, 1); PG8_SCHED; PG8_LDA(At, 1, 0); PG8_STAGE(PG8_SA(0, 1), a2 + hstepA, voffA);
;             PG8_WAIT_V(8); PG8_WAIT_L(0); PG8_BAR; PG8_MMA(0, 0, At, B0); PG8_MMA(0, 1, At, B1); PG8_BAR; PG8_SCHED;
	s_setprio 1
	s_waitcnt lgkmcnt(0)
	v_mfma_f32_16x16x32_bf16 v[62:65], v[122:125], v[182:185], v[62:65]
	v_mfma_f32_16x16x32_bf16 v[58:61], v[138:141], v[182:185], v[58:61]
	v_mfma_f32_16x16x32_bf16 v[46:49], v[122:125], v[190:193], v[46:49]
	v_mfma_f32_16x16x32_bf16 v[42:45], v[138:141], v[190:193], v[42:45]
	v_mfma_f32_16x16x32_bf16 v[30:33], v[122:125], v[198:201], v[30:33]
	v_mfma_f32_16x16x32_bf16 v[26:29], v[138:141], v[198:201], v[26:29]
	v_mfma_f32_16x16x32_bf16 v[14:17], v[122:125], v[214:217], v[14:17]
	v_mfma_f32_16x16x32_bf16 v[10:13], v[138:141], v[214:217], v[10:13]
	v_mfma_f32_16x16x32_bf16 v[62:65], v[134:137], v[186:189], v[62:65]
	v_mfma_f32_16x16x32_bf16 v[58:61], v[142:145], v[186:189], v[58:61]
	v_mfma_f32_16x16x32_bf16 v[46:49], v[134:137], v[194:197], v[46:49]
	v_mfma_f32_16x16x32_bf16 v[42:45], v[142:145], v[194:197], v[42:45]
	v_mfma_f32_16x16x32_bf16 v[30:33], v[134:137], v[202:205], v[30:33]
	v_mfma_f32_16x16x32_bf16 v[26:29], v[142:145], v[202:205], v[26:29]
	v_mfma_f32_16x16x32_bf16 v[14:17], v[134:137], v[218:221], v[14:17]
	v_mfma_f32_16x16x32_bf16 v[10:13], v[142:145], v[218:221], v[10:13]
	v_mfma_f32_16x16x32_bf16 v[54:57], v[146:149], v[182:185], v[54:57]
	v_mfma_f32_16x16x32_bf16 v[50:53], v[154:157], v[182:185], v[50:53]
	v_mfma_f32_16x16x32_bf16 v[38:41], v[146:149], v[190:193], v[38:41]
	v_mfma_f32_16x16x32_bf16 v[34:37], v[154:157], v[190:193], v[34:37]
	v_mfma_f32_16x16x32_bf16 v[22:25], v[146:149], v[198:201], v[22:25]
	v_mfma_f32_16x16x32_bf16 v[18:21], v[154:157], v[198:201], v[18:21]
	v_mfma_f32_16x16x32_bf16 v[6:9], v[146:149], v[214:217], v[6:9]
	v_mfma_f32_16x16x32_bf16 v[2:5], v[154:157], v[214:217], v[2:5]
	v_mfma_f32_16x16x32_bf16 v[54:57], v[150:153], v[186:189], v[54:57]
	v_mfma_f32_16x16x32_bf16 v[50:53], v[158:161], v[186:189], v[50:53]
	v_mfma_f32_16x16x32_bf16 v[38:41], v[150:153], v[194:197], v[38:41]
	v_mfma_f32_16x16x32_bf16 v[34:37], v[158:161], v[194:197], v[34:37]
	v_mfma_f32_16x16x32_bf16 v[22:25], v[150:153], v[202:205], v[22:25]
	v_mfma_f32_16x16x32_bf16 v[18:21], v[158:161], v[202:205], v[18:21]
	v_mfma_f32_16x16x32_bf16 v[6:9], v[150:153], v[218:221], v[6:9]
	v_mfma_f32_16x16x32_bf16 v[2:5], v[158:161], v[218:221], v[2:5]
	s_setprio 0
	s_barrier
	s_add_i32 vcc_hi, 0, 0x18000
	v_add_u32_e32 v0, vcc_hi, v206
	s_add_i32 s39, 0, 0x1c000
	ds_read_b128 v[122:125], v0
	ds_read_b128 v[134:137], v0 offset:1024
	ds_read_b128 v[138:141], v0 offset:2048
	ds_read_b128 v[142:145], v0 offset:3072
	v_add_u32_e32 v0, s39, v206
	ds_read_b128 v[146:149], v0
	ds_read_b128 v[150:153], v0 offset:1024
	ds_read_b128 v[154:157], v0 offset:2048
	ds_read_b128 v[158:161], v0 offset:3072
	s_add_u32 s20, s34, 0x40000
	s_addc_u32 s21, s35, 0
	s_mov_b32 m0, s77
	v_lshl_add_u64 v[240:241], s[20:21], 0, v[162:163]
	ds_read_b128 v[182:185], v212 offset:32768
	ds_read_b128 v[186:189], v212 offset:33792
	ds_read_b128 v[190:193], v212 offset:34816
	ds_read_b128 v[194:197], v212 offset:35840
	ds_read_b128 v[198:201], v212 offset:36864
	ds_read_b128 v[202:205], v212 offset:37888
	ds_read_b128 v[214:217], v212 offset:38912
	ds_read_b128 v[218:221], v212 offset:39936
	global_load_lds_dwordx4 v[240:241], off
	v_lshl_add_u64 v[240:241], s[20:21], 0, v[166:167]
	s_mov_b32 m0, s80
	s_nop 0
	global_load_lds_dwordx4 v[240:241], off
	s_waitcnt vmcnt(8)
	s_waitcnt lgkmcnt(0)
	s_barrier
	s_setprio 1
	s_waitcnt lgkmcnt(0)
	v_mfma_f32_16x16x32_bf16 v[130:133], v[122:125], v[182:185], v[130:133]
	v_mfma_f32_16x16x32_bf16 v[126:129], v[138:141], v[182:185], v[126:129]
	v_mfma_f32_16x16x32_bf16 v[110:113], v[122:125], v[190:193], v[110:113]
	v_mfma_f32_16x16x32_bf16 v[106:109], v[138:141], v[190:193], v[106:109]
	v_mfma_f32_16x16x32_bf16 v[94:97], v[122:125], v[198:201], v[94:97]
	v_mfma_f32_16x16x32_bf16 v[90:93], v[138:141], v[198:201], v[90:93]
	v_mfma_f32_16x16x32_bf16 v[78:81], v[122:125], v[214:217], v[78:81]
	v_mfma_f32_16x16x32_bf16 v[74:77], v[138:141], v[214:217], v[74:77]
	v_mfma_f32_16x16x32_bf16 v[130:133], v[134:137], v[186:189], v[130:133]
	v_mfma_f32_16x16x32_bf16 v[126:129], v[142:145], v[186:189], v[126:129]
	v_mfma_f32_16x16x32_bf16 v[110:113], v[134:137], v[194:197], v[110:113]
	v_mfma_f32_16x16x32_bf16 v[106:109], v[142:145], v[194:197], v[106:109]
	v_mfma_f32_16x16x32_bf16 v[94:97], v[134:137], v[202:205], v[94:97]
	v_mfma_f32_16x16x32_bf16 v[90:93], v[142:145], v[202:205], v[90:93]
	v_mfma_f32_16x16x32_bf16 v[78:81], v[134:137], v[218:221], v[78:81]
	v_mfma_f32_16x16x32_bf16 v[74:77], v[142:145], v[218:221], v[74:77]
	v_mfma_f32_16x16x32_bf16 v[118:121], v[146:149], v[182:185], v[118:121]
	v_mfma_f32_16x16x32_bf16 v[114:117], v[154:157], v[182:185], v[114:117]
	v_mfma_f32_16x16x32_bf16 v[102:105], v[146:149], v[190:193], v[102:105]
	v_mfma_f32_16x16x32_bf16 v[98:101], v[154:157], v[190:193], v[98:101]
	v_mfma_f32_16x16x32_bf16 v[86:89], v[146:149], v[198:201], v[86:89]
	v_mfma_f32_16x16x32_bf16 v[82:85], v[154:157], v[198:201], v[82:85]
	v_mfma_f32_16x16x32_bf16 v[70:73], v[146:149], v[214:217], v[70:73]
	v_mfma_f32_16x16x32_bf16 v[66:69], v[154:157], v[214:217], v[66:69]
	v_mfma_f32_16x16x32_bf16 v[118:121], v[150:153], v[186:189], v[118:121]
	v_mfma_f32_16x16x32_bf16 v[114:117], v[158:161], v[186:189], v[114:117]
	v_mfma_f32_16x16x32_bf16 v[102:105], v[150:153], v[194:197], v[102:105]
	v_mfma_f32_16x16x32_bf16 v[98:101], v[158:161], v[194:197], v[98:101]
	v_mfma_f32_16x16x32_bf16 v[86:89], v[150:153], v[202:205], v[86:89]
	v_mfma_f32_16x16x32_bf16 v[82:85], v[158:161], v[202:205], v[82:85]
	v_mfma_f32_16x16x32_bf16 v[70:73], v[150:153], v[218:221], v[70:73]
	v_mfma_f32_16x16x32_bf16 v[66:69], v[158:161], v[218:221], v[66:69]
	s_setprio 0
	s_barrier
; #define PG8_STAGE(bufoff, gbase, voff) do { _Pragma("unroll") for (int _i = 0; _i < 2; ++_i) \
;         __builtin_amdgcn_global_load_lds((const unsigned*)((const char*)(gbase) + (voff)[_i]), (PG8_LAS unsigned*)(lds + (bufoff) + ldsw + _i * 8192), 16, 0, 0); } while (0)
; #define PG8_LDA(dst, b, h) do { _Pragma("unroll") for (int m = 0; m < 4; ++m) _Pragma("unroll") for (int k = 0; k < 2; ++k) dst[m][k] = *(const PG8_LAS bf16x8*)(lds + PG8_SA(b, h) + aoff + m * 2048 + k * 1024); } while (0)
; #define PG8_MMA(ai, bj, At, Bt) do { __builtin_amdgcn_s_setprio(1); _Pragma("unroll") for (int m = 0; m < 4; ++m) _Pragma("unroll") for (int n = 0; n < 2; ++n) _Pragma("unroll") for (int k = 0; k < 2; ++k) \
;         acc[ai][bj][m][n] = __builtin_amdgcn_mfma_f32_16x16x32_bf16(Bt[n][k], At[m][k], acc[ai][bj][m][n], 0, 0, 0); __builtin_amdgcn_s_setprio(0); } while (0)
; #define PG8_WAIT_V(n) asm volatile("s_waitcnt vmcnt(" #n ")" ::: "memory")
; #define PG8_WAIT_L(n) asm volatile("s_waitcnt lgkmcnt(" #n ")" ::: "memory")
; #define PG8_BAR __builtin_amdgcn_s_barrier()
; #define PG8_SCHED __builtin_amdgcn_sched_barrier(0)
; template <class Epi, class Sched, bool ALIGN_EPI = false, bool SP2 = false>
; __device__ __forceinline__ void gemm_phase(PG8_LAS unsigned char* lds, const Gemm g, const Sched& S, const Epi& E, const int wave_id) {
;     ...
;         for (int t = 0; t < nt; t += 2) {
;             const bool last = (t == nt - 2);
;     ...
;             PG8_LDA(At, 1, 1); PG8_STAGE(PG8_SB(1, 0), b3, voffB); PG8_STAGE(PG8_SB(1, 1), b3 + hstepB, voffB); PG8_STAGE(PG8_SA(1, 0), a3, voffA);
;             PG8_WAIT_V(8); PG8_WAIT_L(0); PG8_BAR; PG8_MMA(1, 0, At, B0); PG8_MMA(1, 1, At, B1); PG8_BAR; PG8_SCHED;
	s_add_i32 s20, vcc_hi, s76
	v_lshl_add_u64 v[222:223], v[222:223], 0, s[62:63]
	s_mov_b32 m0, s20
	ds_read_b128 v[182:185], v212 offset:49152
	ds_read_b128 v[186:189], v212 offset:50176
	ds_read_b128 v[190:193], v212 offset:51200
	ds_read_b128 v[194:197], v212 offset:52224
	ds_read_b128 v[198:201], v212 offset:53248
	ds_read_b128 v[202:205], v212 offset:54272
	ds_read_b128 v[214:217], v212 offset:55296
	ds_read_b128 v[218:221], v212 offset:56320
	global_load_lds_dwordx4 v[222:223], off
	s_add_i32 m0, s20, 0x2000
	s_add_u32 s12, s12, 0x40080
	v_lshl_add_u64 v[222:223], v[224:225], 0, s[62:63]
	s_addc_u32 s13, s13, 0
	s_add_i32 s20, s39, s76
	global_load_lds_dwordx4 v[222:223], off
	v_lshl_add_u64 v[222:223], s[12:13], 0, v[164:165]
	s_mov_b32 m0, s20
	s_nop 0
	global_load_lds_dwordx4 v[222:223], off
	v_lshl_add_u64 v[222:223], s[12:13], 0, v[168:169]
	s_add_i32 m0, s20, 0x2000
	s_nop 0
	global_load_lds_dwordx4 v[222:223], off
	v_lshl_add_u64 v[222:223], v[234:235], 0, s[62:63]
	s_mov_b32 m0, s82
	s_nop 0
	global_load_lds_dwordx4 v[222:223], off
	v_lshl_add_u64 v[222:223], v[236:237], 0, s[62:63]
	s_mov_b32 m0, s83
	s_nop 0
	global_load_lds_dwordx4 v[222:223], off
	s_waitcnt vmcnt(8)
	s_waitcnt lgkmcnt(0)
	s_barrier
	s_setprio 1
	s_waitcnt lgkmcnt(0)
	v_mfma_f32_16x16x32_bf16 v[62:65], v[122:125], v[182:185], v[62:65]
	v_mfma_f32_16x16x32_bf16 v[58:61], v[138:141], v[182:185], v[58:61]
	v_mfma_f32_16x16x32_bf16 v[46:49], v[122:125], v[190:193], v[46:49]
	v_mfma_f32_16x16x32_bf16 v[42:45], v[138:141], v[190:193], v[42:45]
	v_mfma_f32_16x16x32_bf16 v[30:33], v[122:125], v[198:201], v[30:33]
	v_mfma_f32_16x16x32_bf16 v[26:29], v[138:141], v[198:201], v[26:29]
	v_mfma_f32_16x16x32_bf16 v[14:17], v[122:125], v[214:217], v[14:17]
	v_mfma_f32_16x16x32_bf16 v[10:13], v[138:141], v[214:217], v[10:13]
	v_mfma_f32_16x16x32_bf16 v[62:65], v[134:137], v[186:189], v[62:65]
	v_mfma_f32_16x16x32_bf16 v[58:61], v[142:145], v[186:189], v[58:61]
	v_mfma_f32_16x16x32_bf16 v[46:49], v[134:137], v[194:197], v[46:49]
	v_mfma_f32_16x16x32_bf16 v[42:45], v[142:145], v[194:197], v[42:45]
	v_mfma_f32_16x16x32_bf16 v[30:33], v[134:137], v[202:205], v[30:33]
	v_mfma_f32_16x16x32_bf16 v[26:29], v[142:145], v[202:205], v[26:29]
	v_mfma_f32_16x16x32_bf16 v[14:17], v[134:137], v[218:221], v[14:17]
	v_mfma_f32_16x16x32_bf16 v[10:13], v[142:145], v[218:221], v[10:13]
	v_mfma_f32_16x16x32_bf16 v[54:57], v[146:149], v[182:185], v[54:57]
	v_mfma_f32_16x16x32_bf16 v[50:53], v[154:157], v[182:185], v[50:53]
	v_mfma_f32_16x16x32_bf16 v[38:41], v[146:149], v[190:193], v[38:41]
	v_mfma_f32_16x16x32_bf16 v[34:37], v[154:157], v[190:193], v[34:37]
	v_mfma_f32_16x16x32_bf16 v[22:25], v[146:149], v[198:201], v[22:25]
	v_mfma_f32_16x16x32_bf16 v[18:21], v[154:157], v[198:201], v[18:21]
	v_mfma_f32_16x16x32_bf16 v[6:9], v[146:149], v[214:217], v[6:9]
	v_mfma_f32_16x16x32_bf16 v[2:5], v[154:157], v[214:217], v[2:5]
	v_mfma_f32_16x16x32_bf16 v[54:57], v[150:153], v[186:189], v[54:57]
	v_mfma_f32_16x16x32_bf16 v[50:53], v[158:161], v[186:189], v[50:53]
	v_mfma_f32_16x16x32_bf16 v[38:41], v[150:153], v[194:197], v[38:41]
	v_mfma_f32_16x16x32_bf16 v[34:37], v[158:161], v[194:197], v[34:37]
	v_mfma_f32_16x16x32_bf16 v[22:25], v[150:153], v[202:205], v[22:25]
	v_mfma_f32_16x16x32_bf16 v[18:21], v[158:161], v[202:205], v[18:21]
	v_mfma_f32_16x16x32_bf16 v[6:9], v[150:153], v[218:221], v[6:9]
	v_mfma_f32_16x16x32_bf16 v[2:5], v[158:161], v[218:221], v[2:5]
	s_setprio 0
	s_barrier
	s_add_i32 vcc_lo, vcc_lo, 2
	s_add_u32 s10, s10, 0x100
	s_addc_u32 s11, s11, 0
	s_add_u32 s37, s37, 0x100
	s_addc_u32 s38, s38, 0
	s_cmp_gt_u32 vcc_lo, 13
	s_cbranch_scc0 .LBB0_297
	s_and_b64 vcc, exec, s[22:23]
	s_cbranch_vccz .LBB0_300
	s_barrier

; #define PG8_STAGE(bufoff, gbase, voff) do { _Pragma("unroll") for (int _i = 0; _i < 2; ++_i) \
;         __builtin_amdgcn_global_load_lds((const unsigned*)((const char*)(gbase) + (voff)[_i]), (PG8_LAS unsigned*)(lds + (bufoff) + ldsw + _i * 8192), 16, 0, 0); } while (0)
; #define PG8_LDA(dst, b, h) do { _Pragma("unroll") for (int m = 0; m < 4; ++m) _Pragma("unroll") for (int k = 0; k < 2; ++k) dst[m][k] = *(const PG8_LAS bf16x8*)(lds + PG8_SA(b, h) + aoff + m * 2048 + k * 1024); } while (0)
; #define PG8_MMA(ai, bj, At, Bt) do { __builtin_amdgcn_s_setprio(1); _Pragma("unroll") for (int m = 0; m < 4; ++m) _Pragma("unroll") for (int n = 0; n < 2; ++n) _Pragma("unroll") for (int k = 0; k < 2; ++k) \
;         acc[ai][bj][m][n] = __builtin_amdgcn_mfma_f32_16x16x32_bf16(Bt[n][k], At[m][k], acc[ai][bj][m][n], 0, 0, 0); __builtin_amdgcn_s_setprio(0); } while (0)
; #define PG8_WAIT_V(n) asm volatile("s_waitcnt vmcnt(" #n ")" ::: "memory")
; #define PG8_WAIT_L(n) asm volatile("s_waitcnt lgkmcnt(" #n ")" ::: "memory")
; #define PG8_BAR __builtin_amdgcn_s_barrier()
; #define PG8_SCHED __builtin_amdgcn_sched_barrier(0)
; template <class Epi, class Sched, bool ALIGN_EPI = false, bool SP2 = false>
; __device__ __forceinline__ void gemm_phase(PG8_LAS unsigned char* lds, const Gemm g, const Sched& S, const Epi& E, const int wave_id) {
;     ...
;             PG8_WAIT_V(8); PG8_WAIT_L(0); PG8_BAR; PG8_MMA(0, 0, At, B0); PG8_MMA(0, 1, At, B1); PG8_BAR; PG8_SCHED;
;             PG8_LDA(At, 0, 1); PG8_STAGE(PG8_SB(0, 0), b2, voffB); PG8_STAGE(PG8_SB(0, 1), b2 + hstepB, voffB); PG8_STAGE(PG8_SA(0, 0), a2, voffA);
;             PG8_WAIT_V(8); PG8_WAIT_L(0); PG8_BAR; PG8_MMA(1, 0, At, B0); PG8_MMA(1, 1, At, B1); PG8_BAR; PG8_SCHED;
.Lrw_3:
	s_waitcnt lgkmcnt(0)
	s_barrier
	s_setprio 1
	s_waitcnt lgkmcnt(0)
	v_mfma_f32_16x16x32_bf16 v[134:137], v[138:141], v[190:193], v[134:137]
	v_mfma_f32_16x16x32_bf16 v[130:133], v[146:149], v[190:193], v[130:133]
	v_mfma_f32_16x16x32_bf16 v[122:125], v[138:141], v[198:201], v[122:125]
	v_mfma_f32_16x16x32_bf16 v[114:117], v[146:149], v[198:201], v[114:117]
	v_mfma_f32_16x16x32_bf16 v[106:109], v[138:141], v[216:219], v[106:109]
	v_mfma_f32_16x16x32_bf16 v[98:101], v[146:149], v[216:219], v[98:101]
	v_mfma_f32_16x16x32_bf16 v[90:93], v[138:141], v[240:243], v[90:93]
	v_mfma_f32_16x16x32_bf16 v[82:85], v[146:149], v[240:243], v[82:85]
	v_mfma_f32_16x16x32_bf16 v[134:137], v[142:145], v[194:197], v[134:137]
	v_mfma_f32_16x16x32_bf16 v[130:133], v[150:153], v[194:197], v[130:133]
	v_mfma_f32_16x16x32_bf16 v[122:125], v[142:145], v[202:205], v[122:125]
	v_mfma_f32_16x16x32_bf16 v[114:117], v[150:153], v[202:205], v[114:117]
	v_mfma_f32_16x16x32_bf16 v[106:109], v[142:145], v[220:223], v[106:109]
	v_mfma_f32_16x16x32_bf16 v[98:101], v[150:153], v[220:223], v[98:101]
	v_mfma_f32_16x16x32_bf16 v[90:93], v[142:145], v[244:247], v[90:93]
	v_mfma_f32_16x16x32_bf16 v[82:85], v[150:153], v[244:247], v[82:85]
	v_mfma_f32_16x16x32_bf16 v[126:129], v[154:157], v[190:193], v[126:129]
	v_mfma_f32_16x16x32_bf16 v[118:121], v[162:165], v[190:193], v[118:121]
	v_mfma_f32_16x16x32_bf16 v[110:113], v[154:157], v[198:201], v[110:113]
	v_mfma_f32_16x16x32_bf16 v[102:105], v[162:165], v[198:201], v[102:105]
	v_mfma_f32_16x16x32_bf16 v[94:97], v[154:157], v[216:219], v[94:97]
	v_mfma_f32_16x16x32_bf16 v[86:89], v[162:165], v[216:219], v[86:89]
	v_mfma_f32_16x16x32_bf16 v[78:81], v[154:157], v[240:243], v[78:81]
	v_mfma_f32_16x16x32_bf16 v[74:77], v[162:165], v[240:243], v[74:77]
	v_mfma_f32_16x16x32_bf16 v[126:129], v[158:161], v[194:197], v[126:129]
	v_mfma_f32_16x16x32_bf16 v[118:121], v[166:169], v[194:197], v[118:121]
	v_mfma_f32_16x16x32_bf16 v[110:113], v[158:161], v[202:205], v[110:113]
	v_mfma_f32_16x16x32_bf16 v[102:105], v[166:169], v[202:205], v[102:105]
	v_mfma_f32_16x16x32_bf16 v[94:97], v[158:161], v[220:223], v[94:97]
	v_mfma_f32_16x16x32_bf16 v[86:89], v[166:169], v[220:223], v[86:89]
	v_mfma_f32_16x16x32_bf16 v[78:81], v[158:161], v[244:247], v[78:81]
	v_mfma_f32_16x16x32_bf16 v[74:77], v[166:169], v[244:247], v[74:77]
	s_setprio 0
	s_barrier
	s_add_i32 s0, s35, s23
	v_lshl_add_u64 v[206:207], s[26:27], 0, v[180:181]
	s_mov_b32 m0, s0
	ds_read_b128 v[190:193], v215 offset:16384
	ds_read_b128 v[194:197], v215 offset:17408
	ds_read_b128 v[198:201], v215 offset:18432
	ds_read_b128 v[202:205], v215 offset:19456
	ds_read_b128 v[216:219], v215 offset:20480
	ds_read_b128 v[220:223], v215 offset:21504
	ds_read_b128 v[240:243], v215 offset:22528
	ds_read_b128 v[244:247], v215 offset:23552
	global_load_lds_dwordx4 v[206:207], off
	s_add_i32 m0, s0, 0x2000
	s_add_u32 s0, s26, 0x40000
	v_lshl_add_u64 v[224:225], s[26:27], 0, v[184:185]
	s_addc_u32 s1, s27, 0
	s_add_i32 s35, s36, s23
	global_load_lds_dwordx4 v[224:225], off
	v_lshl_add_u64 v[234:235], s[0:1], 0, v[180:181]
	s_mov_b32 m0, s35
	v_lshl_add_u64 v[236:237], s[28:29], 0, v[182:183]
	global_load_lds_dwordx4 v[234:235], off
	v_lshl_add_u64 v[234:235], s[0:1], 0, v[184:185]
	s_add_i32 m0, s35, 0x2000
	s_nop 0
	global_load_lds_dwordx4 v[234:235], off
	v_lshl_add_u64 v[234:235], s[28:29], 0, v[178:179]
	s_mov_b32 m0, s25
	s_nop 0
	global_load_lds_dwordx4 v[234:235], off
	s_mov_b32 m0, s30
	s_nop 0
	global_load_lds_dwordx4 v[236:237], off
	s_waitcnt vmcnt(24)
	s_cmp_eq_u32 s98, 1
	s_cbranch_scc1 .Lrw_4
	s_waitcnt vmcnt(8)
.Lrw_4:
	s_mov_b32 s98, 0
	s_waitcnt lgkmcnt(0)
	s_barrier
	s_setprio 1
	s_waitcnt lgkmcnt(0)
	v_mfma_f32_16x16x32_bf16 v[70:73], v[138:141], v[190:193], v[70:73]
	v_mfma_f32_16x16x32_bf16 v[66:69], v[146:149], v[190:193], v[66:69]
	v_mfma_f32_16x16x32_bf16 v[58:61], v[138:141], v[198:201], v[58:61]
	v_mfma_f32_16x16x32_bf16 v[50:53], v[146:149], v[198:201], v[50:53]
	v_mfma_f32_16x16x32_bf16 v[42:45], v[138:141], v[216:219], v[42:45]
	v_mfma_f32_16x16x32_bf16 v[34:37], v[146:149], v[216:219], v[34:37]
	v_mfma_f32_16x16x32_bf16 v[26:29], v[138:141], v[240:243], v[26:29]
	v_mfma_f32_16x16x32_bf16 v[18:21], v[146:149], v[240:243], v[18:21]
	v_mfma_f32_16x16x32_bf16 v[70:73], v[142:145], v[194:197], v[70:73]
	v_mfma_f32_16x16x32_bf16 v[66:69], v[150:153], v[194:197], v[66:69]
	v_mfma_f32_16x16x32_bf16 v[58:61], v[142:145], v[202:205], v[58:61]
	v_mfma_f32_16x16x32_bf16 v[50:53], v[150:153], v[202:205], v[50:53]
	v_mfma_f32_16x16x32_bf16 v[42:45], v[142:145], v[220:223], v[42:45]
	v_mfma_f32_16x16x32_bf16 v[34:37], v[150:153], v[220:223], v[34:37]
	v_mfma_f32_16x16x32_bf16 v[26:29], v[142:145], v[244:247], v[26:29]
	v_mfma_f32_16x16x32_bf16 v[18:21], v[150:153], v[244:247], v[18:21]
	v_mfma_f32_16x16x32_bf16 v[62:65], v[154:157], v[190:193], v[62:65]
	v_mfma_f32_16x16x32_bf16 v[54:57], v[162:165], v[190:193], v[54:57]
	v_mfma_f32_16x16x32_bf16 v[46:49], v[154:157], v[198:201], v[46:49]
	v_mfma_f32_16x16x32_bf16 v[38:41], v[162:165], v[198:201], v[38:41]
	v_mfma_f32_16x16x32_bf16 v[30:33], v[154:157], v[216:219], v[30:33]
	v_mfma_f32_16x16x32_bf16 v[22:25], v[162:165], v[216:219], v[22:25]
	v_mfma_f32_16x16x32_bf16 v[14:17], v[154:157], v[240:243], v[14:17]
	v_mfma_f32_16x16x32_bf16 v[10:13], v[162:165], v[240:243], v[10:13]
	v_mfma_f32_16x16x32_bf16 v[62:65], v[158:161], v[194:197], v[62:65]
	v_mfma_f32_16x16x32_bf16 v[54:57], v[166:169], v[194:197], v[54:57]
	v_mfma_f32_16x16x32_bf16 v[46:49], v[158:161], v[202:205], v[46:49]
	v_mfma_f32_16x16x32_bf16 v[38:41], v[166:169], v[202:205], v[38:41]
	v_mfma_f32_16x16x32_bf16 v[30:33], v[158:161], v[220:223], v[30:33]
	v_mfma_f32_16x16x32_bf16 v[22:25], v[166:169], v[220:223], v[22:25]
	v_mfma_f32_16x16x32_bf16 v[14:17], v[158:161], v[244:247], v[14:17]
	v_mfma_f32_16x16x32_bf16 v[10:13], v[166:169], v[244:247], v[10:13]
	s_setprio 0
	s_barrier
; #define PG8_STAGE(bufoff, gbase, voff) do { _Pragma("unroll") for (int _i = 0; _i < 2; ++_i) \
;         __builtin_amdgcn_global_load_lds((const unsigned*)((const char*)(gbase) + (voff)[_i]), (PG8_LAS unsigned*)(lds + (bufoff) + ldsw + _i * 8192), 16, 0, 0); } while (0)
; #define PG8_LDA(dst, b, h) do { _Pragma("unroll") for (int m = 0; m < 4; ++m) _Pragma("unroll") for (int k = 0; k < 2; ++k) dst[m][k] = *(const PG8_LAS bf16x8*)(lds + PG8_SA(b, h) + aoff + m * 2048 + k * 1024); } while (0)
; #define PG8_LDB(dst, b, h) do { _Pragma("unroll") for (int n = 0; n < 2; ++n) _Pragma("unroll") for (int k = 0; k < 2; ++k) dst[n][k] = *(const PG8_LAS bf16x8*)(lds + PG8_SB(b, h) + boff + n * 2048 + k * 1024); } while (0)
; #define PG8_MMA(ai, bj, At, Bt) do { __builtin_amdgcn_s_setprio(1); _Pragma("unroll") for (int m = 0; m < 4; ++m) _Pragma("unroll") for (int n = 0; n < 2; ++n) _Pragma("unroll") for (int k = 0; k < 2; ++k) \
;         acc[ai][bj][m][n] = __builtin_amdgcn_mfma_f32_16x16x32_bf16(Bt[n][k], At[m][k], acc[ai][bj][m][n], 0, 0, 0); __builtin_amdgcn_s_setprio(0); } while (0)
; #define PG8_WAIT_V(n) asm volatile("s_waitcnt vmcnt(" #n ")" ::: "memory")
; #define PG8_WAIT_L(n) asm volatile("s_waitcnt lgkmcnt(" #n ")" ::: "memory")
; #define PG8_BAR __builtin_amdgcn_s_barrier()
; #define PG8_SCHED __builtin_amdgcn_sched_barrier(0)
; template <class Epi, class Sched, bool ALIGN_EPI = false, bool SP2 = false>
; __device__ __forceinline__ void gemm_phase(PG8_LAS unsigned char* lds, const Gemm g, const Sched& S, const Epi& E, const int wave_id) {
;     ...
;             PG8_LDB(B0, 1, 0); PG8_LDB(B1, 1, 1); PG8_SCHED; PG8_LDA(At, 1, 0); PG8_STAGE(PG8_SA(0, 1), a2 + hstepA, voffA);
;             PG8_WAIT_V(8); PG8_WAIT_L(0); PG8_BAR; PG8_MMA(0, 0, At, B0); PG8_MMA(0, 1, At, B1); PG8_BAR; PG8_SCHED;
	s_add_i32 s35, 0, 0x18000
	v_add_u32_e32 v0, s35, v210
	s_add_i32 s36, 0, 0x1c000
	ds_read_b128 v[138:141], v0
	ds_read_b128 v[142:145], v0 offset:1024
	ds_read_b128 v[146:149], v0 offset:2048
	ds_read_b128 v[150:153], v0 offset:3072
	v_add_u32_e32 v0, s36, v210
	ds_read_b128 v[154:157], v0
	ds_read_b128 v[158:161], v0 offset:1024
	ds_read_b128 v[162:165], v0 offset:2048
	ds_read_b128 v[166:169], v0 offset:3072
	s_add_u32 s0, s28, 0x40000
	s_addc_u32 s1, s29, 0
	s_mov_b32 m0, s31
	v_lshl_add_u64 v[248:249], s[0:1], 0, v[178:179]
	ds_read_b128 v[190:193], v215 offset:32768
	ds_read_b128 v[194:197], v215 offset:33792
	ds_read_b128 v[198:201], v215 offset:34816
	ds_read_b128 v[202:205], v215 offset:35840
	ds_read_b128 v[216:219], v215 offset:36864
	ds_read_b128 v[220:223], v215 offset:37888
	ds_read_b128 v[240:243], v215 offset:38912
	ds_read_b128 v[244:247], v215 offset:39936
	global_load_lds_dwordx4 v[248:249], off
	v_lshl_add_u64 v[248:249], s[0:1], 0, v[182:183]
	s_mov_b32 m0, s34
	s_nop 0
	global_load_lds_dwordx4 v[248:249], off
	s_waitcnt vmcnt(8)
	s_waitcnt lgkmcnt(0)
	s_barrier
	s_setprio 1
	s_waitcnt lgkmcnt(0)
	v_mfma_f32_16x16x32_bf16 v[134:137], v[138:141], v[190:193], v[134:137]
	v_mfma_f32_16x16x32_bf16 v[130:133], v[146:149], v[190:193], v[130:133]
	v_mfma_f32_16x16x32_bf16 v[122:125], v[138:141], v[198:201], v[122:125]
	v_mfma_f32_16x16x32_bf16 v[114:117], v[146:149], v[198:201], v[114:117]
	v_mfma_f32_16x16x32_bf16 v[106:109], v[138:141], v[216:219], v[106:109]
	v_mfma_f32_16x16x32_bf16 v[98:101], v[146:149], v[216:219], v[98:101]
	v_mfma_f32_16x16x32_bf16 v[90:93], v[138:141], v[240:243], v[90:93]
	v_mfma_f32_16x16x32_bf16 v[82:85], v[146:149], v[240:243], v[82:85]
	v_mfma_f32_16x16x32_bf16 v[134:137], v[142:145], v[194:197], v[134:137]
	v_mfma_f32_16x16x32_bf16 v[130:133], v[150:153], v[194:197], v[130:133]
	v_mfma_f32_16x16x32_bf16 v[122:125], v[142:145], v[202:205], v[122:125]
	v_mfma_f32_16x16x32_bf16 v[114:117], v[150:153], v[202:205], v[114:117]
	v_mfma_f32_16x16x32_bf16 v[106:109], v[142:145], v[220:223], v[106:109]
	v_mfma_f32_16x16x32_bf16 v[98:101], v[150:153], v[220:223], v[98:101]
	v_mfma_f32_16x16x32_bf16 v[90:93], v[142:145], v[244:247], v[90:93]
	v_mfma_f32_16x16x32_bf16 v[82:85], v[150:153], v[244:247], v[82:85]
	v_mfma_f32_16x16x32_bf16 v[126:129], v[154:157], v[190:193], v[126:129]
	v_mfma_f32_16x16x32_bf16 v[118:121], v[162:165], v[190:193], v[118:121]
	v_mfma_f32_16x16x32_bf16 v[110:113], v[154:157], v[198:201], v[110:113]
	v_mfma_f32_16x16x32_bf16 v[102:105], v[162:165], v[198:201], v[102:105]
	v_mfma_f32_16x16x32_bf16 v[94:97], v[154:157], v[216:219], v[94:97]
	v_mfma_f32_16x16x32_bf16 v[86:89], v[162:165], v[216:219], v[86:89]
	v_mfma_f32_16x16x32_bf16 v[78:81], v[154:157], v[240:243], v[78:81]
	v_mfma_f32_16x16x32_bf16 v[74:77], v[162:165], v[240:243], v[74:77]
	v_mfma_f32_16x16x32_bf16 v[126:129], v[158:161], v[194:197], v[126:129]
	v_mfma_f32_16x16x32_bf16 v[118:121], v[166:169], v[194:197], v[118:121]
	v_mfma_f32_16x16x32_bf16 v[110:113], v[158:161], v[202:205], v[110:113]
	v_mfma_f32_16x16x32_bf16 v[102:105], v[166:169], v[202:205], v[102:105]
	v_mfma_f32_16x16x32_bf16 v[94:97], v[158:161], v[220:223], v[94:97]
	v_mfma_f32_16x16x32_bf16 v[86:89], v[166:169], v[220:223], v[86:89]
	v_mfma_f32_16x16x32_bf16 v[78:81], v[158:161], v[244:247], v[78:81]
	v_mfma_f32_16x16x32_bf16 v[74:77], v[166:169], v[244:247], v[74:77]
	s_setprio 0
	s_barrier
; #define PG8_STAGE(bufoff, gbase, voff) do { _Pragma("unroll") for (int _i = 0; _i < 2; ++_i) \
;         __builtin_amdgcn_global_load_lds((const unsigned*)((const char*)(gbase) + (voff)[_i]), (PG8_LAS unsigned*)(lds + (bufoff) + ldsw + _i * 8192), 16, 0, 0); } while (0)
; #define PG8_LDA(dst, b, h) do { _Pragma("unroll") for (int m = 0; m < 4; ++m) _Pragma("unroll") for (int k = 0; k < 2; ++k) dst[m][k] = *(const PG8_LAS bf16x8*)(lds + PG8_SA(b, h) + aoff + m * 2048 + k * 1024); } while (0)
; #define PG8_MMA(ai, bj, At, Bt) do { __builtin_amdgcn_s_setprio(1); _Pragma("unroll") for (int m = 0; m < 4; ++m) _Pragma("unroll") for (int n = 0; n < 2; ++n) _Pragma("unroll") for (int k = 0; k < 2; ++k) \
;         acc[ai][bj][m][n] = __builtin_amdgcn_mfma_f32_16x16x32_bf16(Bt[n][k], At[m][k], acc[ai][bj][m][n], 0, 0, 0); __builtin_amdgcn_s_setprio(0); } while (0)
; #define PG8_WAIT_V(n) asm volatile("s_waitcnt vmcnt(" #n ")" ::: "memory")
; #define PG8_WAIT_L(n) asm volatile("s_waitcnt lgkmcnt(" #n ")" ::: "memory")
; #define PG8_BAR __builtin_amdgcn_s_barrier()
; #define PG8_SCHED __builtin_amdgcn_sched_barrier(0)
; template <class Epi, class Sched, bool ALIGN_EPI = false, bool SP2 = false>
; __device__ __forceinline__ void gemm_phase(PG8_LAS unsigned char* lds, const Gemm g, const Sched& S, const Epi& E, const int wave_id) {
;     ...
;         for (int t = 0; t < nt; t += 2) {
;             const bool last = (t == nt - 2);
;     ...
;             PG8_LDA(At, 1, 1); PG8_STAGE(PG8_SB(1, 0), b3, voffB); PG8_STAGE(PG8_SB(1, 1), b3 + hstepB, voffB); PG8_STAGE(PG8_SA(1, 0), a3, voffA);
;             PG8_WAIT_V(8); PG8_WAIT_L(0); PG8_BAR; PG8_MMA(1, 0, At, B0); PG8_MMA(1, 1, At, B1); PG8_BAR; PG8_SCHED;
	s_add_i32 s0, s35, s23
	v_lshl_add_u64 v[206:207], v[206:207], 0, s[62:63]
	s_mov_b32 m0, s0
	ds_read_b128 v[190:193], v215 offset:49152
	ds_read_b128 v[194:197], v215 offset:50176
	ds_read_b128 v[198:201], v215 offset:51200
	ds_read_b128 v[202:205], v215 offset:52224
	ds_read_b128 v[216:219], v215 offset:53248
	ds_read_b128 v[220:223], v215 offset:54272
	ds_read_b128 v[240:243], v215 offset:55296
	ds_read_b128 v[244:247], v215 offset:56320
	global_load_lds_dwordx4 v[206:207], off
	s_add_i32 m0, s0, 0x2000
	s_add_u32 s0, s26, 0x40080
	v_lshl_add_u64 v[206:207], v[224:225], 0, s[62:63]
	s_addc_u32 s1, s27, 0
	s_add_i32 s26, s36, s23
	global_load_lds_dwordx4 v[206:207], off
	v_lshl_add_u64 v[206:207], s[0:1], 0, v[180:181]
	s_mov_b32 m0, s26
	s_nop 0
	global_load_lds_dwordx4 v[206:207], off
	v_lshl_add_u64 v[206:207], s[0:1], 0, v[184:185]
	s_add_i32 m0, s26, 0x2000
	s_nop 0
	global_load_lds_dwordx4 v[206:207], off
	v_lshl_add_u64 v[206:207], v[234:235], 0, s[62:63]
	s_mov_b32 m0, s44
	s_nop 0
	global_load_lds_dwordx4 v[206:207], off
	v_lshl_add_u64 v[206:207], v[236:237], 0, s[62:63]
	s_mov_b32 m0, s45
	s_nop 0
	global_load_lds_dwordx4 v[206:207], off
	s_waitcnt vmcnt(8)
	s_waitcnt lgkmcnt(0)
	s_barrier
	s_setprio 1
	s_waitcnt lgkmcnt(0)
	v_mfma_f32_16x16x32_bf16 v[70:73], v[138:141], v[190:193], v[70:73]
	v_mfma_f32_16x16x32_bf16 v[66:69], v[146:149], v[190:193], v[66:69]
	v_mfma_f32_16x16x32_bf16 v[58:61], v[138:141], v[198:201], v[58:61]
	v_mfma_f32_16x16x32_bf16 v[50:53], v[146:149], v[198:201], v[50:53]
	v_mfma_f32_16x16x32_bf16 v[42:45], v[138:141], v[216:219], v[42:45]
	v_mfma_f32_16x16x32_bf16 v[34:37], v[146:149], v[216:219], v[34:37]
	v_mfma_f32_16x16x32_bf16 v[26:29], v[138:141], v[240:243], v[26:29]
	v_mfma_f32_16x16x32_bf16 v[18:21], v[146:149], v[240:243], v[18:21]
	v_mfma_f32_16x16x32_bf16 v[70:73], v[142:145], v[194:197], v[70:73]
	v_mfma_f32_16x16x32_bf16 v[66:69], v[150:153], v[194:197], v[66:69]
	v_mfma_f32_16x16x32_bf16 v[58:61], v[142:145], v[202:205], v[58:61]
	v_mfma_f32_16x16x32_bf16 v[50:53], v[150:153], v[202:205], v[50:53]
	v_mfma_f32_16x16x32_bf16 v[42:45], v[142:145], v[220:223], v[42:45]
	v_mfma_f32_16x16x32_bf16 v[34:37], v[150:153], v[220:223], v[34:37]
	v_mfma_f32_16x16x32_bf16 v[26:29], v[142:145], v[244:247], v[26:29]
	v_mfma_f32_16x16x32_bf16 v[18:21], v[150:153], v[244:247], v[18:21]
	v_mfma_f32_16x16x32_bf16 v[62:65], v[154:157], v[190:193], v[62:65]
	v_mfma_f32_16x16x32_bf16 v[54:57], v[162:165], v[190:193], v[54:57]
	v_mfma_f32_16x16x32_bf16 v[46:49], v[154:157], v[198:201], v[46:49]
	v_mfma_f32_16x16x32_bf16 v[38:41], v[162:165], v[198:201], v[38:41]
	v_mfma_f32_16x16x32_bf16 v[30:33], v[154:157], v[216:219], v[30:33]
	v_mfma_f32_16x16x32_bf16 v[22:25], v[162:165], v[216:219], v[22:25]
	v_mfma_f32_16x16x32_bf16 v[14:17], v[154:157], v[240:243], v[14:17]
	v_mfma_f32_16x16x32_bf16 v[10:13], v[162:165], v[240:243], v[10:13]
	v_mfma_f32_16x16x32_bf16 v[62:65], v[158:161], v[194:197], v[62:65]
	v_mfma_f32_16x16x32_bf16 v[54:57], v[166:169], v[194:197], v[54:57]
	v_mfma_f32_16x16x32_bf16 v[46:49], v[158:161], v[202:205], v[46:49]
	v_mfma_f32_16x16x32_bf16 v[38:41], v[166:169], v[202:205], v[38:41]
	v_mfma_f32_16x16x32_bf16 v[30:33], v[158:161], v[220:223], v[30:33]
	v_mfma_f32_16x16x32_bf16 v[22:25], v[166:169], v[220:223], v[22:25]
	v_mfma_f32_16x16x32_bf16 v[14:17], v[158:161], v[244:247], v[14:17]
	v_mfma_f32_16x16x32_bf16 v[10:13], v[166:169], v[244:247], v[10:13]
	s_setprio 0
	s_barrier
	s_add_i32 s5, s5, 2
	s_add_u32 s8, s8, 0x100
	s_addc_u32 s9, s9, 0
	s_add_u32 vcc_hi, vcc_hi, 0x100
	s_addc_u32 s4, s4, 0
	s_cmp_gt_u32 s5, 13
	s_cbranch_scc0 .LBB0_576

; #define PG8_STAGE(bufoff, gbase, voff) do { _Pragma("unroll") for (int _i = 0; _i < 2; ++_i) \
;         __builtin_amdgcn_global_load_lds((const unsigned*)((const char*)(gbase) + (voff)[_i]), (PG8_LAS unsigned*)(lds + (bufoff) + ldsw + _i * 8192), 16, 0, 0); } while (0)
; #define PG8_LDA(dst, b, h) do { _Pragma("unroll") for (int m = 0; m < 4; ++m) _Pragma("unroll") for (int k = 0; k < 2; ++k) dst[m][k] = *(const PG8_LAS bf16x8*)(lds + PG8_SA(b, h) + aoff + m * 2048 + k * 1024); } while (0)
; #define PG8_MMA(ai, bj, At, Bt) do { __builtin_amdgcn_s_setprio(1); _Pragma("unroll") for (int m = 0; m < 4; ++m) _Pragma("unroll") for (int n = 0; n < 2; ++n) _Pragma("unroll") for (int k = 0; k < 2; ++k) \
;         acc[ai][bj][m][n] = __builtin_amdgcn_mfma_f32_16x16x32_bf16(Bt[n][k], At[m][k], acc[ai][bj][m][n], 0, 0, 0); __builtin_amdgcn_s_setprio(0); } while (0)
; #define PG8_WAIT_V(n) asm volatile("s_waitcnt vmcnt(" #n ")" ::: "memory")
; #define PG8_WAIT_L(n) asm volatile("s_waitcnt lgkmcnt(" #n ")" ::: "memory")
; #define PG8_BAR __builtin_amdgcn_s_barrier()
; #define PG8_SCHED __builtin_amdgcn_sched_barrier(0)
; template <class Epi, class Sched, bool ALIGN_EPI = false, bool SP2 = false>
; __device__ __forceinline__ void gemm_phase(PG8_LAS unsigned char* lds, const Gemm g, const Sched& S, const Epi& E, const int wave_id) {
;     ...
;             PG8_WAIT_V(8); PG8_WAIT_L(0); PG8_BAR; PG8_MMA(0, 0, At, B0); PG8_MMA(0, 1, At, B1); PG8_BAR; PG8_SCHED;
;             PG8_LDA(At, 0, 1); PG8_STAGE(PG8_SB(0, 0), b2, voffB); PG8_STAGE(PG8_SB(0, 1), b2 + hstepB, voffB); PG8_STAGE(PG8_SA(0, 0), a2, voffA);
;             PG8_WAIT_V(8); PG8_WAIT_L(0); PG8_BAR; PG8_MMA(1, 0, At, B0); PG8_MMA(1, 1, At, B1); PG8_BAR; PG8_SCHED;
.Lrw_5:
	s_waitcnt lgkmcnt(0)
	s_barrier
	s_setprio 1
	s_waitcnt lgkmcnt(0)
	v_mfma_f32_16x16x32_bf16 v[166:169], v[114:117], v[190:193], v[166:169]
	v_mfma_f32_16x16x32_bf16 v[162:165], v[122:125], v[190:193], v[162:165]
	v_mfma_f32_16x16x32_bf16 v[134:137], v[114:117], v[202:205], v[134:137]
	v_mfma_f32_16x16x32_bf16 v[126:129], v[122:125], v[202:205], v[126:129]
	v_mfma_f32_16x16x32_bf16 v[102:105], v[114:117], v[210:213], v[102:105]
	v_mfma_f32_16x16x32_bf16 v[98:101], v[122:125], v[210:213], v[98:101]
	v_mfma_f32_16x16x32_bf16 v[86:89], v[114:117], v[218:221], v[86:89]
	v_mfma_f32_16x16x32_bf16 v[82:85], v[122:125], v[218:221], v[82:85]
	v_mfma_f32_16x16x32_bf16 v[166:169], v[118:121], v[194:197], v[166:169]
	v_mfma_f32_16x16x32_bf16 v[162:165], v[130:133], v[194:197], v[162:165]
	v_mfma_f32_16x16x32_bf16 v[134:137], v[118:121], v[206:209], v[134:137]
	v_mfma_f32_16x16x32_bf16 v[126:129], v[130:133], v[206:209], v[126:129]
	v_mfma_f32_16x16x32_bf16 v[102:105], v[118:121], v[214:217], v[102:105]
	v_mfma_f32_16x16x32_bf16 v[98:101], v[130:133], v[214:217], v[98:101]
	v_mfma_f32_16x16x32_bf16 v[86:89], v[118:121], v[222:225], v[86:89]
	v_mfma_f32_16x16x32_bf16 v[82:85], v[130:133], v[222:225], v[82:85]
	v_mfma_f32_16x16x32_bf16 v[158:161], v[138:141], v[190:193], v[158:161]
	v_mfma_f32_16x16x32_bf16 v[146:149], v[150:153], v[190:193], v[146:149]
	v_mfma_f32_16x16x32_bf16 v[110:113], v[138:141], v[202:205], v[110:113]
	v_mfma_f32_16x16x32_bf16 v[106:109], v[150:153], v[202:205], v[106:109]
	v_mfma_f32_16x16x32_bf16 v[94:97], v[138:141], v[210:213], v[94:97]
	v_mfma_f32_16x16x32_bf16 v[90:93], v[150:153], v[210:213], v[90:93]
	v_mfma_f32_16x16x32_bf16 v[78:81], v[138:141], v[218:221], v[78:81]
	v_mfma_f32_16x16x32_bf16 v[74:77], v[150:153], v[218:221], v[74:77]
	v_mfma_f32_16x16x32_bf16 v[158:161], v[142:145], v[194:197], v[158:161]
	v_mfma_f32_16x16x32_bf16 v[146:149], v[154:157], v[194:197], v[146:149]
	v_mfma_f32_16x16x32_bf16 v[110:113], v[142:145], v[206:209], v[110:113]
	v_mfma_f32_16x16x32_bf16 v[106:109], v[154:157], v[206:209], v[106:109]
	v_mfma_f32_16x16x32_bf16 v[94:97], v[142:145], v[214:217], v[94:97]
	v_mfma_f32_16x16x32_bf16 v[90:93], v[154:157], v[214:217], v[90:93]
	v_mfma_f32_16x16x32_bf16 v[78:81], v[142:145], v[222:225], v[78:81]
	v_mfma_f32_16x16x32_bf16 v[74:77], v[154:157], v[222:225], v[74:77]
	s_setprio 0
	s_barrier
	s_add_i32 s1, s38, s23
	v_lshl_add_u64 v[198:199], s[26:27], 0, v[180:181]
	s_mov_b32 m0, s1
	ds_read_b128 v[190:193], v245 offset:16384
	ds_read_b128 v[194:197], v245 offset:17408
	ds_read_b128 v[202:205], v245 offset:18432
	ds_read_b128 v[206:209], v245 offset:19456
	ds_read_b128 v[210:213], v245 offset:20480
	ds_read_b128 v[214:217], v245 offset:21504
	ds_read_b128 v[218:221], v245 offset:22528
	ds_read_b128 v[222:225], v245 offset:23552
	global_load_lds_dwordx4 v[198:199], off
	s_add_i32 m0, s1, 0x2000
	s_add_u32 s38, s26, 0x40000
	v_lshl_add_u64 v[234:235], s[26:27], 0, v[184:185]
	s_addc_u32 s39, s27, 0
	s_add_i32 s0, s0, s23
	global_load_lds_dwordx4 v[234:235], off
	v_lshl_add_u64 v[236:237], s[38:39], 0, v[180:181]
	s_mov_b32 m0, s0
	v_lshl_add_u64 v[246:247], s[28:29], 0, v[182:183]
	global_load_lds_dwordx4 v[236:237], off
	v_lshl_add_u64 v[236:237], s[38:39], 0, v[184:185]
	s_add_i32 m0, s0, 0x2000
	s_nop 0
	global_load_lds_dwordx4 v[236:237], off
	v_lshl_add_u64 v[236:237], s[28:29], 0, v[178:179]
	s_mov_b32 m0, s30
	s_nop 0
	global_load_lds_dwordx4 v[236:237], off
	s_mov_b32 m0, s31
	s_nop 0
	global_load_lds_dwordx4 v[246:247], off
	s_waitcnt vmcnt(24)
	s_cmp_eq_u32 s98, 1
	s_cbranch_scc1 .Lrw_6
	s_waitcnt vmcnt(8)
.Lrw_6:
	s_mov_b32 s98, 0
	s_waitcnt lgkmcnt(0)
	s_barrier
	s_setprio 1
	s_waitcnt lgkmcnt(0)
	v_mfma_f32_16x16x32_bf16 v[70:73], v[114:117], v[190:193], v[70:73]
	v_mfma_f32_16x16x32_bf16 v[66:69], v[122:125], v[190:193], v[66:69]
	v_mfma_f32_16x16x32_bf16 v[54:57], v[114:117], v[202:205], v[54:57]
	v_mfma_f32_16x16x32_bf16 v[50:53], v[122:125], v[202:205], v[50:53]
	v_mfma_f32_16x16x32_bf16 v[38:41], v[114:117], v[210:213], v[38:41]
	v_mfma_f32_16x16x32_bf16 v[34:37], v[122:125], v[210:213], v[34:37]
	v_mfma_f32_16x16x32_bf16 v[22:25], v[114:117], v[218:221], v[22:25]
	v_mfma_f32_16x16x32_bf16 v[18:21], v[122:125], v[218:221], v[18:21]
	v_mfma_f32_16x16x32_bf16 v[70:73], v[118:121], v[194:197], v[70:73]
	v_mfma_f32_16x16x32_bf16 v[66:69], v[130:133], v[194:197], v[66:69]
	v_mfma_f32_16x16x32_bf16 v[54:57], v[118:121], v[206:209], v[54:57]
	v_mfma_f32_16x16x32_bf16 v[50:53], v[130:133], v[206:209], v[50:53]
	v_mfma_f32_16x16x32_bf16 v[38:41], v[118:121], v[214:217], v[38:41]
	v_mfma_f32_16x16x32_bf16 v[34:37], v[130:133], v[214:217], v[34:37]
	v_mfma_f32_16x16x32_bf16 v[22:25], v[118:121], v[222:225], v[22:25]
	v_mfma_f32_16x16x32_bf16 v[18:21], v[130:133], v[222:225], v[18:21]
	v_mfma_f32_16x16x32_bf16 v[62:65], v[138:141], v[190:193], v[62:65]
	v_mfma_f32_16x16x32_bf16 v[58:61], v[150:153], v[190:193], v[58:61]
	v_mfma_f32_16x16x32_bf16 v[46:49], v[138:141], v[202:205], v[46:49]
	v_mfma_f32_16x16x32_bf16 v[42:45], v[150:153], v[202:205], v[42:45]
	v_mfma_f32_16x16x32_bf16 v[30:33], v[138:141], v[210:213], v[30:33]
	v_mfma_f32_16x16x32_bf16 v[26:29], v[150:153], v[210:213], v[26:29]
	v_mfma_f32_16x16x32_bf16 v[14:17], v[138:141], v[218:221], v[14:17]
	v_mfma_f32_16x16x32_bf16 v[10:13], v[150:153], v[218:221], v[10:13]
	v_mfma_f32_16x16x32_bf16 v[62:65], v[142:145], v[194:197], v[62:65]
	v_mfma_f32_16x16x32_bf16 v[58:61], v[154:157], v[194:197], v[58:61]
	v_mfma_f32_16x16x32_bf16 v[46:49], v[142:145], v[206:209], v[46:49]
	v_mfma_f32_16x16x32_bf16 v[42:45], v[154:157], v[206:209], v[42:45]
	v_mfma_f32_16x16x32_bf16 v[30:33], v[142:145], v[214:217], v[30:33]
	v_mfma_f32_16x16x32_bf16 v[26:29], v[154:157], v[214:217], v[26:29]
	v_mfma_f32_16x16x32_bf16 v[14:17], v[142:145], v[222:225], v[14:17]
	v_mfma_f32_16x16x32_bf16 v[10:13], v[154:157], v[222:225], v[10:13]
	s_setprio 0
	s_barrier
; #define PG8_STAGE(bufoff, gbase, voff) do { _Pragma("unroll") for (int _i = 0; _i < 2; ++_i) \
;         __builtin_amdgcn_global_load_lds((const unsigned*)((const char*)(gbase) + (voff)[_i]), (PG8_LAS unsigned*)(lds + (bufoff) + ldsw + _i * 8192), 16, 0, 0); } while (0)
; #define PG8_LDA(dst, b, h) do { _Pragma("unroll") for (int m = 0; m < 4; ++m) _Pragma("unroll") for (int k = 0; k < 2; ++k) dst[m][k] = *(const PG8_LAS bf16x8*)(lds + PG8_SA(b, h) + aoff + m * 2048 + k * 1024); } while (0)
; #define PG8_LDB(dst, b, h) do { _Pragma("unroll") for (int n = 0; n < 2; ++n) _Pragma("unroll") for (int k = 0; k < 2; ++k) dst[n][k] = *(const PG8_LAS bf16x8*)(lds + PG8_SB(b, h) + boff + n * 2048 + k * 1024); } while (0)
; #define PG8_MMA(ai, bj, At, Bt) do { __builtin_amdgcn_s_setprio(1); _Pragma("unroll") for (int m = 0; m < 4; ++m) _Pragma("unroll") for (int n = 0; n < 2; ++n) _Pragma("unroll") for (int k = 0; k < 2; ++k) \
;         acc[ai][bj][m][n] = __builtin_amdgcn_mfma_f32_16x16x32_bf16(Bt[n][k], At[m][k], acc[ai][bj][m][n], 0, 0, 0); __builtin_amdgcn_s_setprio(0); } while (0)
; #define PG8_WAIT_V(n) asm volatile("s_waitcnt vmcnt(" #n ")" ::: "memory")
; #define PG8_WAIT_L(n) asm volatile("s_waitcnt lgkmcnt(" #n ")" ::: "memory")
; #define PG8_BAR __builtin_amdgcn_s_barrier()
; #define PG8_SCHED __builtin_amdgcn_sched_barrier(0)
; template <class Epi, class Sched, bool ALIGN_EPI = false, bool SP2 = false>
; __device__ __forceinline__ void gemm_phase(PG8_LAS unsigned char* lds, const Gemm g, const Sched& S, const Epi& E, const int wave_id) {
;     ...
;             PG8_LDB(B0, 1, 0); PG8_LDB(B1, 1, 1); PG8_SCHED; PG8_LDA(At, 1, 0); PG8_STAGE(PG8_SA(0, 1), a2 + hstepA, voffA);
;             PG8_WAIT_V(8); PG8_WAIT_L(0); PG8_BAR; PG8_MMA(0, 0, At, B0); PG8_MMA(0, 1, At, B1); PG8_BAR; PG8_SCHED;
	s_add_i32 s0, 0, 0x18000
	v_add_u32_e32 v0, s0, v240
	s_add_i32 s1, 0, 0x1c000
	ds_read_b128 v[114:117], v0
	ds_read_b128 v[118:121], v0 offset:1024
	ds_read_b128 v[122:125], v0 offset:2048
	ds_read_b128 v[130:133], v0 offset:3072
	v_add_u32_e32 v0, s1, v240
	ds_read_b128 v[138:141], v0
	ds_read_b128 v[142:145], v0 offset:1024
	ds_read_b128 v[150:153], v0 offset:2048
	ds_read_b128 v[154:157], v0 offset:3072
	s_add_u32 s28, s28, 0x40000
	s_addc_u32 s29, s29, 0
	s_mov_b32 m0, s34
	v_lshl_add_u64 v[248:249], s[28:29], 0, v[178:179]
	ds_read_b128 v[190:193], v245 offset:32768
	ds_read_b128 v[194:197], v245 offset:33792
	ds_read_b128 v[202:205], v245 offset:34816
	ds_read_b128 v[206:209], v245 offset:35840
	ds_read_b128 v[210:213], v245 offset:36864
	ds_read_b128 v[214:217], v245 offset:37888
	ds_read_b128 v[218:221], v245 offset:38912
	ds_read_b128 v[222:225], v245 offset:39936
	global_load_lds_dwordx4 v[248:249], off
	v_lshl_add_u64 v[248:249], s[28:29], 0, v[182:183]
	s_mov_b32 m0, s35
	s_nop 0
	global_load_lds_dwordx4 v[248:249], off
	s_waitcnt vmcnt(8)
	s_waitcnt lgkmcnt(0)
	s_barrier
	s_setprio 1
	s_waitcnt lgkmcnt(0)
	v_mfma_f32_16x16x32_bf16 v[166:169], v[114:117], v[190:193], v[166:169]
	v_mfma_f32_16x16x32_bf16 v[162:165], v[122:125], v[190:193], v[162:165]
	v_mfma_f32_16x16x32_bf16 v[134:137], v[114:117], v[202:205], v[134:137]
	v_mfma_f32_16x16x32_bf16 v[126:129], v[122:125], v[202:205], v[126:129]
	v_mfma_f32_16x16x32_bf16 v[102:105], v[114:117], v[210:213], v[102:105]
	v_mfma_f32_16x16x32_bf16 v[98:101], v[122:125], v[210:213], v[98:101]
	v_mfma_f32_16x16x32_bf16 v[86:89], v[114:117], v[218:221], v[86:89]
	v_mfma_f32_16x16x32_bf16 v[82:85], v[122:125], v[218:221], v[82:85]
	v_mfma_f32_16x16x32_bf16 v[166:169], v[118:121], v[194:197], v[166:169]
	v_mfma_f32_16x16x32_bf16 v[162:165], v[130:133], v[194:197], v[162:165]
	v_mfma_f32_16x16x32_bf16 v[134:137], v[118:121], v[206:209], v[134:137]
	v_mfma_f32_16x16x32_bf16 v[126:129], v[130:133], v[206:209], v[126:129]
	v_mfma_f32_16x16x32_bf16 v[102:105], v[118:121], v[214:217], v[102:105]
	v_mfma_f32_16x16x32_bf16 v[98:101], v[130:133], v[214:217], v[98:101]
	v_mfma_f32_16x16x32_bf16 v[86:89], v[118:121], v[222:225], v[86:89]
	v_mfma_f32_16x16x32_bf16 v[82:85], v[130:133], v[222:225], v[82:85]
	v_mfma_f32_16x16x32_bf16 v[158:161], v[138:141], v[190:193], v[158:161]
	v_mfma_f32_16x16x32_bf16 v[146:149], v[150:153], v[190:193], v[146:149]
	v_mfma_f32_16x16x32_bf16 v[110:113], v[138:141], v[202:205], v[110:113]
	v_mfma_f32_16x16x32_bf16 v[106:109], v[150:153], v[202:205], v[106:109]
	v_mfma_f32_16x16x32_bf16 v[94:97], v[138:141], v[210:213], v[94:97]
	v_mfma_f32_16x16x32_bf16 v[90:93], v[150:153], v[210:213], v[90:93]
	v_mfma_f32_16x16x32_bf16 v[78:81], v[138:141], v[218:221], v[78:81]
	v_mfma_f32_16x16x32_bf16 v[74:77], v[150:153], v[218:221], v[74:77]
	v_mfma_f32_16x16x32_bf16 v[158:161], v[142:145], v[194:197], v[158:161]
	v_mfma_f32_16x16x32_bf16 v[146:149], v[154:157], v[194:197], v[146:149]
	v_mfma_f32_16x16x32_bf16 v[110:113], v[142:145], v[206:209], v[110:113]
	v_mfma_f32_16x16x32_bf16 v[106:109], v[154:157], v[206:209], v[106:109]
	v_mfma_f32_16x16x32_bf16 v[94:97], v[142:145], v[214:217], v[94:97]
	v_mfma_f32_16x16x32_bf16 v[90:93], v[154:157], v[214:217], v[90:93]
	v_mfma_f32_16x16x32_bf16 v[78:81], v[142:145], v[222:225], v[78:81]
	v_mfma_f32_16x16x32_bf16 v[74:77], v[154:157], v[222:225], v[74:77]
	s_setprio 0
	s_barrier
; #define PG8_STAGE(bufoff, gbase, voff) do { _Pragma("unroll") for (int _i = 0; _i < 2; ++_i) \
;         __builtin_amdgcn_global_load_lds((const unsigned*)((const char*)(gbase) + (voff)[_i]), (PG8_LAS unsigned*)(lds + (bufoff) + ldsw + _i * 8192), 16, 0, 0); } while (0)
; #define PG8_LDA(dst, b, h) do { _Pragma("unroll") for (int m = 0; m < 4; ++m) _Pragma("unroll") for (int k = 0; k < 2; ++k) dst[m][k] = *(const PG8_LAS bf16x8*)(lds + PG8_SA(b, h) + aoff + m * 2048 + k * 1024); } while (0)
; #define PG8_MMA(ai, bj, At, Bt) do { __builtin_amdgcn_s_setprio(1); _Pragma("unroll") for (int m = 0; m < 4; ++m) _Pragma("unroll") for (int n = 0; n < 2; ++n) _Pragma("unroll") for (int k = 0; k < 2; ++k) \
;         acc[ai][bj][m][n] = __builtin_amdgcn_mfma_f32_16x16x32_bf16(Bt[n][k], At[m][k], acc[ai][bj][m][n], 0, 0, 0); __builtin_amdgcn_s_setprio(0); } while (0)
; #define PG8_WAIT_V(n) asm volatile("s_waitcnt vmcnt(" #n ")" ::: "memory")
; #define PG8_WAIT_L(n) asm volatile("s_waitcnt lgkmcnt(" #n ")" ::: "memory")
; #define PG8_BAR __builtin_amdgcn_s_barrier()
; #define PG8_SCHED __builtin_amdgcn_sched_barrier(0)
; template <class Epi, class Sched, bool ALIGN_EPI = false, bool SP2 = false>
; __device__ __forceinline__ void gemm_phase(PG8_LAS unsigned char* lds, const Gemm g, const Sched& S, const Epi& E, const int wave_id) {
;     ...
;         for (int t = 0; t < nt; t += 2) {
;             const bool last = (t == nt - 2);
;     ...
;             PG8_LDA(At, 1, 1); PG8_STAGE(PG8_SB(1, 0), b3, voffB); PG8_STAGE(PG8_SB(1, 1), b3 + hstepB, voffB); PG8_STAGE(PG8_SA(1, 0), a3, voffA);
;             PG8_WAIT_V(8); PG8_WAIT_L(0); PG8_BAR; PG8_MMA(1, 0, At, B0); PG8_MMA(1, 1, At, B1); PG8_BAR; PG8_SCHED;
	s_add_i32 s0, s0, s23
	v_lshl_add_u64 v[198:199], v[198:199], 0, s[62:63]
	s_mov_b32 m0, s0
	ds_read_b128 v[190:193], v245 offset:49152
	ds_read_b128 v[194:197], v245 offset:50176
	ds_read_b128 v[202:205], v245 offset:51200
	ds_read_b128 v[206:209], v245 offset:52224
	ds_read_b128 v[210:213], v245 offset:53248
	ds_read_b128 v[214:217], v245 offset:54272
	ds_read_b128 v[218:221], v245 offset:55296
	ds_read_b128 v[222:225], v245 offset:56320
	global_load_lds_dwordx4 v[198:199], off
	s_add_i32 m0, s0, 0x2000
	s_add_u32 s26, s26, 0x40080
	v_lshl_add_u64 v[198:199], v[234:235], 0, s[62:63]
	s_addc_u32 s27, s27, 0
	s_add_i32 s0, s1, s23
	global_load_lds_dwordx4 v[198:199], off
	v_lshl_add_u64 v[198:199], s[26:27], 0, v[180:181]
	s_mov_b32 m0, s0
	s_nop 0
	global_load_lds_dwordx4 v[198:199], off
	v_lshl_add_u64 v[198:199], s[26:27], 0, v[184:185]
	s_add_i32 m0, s0, 0x2000
	s_nop 0
	global_load_lds_dwordx4 v[198:199], off
	v_lshl_add_u64 v[198:199], v[236:237], 0, s[62:63]
	s_mov_b32 m0, s45
	s_nop 0
	global_load_lds_dwordx4 v[198:199], off
	v_lshl_add_u64 v[198:199], v[246:247], 0, s[62:63]
	s_mov_b32 m0, s76
	s_nop 0
	global_load_lds_dwordx4 v[198:199], off
	s_waitcnt vmcnt(8)
	s_waitcnt lgkmcnt(0)
	s_barrier
	s_setprio 1
	s_waitcnt lgkmcnt(0)
	v_mfma_f32_16x16x32_bf16 v[70:73], v[114:117], v[190:193], v[70:73]
	v_mfma_f32_16x16x32_bf16 v[66:69], v[122:125], v[190:193], v[66:69]
	v_mfma_f32_16x16x32_bf16 v[54:57], v[114:117], v[202:205], v[54:57]
	v_mfma_f32_16x16x32_bf16 v[50:53], v[122:125], v[202:205], v[50:53]
	v_mfma_f32_16x16x32_bf16 v[38:41], v[114:117], v[210:213], v[38:41]
	v_mfma_f32_16x16x32_bf16 v[34:37], v[122:125], v[210:213], v[34:37]
	v_mfma_f32_16x16x32_bf16 v[22:25], v[114:117], v[218:221], v[22:25]
	v_mfma_f32_16x16x32_bf16 v[18:21], v[122:125], v[218:221], v[18:21]
	v_mfma_f32_16x16x32_bf16 v[70:73], v[118:121], v[194:197], v[70:73]
	v_mfma_f32_16x16x32_bf16 v[66:69], v[130:133], v[194:197], v[66:69]
	v_mfma_f32_16x16x32_bf16 v[54:57], v[118:121], v[206:209], v[54:57]
	v_mfma_f32_16x16x32_bf16 v[50:53], v[130:133], v[206:209], v[50:53]
	v_mfma_f32_16x16x32_bf16 v[38:41], v[118:121], v[214:217], v[38:41]
	v_mfma_f32_16x16x32_bf16 v[34:37], v[130:133], v[214:217], v[34:37]
	v_mfma_f32_16x16x32_bf16 v[22:25], v[118:121], v[222:225], v[22:25]
	v_mfma_f32_16x16x32_bf16 v[18:21], v[130:133], v[222:225], v[18:21]
	v_mfma_f32_16x16x32_bf16 v[62:65], v[138:141], v[190:193], v[62:65]
	v_mfma_f32_16x16x32_bf16 v[58:61], v[150:153], v[190:193], v[58:61]
	v_mfma_f32_16x16x32_bf16 v[46:49], v[138:141], v[202:205], v[46:49]
	v_mfma_f32_16x16x32_bf16 v[42:45], v[150:153], v[202:205], v[42:45]
	v_mfma_f32_16x16x32_bf16 v[30:33], v[138:141], v[210:213], v[30:33]
	v_mfma_f32_16x16x32_bf16 v[26:29], v[150:153], v[210:213], v[26:29]
	v_mfma_f32_16x16x32_bf16 v[14:17], v[138:141], v[218:221], v[14:17]
	v_mfma_f32_16x16x32_bf16 v[10:13], v[150:153], v[218:221], v[10:13]
	v_mfma_f32_16x16x32_bf16 v[62:65], v[142:145], v[194:197], v[62:65]
	v_mfma_f32_16x16x32_bf16 v[58:61], v[154:157], v[194:197], v[58:61]
	v_mfma_f32_16x16x32_bf16 v[46:49], v[142:145], v[206:209], v[46:49]
	v_mfma_f32_16x16x32_bf16 v[42:45], v[154:157], v[206:209], v[42:45]
	v_mfma_f32_16x16x32_bf16 v[30:33], v[142:145], v[214:217], v[30:33]
	v_mfma_f32_16x16x32_bf16 v[26:29], v[154:157], v[214:217], v[26:29]
	v_mfma_f32_16x16x32_bf16 v[14:17], v[142:145], v[222:225], v[14:17]
	v_mfma_f32_16x16x32_bf16 v[10:13], v[154:157], v[222:225], v[10:13]
	s_setprio 0
	s_barrier
	s_add_i32 s37, s37, 2
	s_add_u32 s8, s8, 0x100
	s_addc_u32 s9, s9, 0
	s_add_u32 vcc_lo, vcc_lo, 0x100
	s_addc_u32 vcc_hi, vcc_hi, 0
	s_cmp_gt_u32 s37, 13
	s_cbranch_scc0 .LBB0_627
	s_and_b64 vcc, exec, s[12:13]
	s_cbranch_vccz .LBB0_630
	s_barrier
